# GEMM load segments: m0 setup moved ahead of the DMA address add so the VALU supplies the M0 wait state and the s_nop 0 is dropped (86 sites)
# speedup vs baseline: 1.0017x; 1.0017x over previous
; #define PG8_STAGE(bufoff, gbase, voff) do { _Pragma("unroll") for (int _i = 0; _i < 2; ++_i) \
;         __builtin_amdgcn_global_load_lds((const unsigned*)((const char*)(gbase) + (voff)[_i]), (LAS unsigned*)(lds + (bufoff) + ldsw + _i * 8192), 16, 0, 0); } while (0)
; #define PG8_LDA(dst, b, h) do { _Pragma("unroll") for (int m = 0; m < 4; ++m) _Pragma("unroll") for (int k = 0; k < 2; ++k) dst[m][k] = *(const LAS bf16x8*)(lds + PG8_SA(b, h) + aoff + m * 2048 + k * 1024); } while (0)
; #define PG8_LDB(dst, b, h) do { _Pragma("unroll") for (int n = 0; n < 2; ++n) _Pragma("unroll") for (int k = 0; k < 2; ++k) dst[n][k] = *(const LAS bf16x8*)(lds + PG8_SB(b, h) + boff + n * 2048 + k * 1024); } while (0)
; #define PG8_MMA(ai, bj, At, Bt) do { __builtin_amdgcn_s_setprio(1); _Pragma("unroll") for (int m = 0; m < 4; ++m) _Pragma("unroll") for (int n = 0; n < 2; ++n) _Pragma("unroll") for (int k = 0; k < 2; ++k) \
;         acc[ai][bj][m][n] = __builtin_amdgcn_mfma_f32_16x16x32_bf16(Bt[n][k], At[m][k], acc[ai][bj][m][n], 0, 0, 0); __builtin_amdgcn_s_setprio(0); } while (0)
; #define PG8_WAIT_V(n) asm volatile("s_waitcnt vmcnt(" #n ")" ::: "memory")
; #define PG8_WAIT_L(n) asm volatile("s_waitcnt lgkmcnt(" #n ")" ::: "memory")
; #define PG8_BAR __builtin_amdgcn_s_barrier()
; template <class Epi, bool SP2, class Sched>
; __device__ __forceinline__ void gemm_phase(LAS unsigned char* lds, const Gemm g, const Sched& S, const Epi& E) {
;     ...
;             const bool last = (t == nt - 2);
;             const char* a1 = cA + (size_t)(t + 1) * kstep;
;             const char* a2 = last ? nA : cA + (size_t)(t + 2) * kstep; const char* b2 = last ? nB : cB + (size_t)(t + 2) * kstep;
;             const char* a3 = a2 + kstep; const char* b3 = b2 + kstep;
;             if constexpr (Epi::MID) { if (t == (nt >> 1)) E.mid(acc, cur, wr, fr); }
;             if constexpr (SP2) {
;             PG8_LDB(B0, 0, 0); PG8_LDB(B1, 0, 1); PG8_SCHED; PG8_LDA(At, 0, 0); PG8_STAGE(PG8_SA(1, 1), a1 + hstep, voffA);
;             PG8_WAIT_V(8); PG8_WAIT_L(0); PG8_BAR; PG8_MMA(0, 0, At, B0); PG8_MMA(0, 1, At, B1); PG8_BAR; PG8_SCHED;
;             PG8_LDA(At, 0, 1); PG8_STAGE(PG8_SB(0, 0), b2, voffB); PG8_STAGE(PG8_SB(0, 1), b2 + hstepB, voffB); PG8_STAGE(PG8_SA(0, 0), a2, voffA);
;             PG8_WAIT_V(8); PG8_WAIT_L(0); PG8_BAR; PG8_MMA(1, 0, At, B0); PG8_MMA(1, 1, At, B1); PG8_BAR; PG8_SCHED;
.LBB0_313:
	s_add_u32 s10, vcc_lo, 0xfffc0080
	s_addc_u32 s11, vcc_hi, -1
	s_add_i32 s22, 0, 0x10000
	s_cmp_eq_u32 s21, 12
	s_cselect_b32 s97, s3, s11
	s_cselect_b32 s96, s17, s10
	v_add_u32_e32 v64, s22, v155
	s_cselect_b32 s11, s62, s20
	s_cselect_b32 s10, s93, s95
	s_add_i32 s24, 0, 0x14000
	ds_read_b128 v[130:133], v64
	ds_read_b128 v[148:151], v64 offset:1024
	ds_read_b128 v[156:159], v64 offset:2048
	ds_read_b128 v[164:167], v64 offset:3072
	v_add_u32_e32 v64, s24, v155
	ds_read_b128 v[168:171], v64
	ds_read_b128 v[172:175], v64 offset:1024
	ds_read_b128 v[176:179], v64 offset:2048
	ds_read_b128 v[180:183], v64 offset:3072
	v_lshl_add_u64 v[152:153], vcc, 0, v[146:147]
	s_add_i32 m0, s73, 0xc000
	ds_read_b128 v[184:187], v162
	ds_read_b128 v[188:191], v162 offset:1024
	ds_read_b128 v[214:217], v162 offset:2048
	ds_read_b128 v[218:221], v162 offset:3072
	ds_read_b128 v[222:225], v162 offset:4096
	ds_read_b128 v[226:229], v162 offset:5120
	ds_read_b128 v[230:233], v162 offset:6144
	ds_read_b128 v[234:237], v162 offset:7168
	global_load_lds_dwordx4 v[152:153], off
	s_add_i32 m0, s73, 0xe000
	v_lshl_add_u64 v[152:153], vcc, 0, v[144:145]
	global_load_lds_dwordx4 v[152:153], off
	s_waitcnt vmcnt(8) lgkmcnt(0)
	s_barrier
	s_setprio 1
	v_mfma_f32_16x16x32_bf16 v[126:129], v[130:133], v[184:187], v[126:129]
	v_mfma_f32_16x16x32_bf16 v[122:125], v[156:159], v[184:187], v[122:125]
	v_mfma_f32_16x16x32_bf16 v[110:113], v[130:133], v[214:217], v[110:113]
	v_mfma_f32_16x16x32_bf16 v[106:109], v[156:159], v[214:217], v[106:109]
	v_mfma_f32_16x16x32_bf16 v[94:97], v[130:133], v[222:225], v[94:97]
	v_mfma_f32_16x16x32_bf16 v[90:93], v[156:159], v[222:225], v[90:93]
	v_mfma_f32_16x16x32_bf16 v[78:81], v[130:133], v[230:233], v[78:81]
	v_mfma_f32_16x16x32_bf16 v[74:77], v[156:159], v[230:233], v[74:77]
	v_mfma_f32_16x16x32_bf16 v[126:129], v[148:151], v[188:191], v[126:129]
	v_mfma_f32_16x16x32_bf16 v[122:125], v[164:167], v[188:191], v[122:125]
	v_mfma_f32_16x16x32_bf16 v[110:113], v[148:151], v[218:221], v[110:113]
	v_mfma_f32_16x16x32_bf16 v[106:109], v[164:167], v[218:221], v[106:109]
	v_mfma_f32_16x16x32_bf16 v[94:97], v[148:151], v[226:229], v[94:97]
	v_mfma_f32_16x16x32_bf16 v[90:93], v[164:167], v[226:229], v[90:93]
	v_mfma_f32_16x16x32_bf16 v[78:81], v[148:151], v[234:237], v[78:81]
	v_mfma_f32_16x16x32_bf16 v[74:77], v[164:167], v[234:237], v[74:77]
	s_setprio 0
	s_setprio 1
	v_mfma_f32_16x16x32_bf16 v[118:121], v[168:171], v[184:187], v[118:121]
	v_mfma_f32_16x16x32_bf16 v[114:117], v[176:179], v[184:187], v[114:117]
	v_mfma_f32_16x16x32_bf16 v[102:105], v[168:171], v[214:217], v[102:105]
	v_mfma_f32_16x16x32_bf16 v[98:101], v[176:179], v[214:217], v[98:101]
	v_mfma_f32_16x16x32_bf16 v[86:89], v[168:171], v[222:225], v[86:89]
	v_mfma_f32_16x16x32_bf16 v[82:85], v[176:179], v[222:225], v[82:85]
	v_mfma_f32_16x16x32_bf16 v[70:73], v[168:171], v[230:233], v[70:73]
	v_mfma_f32_16x16x32_bf16 v[66:69], v[176:179], v[230:233], v[66:69]
	v_mfma_f32_16x16x32_bf16 v[118:121], v[172:175], v[188:191], v[118:121]
	v_mfma_f32_16x16x32_bf16 v[114:117], v[180:183], v[188:191], v[114:117]
	v_mfma_f32_16x16x32_bf16 v[102:105], v[172:175], v[218:221], v[102:105]
	v_mfma_f32_16x16x32_bf16 v[98:101], v[180:183], v[218:221], v[98:101]
	v_mfma_f32_16x16x32_bf16 v[86:89], v[172:175], v[226:229], v[86:89]
	v_mfma_f32_16x16x32_bf16 v[82:85], v[180:183], v[226:229], v[82:85]
	v_mfma_f32_16x16x32_bf16 v[70:73], v[172:175], v[234:237], v[70:73]
	v_mfma_f32_16x16x32_bf16 v[66:69], v[180:183], v[234:237], v[66:69]
	s_setprio 0
	s_barrier
	s_add_i32 s22, s22, s72
	v_lshl_add_u64 v[152:153], s[10:11], 0, v[136:137]
	s_mov_b32 m0, s22
	ds_read_b128 v[184:187], v162 offset:16384
	ds_read_b128 v[188:191], v162 offset:17408
	ds_read_b128 v[214:217], v162 offset:18432
	ds_read_b128 v[218:221], v162 offset:19456
	ds_read_b128 v[222:225], v162 offset:20480
	ds_read_b128 v[226:229], v162 offset:21504
	ds_read_b128 v[230:233], v162 offset:22528
	ds_read_b128 v[234:237], v162 offset:23552
	global_load_lds_dwordx4 v[152:153], off
	s_add_i32 m0, s22, 0x2000
	s_add_u32 s22, s10, 0x40000
	v_lshl_add_u64 v[192:193], s[10:11], 0, v[140:141]
	s_addc_u32 s23, s11, 0
	s_add_i32 s24, s24, s72
	global_load_lds_dwordx4 v[192:193], off
	v_lshl_add_u64 v[238:239], s[22:23], 0, v[136:137]
	s_mov_b32 m0, s24
	v_lshl_add_u64 v[240:241], s[96:97], 0, v[138:139]
	global_load_lds_dwordx4 v[238:239], off
	s_add_i32 m0, s24, 0x2000
	v_lshl_add_u64 v[238:239], s[22:23], 0, v[140:141]
	global_load_lds_dwordx4 v[238:239], off
	s_mov_b32 m0, s73
	v_lshl_add_u64 v[238:239], s[96:97], 0, v[134:135]
	global_load_lds_dwordx4 v[238:239], off
	s_mov_b32 m0, s74
	s_nop 0
	global_load_lds_dwordx4 v[240:241], off
	s_waitcnt vmcnt(8) lgkmcnt(0)
	s_barrier
; #define PG8_STAGE(bufoff, gbase, voff) do { _Pragma("unroll") for (int _i = 0; _i < 2; ++_i) \
;         __builtin_amdgcn_global_load_lds((const unsigned*)((const char*)(gbase) + (voff)[_i]), (LAS unsigned*)(lds + (bufoff) + ldsw + _i * 8192), 16, 0, 0); } while (0)
; #define PG8_LDA(dst, b, h) do { _Pragma("unroll") for (int m = 0; m < 4; ++m) _Pragma("unroll") for (int k = 0; k < 2; ++k) dst[m][k] = *(const LAS bf16x8*)(lds + PG8_SA(b, h) + aoff + m * 2048 + k * 1024); } while (0)
; #define PG8_LDB(dst, b, h) do { _Pragma("unroll") for (int n = 0; n < 2; ++n) _Pragma("unroll") for (int k = 0; k < 2; ++k) dst[n][k] = *(const LAS bf16x8*)(lds + PG8_SB(b, h) + boff + n * 2048 + k * 1024); } while (0)
; #define PG8_MMA(ai, bj, At, Bt) do { __builtin_amdgcn_s_setprio(1); _Pragma("unroll") for (int m = 0; m < 4; ++m) _Pragma("unroll") for (int n = 0; n < 2; ++n) _Pragma("unroll") for (int k = 0; k < 2; ++k) \
;         acc[ai][bj][m][n] = __builtin_amdgcn_mfma_f32_16x16x32_bf16(Bt[n][k], At[m][k], acc[ai][bj][m][n], 0, 0, 0); __builtin_amdgcn_s_setprio(0); } while (0)
; #define PG8_WAIT_V(n) asm volatile("s_waitcnt vmcnt(" #n ")" ::: "memory")
; #define PG8_WAIT_L(n) asm volatile("s_waitcnt lgkmcnt(" #n ")" ::: "memory")
; #define PG8_BAR __builtin_amdgcn_s_barrier()
; #define PG8_SCHED __builtin_amdgcn_sched_barrier(0)
; template <class Epi, bool SP2, class Sched>
; __device__ __forceinline__ void gemm_phase(LAS unsigned char* lds, const Gemm g, const Sched& S, const Epi& E) {
;     ...
;             PG8_WAIT_V(8); PG8_WAIT_L(0); PG8_BAR; PG8_MMA(1, 0, At, B0); PG8_MMA(1, 1, At, B1); PG8_BAR; PG8_SCHED;
;             PG8_LDB(B0, 1, 0); PG8_LDB(B1, 1, 1); PG8_SCHED; PG8_LDA(At, 1, 0); PG8_STAGE(PG8_SA(0, 1), a2 + hstep, voffA);
;             PG8_WAIT_V(8); PG8_WAIT_L(0); PG8_BAR; PG8_MMA(0, 0, At, B0); PG8_MMA(0, 1, At, B1); PG8_BAR; PG8_SCHED;
	s_setprio 1
	v_mfma_f32_16x16x32_bf16 v[60:63], v[130:133], v[184:187], v[60:63]
	v_mfma_f32_16x16x32_bf16 v[56:59], v[156:159], v[184:187], v[56:59]
	v_mfma_f32_16x16x32_bf16 v[44:47], v[130:133], v[214:217], v[44:47]
	v_mfma_f32_16x16x32_bf16 v[40:43], v[156:159], v[214:217], v[40:43]
	v_mfma_f32_16x16x32_bf16 v[28:31], v[130:133], v[222:225], v[28:31]
	v_mfma_f32_16x16x32_bf16 v[24:27], v[156:159], v[222:225], v[24:27]
	v_mfma_f32_16x16x32_bf16 v[12:15], v[130:133], v[230:233], v[12:15]
	v_mfma_f32_16x16x32_bf16 v[8:11], v[156:159], v[230:233], v[8:11]
	v_mfma_f32_16x16x32_bf16 v[60:63], v[148:151], v[188:191], v[60:63]
	v_mfma_f32_16x16x32_bf16 v[56:59], v[164:167], v[188:191], v[56:59]
	v_mfma_f32_16x16x32_bf16 v[44:47], v[148:151], v[218:221], v[44:47]
	v_mfma_f32_16x16x32_bf16 v[40:43], v[164:167], v[218:221], v[40:43]
	v_mfma_f32_16x16x32_bf16 v[28:31], v[148:151], v[226:229], v[28:31]
	v_mfma_f32_16x16x32_bf16 v[24:27], v[164:167], v[226:229], v[24:27]
	v_mfma_f32_16x16x32_bf16 v[12:15], v[148:151], v[234:237], v[12:15]
	v_mfma_f32_16x16x32_bf16 v[8:11], v[164:167], v[234:237], v[8:11]
	s_setprio 0
	s_setprio 1
	v_mfma_f32_16x16x32_bf16 v[52:55], v[168:171], v[184:187], v[52:55]
	v_mfma_f32_16x16x32_bf16 v[48:51], v[176:179], v[184:187], v[48:51]
	v_mfma_f32_16x16x32_bf16 v[36:39], v[168:171], v[214:217], v[36:39]
	v_mfma_f32_16x16x32_bf16 v[32:35], v[176:179], v[214:217], v[32:35]
	v_mfma_f32_16x16x32_bf16 v[20:23], v[168:171], v[222:225], v[20:23]
	v_mfma_f32_16x16x32_bf16 v[16:19], v[176:179], v[222:225], v[16:19]
	v_mfma_f32_16x16x32_bf16 v[4:7], v[168:171], v[230:233], v[4:7]
	v_mfma_f32_16x16x32_bf16 v[0:3], v[176:179], v[230:233], v[0:3]
	v_mfma_f32_16x16x32_bf16 v[52:55], v[172:175], v[188:191], v[52:55]
	v_mfma_f32_16x16x32_bf16 v[48:51], v[180:183], v[188:191], v[48:51]
	v_mfma_f32_16x16x32_bf16 v[36:39], v[172:175], v[218:221], v[36:39]
	v_mfma_f32_16x16x32_bf16 v[32:35], v[180:183], v[218:221], v[32:35]
	v_mfma_f32_16x16x32_bf16 v[20:23], v[172:175], v[226:229], v[20:23]
	v_mfma_f32_16x16x32_bf16 v[16:19], v[180:183], v[226:229], v[16:19]
	v_mfma_f32_16x16x32_bf16 v[4:7], v[172:175], v[234:237], v[4:7]
	v_mfma_f32_16x16x32_bf16 v[0:3], v[180:183], v[234:237], v[0:3]
	s_setprio 0
	s_barrier
	s_add_i32 s24, 0, 0x18000
	v_add_u32_e32 v64, s24, v155
	s_add_i32 s25, 0, 0x1c000
	ds_read_b128 v[130:133], v64
	ds_read_b128 v[148:151], v64 offset:1024
	ds_read_b128 v[156:159], v64 offset:2048
	ds_read_b128 v[164:167], v64 offset:3072
	v_add_u32_e32 v64, s25, v155
	ds_read_b128 v[168:171], v64
	ds_read_b128 v[172:175], v64 offset:1024
	ds_read_b128 v[176:179], v64 offset:2048
	ds_read_b128 v[180:183], v64 offset:3072
	s_add_u32 s22, s96, 0x40000
	s_addc_u32 s23, s97, 0
	s_mov_b32 m0, s75
	v_lshl_add_u64 v[248:249], s[22:23], 0, v[134:135]
	ds_read_b128 v[184:187], v162 offset:32768
	ds_read_b128 v[188:191], v162 offset:33792
	ds_read_b128 v[214:217], v162 offset:34816
	ds_read_b128 v[218:221], v162 offset:35840
	ds_read_b128 v[222:225], v162 offset:36864
	ds_read_b128 v[226:229], v162 offset:37888
	ds_read_b128 v[230:233], v162 offset:38912
	ds_read_b128 v[234:237], v162 offset:39936
	global_load_lds_dwordx4 v[248:249], off
	s_mov_b32 m0, s76
	v_lshl_add_u64 v[248:249], s[22:23], 0, v[138:139]
	global_load_lds_dwordx4 v[248:249], off
	s_waitcnt vmcnt(8) lgkmcnt(0)
	s_barrier
	s_setprio 1
	v_mfma_f32_16x16x32_bf16 v[126:129], v[130:133], v[184:187], v[126:129]
	v_mfma_f32_16x16x32_bf16 v[122:125], v[156:159], v[184:187], v[122:125]
	v_mfma_f32_16x16x32_bf16 v[110:113], v[130:133], v[214:217], v[110:113]
	v_mfma_f32_16x16x32_bf16 v[106:109], v[156:159], v[214:217], v[106:109]
	v_mfma_f32_16x16x32_bf16 v[94:97], v[130:133], v[222:225], v[94:97]
	v_mfma_f32_16x16x32_bf16 v[90:93], v[156:159], v[222:225], v[90:93]
	v_mfma_f32_16x16x32_bf16 v[78:81], v[130:133], v[230:233], v[78:81]
	v_mfma_f32_16x16x32_bf16 v[74:77], v[156:159], v[230:233], v[74:77]
	v_mfma_f32_16x16x32_bf16 v[126:129], v[148:151], v[188:191], v[126:129]
	v_mfma_f32_16x16x32_bf16 v[122:125], v[164:167], v[188:191], v[122:125]
	v_mfma_f32_16x16x32_bf16 v[110:113], v[148:151], v[218:221], v[110:113]
	v_mfma_f32_16x16x32_bf16 v[106:109], v[164:167], v[218:221], v[106:109]
	v_mfma_f32_16x16x32_bf16 v[94:97], v[148:151], v[226:229], v[94:97]
	v_mfma_f32_16x16x32_bf16 v[90:93], v[164:167], v[226:229], v[90:93]
	v_mfma_f32_16x16x32_bf16 v[78:81], v[148:151], v[234:237], v[78:81]
	v_mfma_f32_16x16x32_bf16 v[74:77], v[164:167], v[234:237], v[74:77]
	s_setprio 0
	s_setprio 1
	v_mfma_f32_16x16x32_bf16 v[118:121], v[168:171], v[184:187], v[118:121]
	v_mfma_f32_16x16x32_bf16 v[114:117], v[176:179], v[184:187], v[114:117]
	v_mfma_f32_16x16x32_bf16 v[102:105], v[168:171], v[214:217], v[102:105]
	v_mfma_f32_16x16x32_bf16 v[98:101], v[176:179], v[214:217], v[98:101]
	v_mfma_f32_16x16x32_bf16 v[86:89], v[168:171], v[222:225], v[86:89]
	v_mfma_f32_16x16x32_bf16 v[82:85], v[176:179], v[222:225], v[82:85]
	v_mfma_f32_16x16x32_bf16 v[70:73], v[168:171], v[230:233], v[70:73]
	v_mfma_f32_16x16x32_bf16 v[66:69], v[176:179], v[230:233], v[66:69]
	v_mfma_f32_16x16x32_bf16 v[118:121], v[172:175], v[188:191], v[118:121]
	v_mfma_f32_16x16x32_bf16 v[114:117], v[180:183], v[188:191], v[114:117]
	v_mfma_f32_16x16x32_bf16 v[102:105], v[172:175], v[218:221], v[102:105]
	v_mfma_f32_16x16x32_bf16 v[98:101], v[180:183], v[218:221], v[98:101]
	v_mfma_f32_16x16x32_bf16 v[86:89], v[172:175], v[226:229], v[86:89]
	v_mfma_f32_16x16x32_bf16 v[82:85], v[180:183], v[226:229], v[82:85]
	v_mfma_f32_16x16x32_bf16 v[70:73], v[172:175], v[234:237], v[70:73]
	v_mfma_f32_16x16x32_bf16 v[66:69], v[180:183], v[234:237], v[66:69]
	s_setprio 0
	s_barrier
; #define PG8_STAGE(bufoff, gbase, voff) do { _Pragma("unroll") for (int _i = 0; _i < 2; ++_i) \
;         __builtin_amdgcn_global_load_lds((const unsigned*)((const char*)(gbase) + (voff)[_i]), (LAS unsigned*)(lds + (bufoff) + ldsw + _i * 8192), 16, 0, 0); } while (0)
; #define PG8_LDA(dst, b, h) do { _Pragma("unroll") for (int m = 0; m < 4; ++m) _Pragma("unroll") for (int k = 0; k < 2; ++k) dst[m][k] = *(const LAS bf16x8*)(lds + PG8_SA(b, h) + aoff + m * 2048 + k * 1024); } while (0)
; #define PG8_MMA(ai, bj, At, Bt) do { __builtin_amdgcn_s_setprio(1); _Pragma("unroll") for (int m = 0; m < 4; ++m) _Pragma("unroll") for (int n = 0; n < 2; ++n) _Pragma("unroll") for (int k = 0; k < 2; ++k) \
;         acc[ai][bj][m][n] = __builtin_amdgcn_mfma_f32_16x16x32_bf16(Bt[n][k], At[m][k], acc[ai][bj][m][n], 0, 0, 0); __builtin_amdgcn_s_setprio(0); } while (0)
; #define PG8_WAIT_V(n) asm volatile("s_waitcnt vmcnt(" #n ")" ::: "memory")
; #define PG8_WAIT_L(n) asm volatile("s_waitcnt lgkmcnt(" #n ")" ::: "memory")
; #define PG8_BAR __builtin_amdgcn_s_barrier()
; #define PG8_SCHED __builtin_amdgcn_sched_barrier(0)
; template <class Epi, bool SP2, class Sched>
; __device__ __forceinline__ void gemm_phase(LAS unsigned char* lds, const Gemm g, const Sched& S, const Epi& E) {
;     ...
;             PG8_LDA(At, 1, 1); PG8_STAGE(PG8_SB(1, 0), b3, voffB); PG8_STAGE(PG8_SB(1, 1), b3 + hstepB, voffB); PG8_STAGE(PG8_SA(1, 0), a3, voffA);
;             PG8_WAIT_V(8); PG8_WAIT_L(0); PG8_BAR; PG8_MMA(1, 0, At, B0); PG8_MMA(1, 1, At, B1); PG8_BAR; PG8_SCHED;
;     ...
;         if (wr == 0) PG8_BAR;
	s_add_i32 s22, s24, s72
	v_lshl_add_u64 v[152:153], v[152:153], 0, s[66:67]
	s_mov_b32 m0, s22
	ds_read_b128 v[184:187], v162 offset:49152
	ds_read_b128 v[188:191], v162 offset:50176
	ds_read_b128 v[214:217], v162 offset:51200
	ds_read_b128 v[218:221], v162 offset:52224
	ds_read_b128 v[222:225], v162 offset:53248
	ds_read_b128 v[226:229], v162 offset:54272
	ds_read_b128 v[230:233], v162 offset:55296
	ds_read_b128 v[234:237], v162 offset:56320
	global_load_lds_dwordx4 v[152:153], off
	s_add_i32 m0, s22, 0x2000
	s_add_u32 s10, s10, 0x40080
	v_lshl_add_u64 v[152:153], v[192:193], 0, s[66:67]
	s_addc_u32 s11, s11, 0
	s_add_i32 s22, s25, s72
	global_load_lds_dwordx4 v[152:153], off
	s_mov_b32 m0, s22
	v_lshl_add_u64 v[152:153], s[10:11], 0, v[136:137]
	global_load_lds_dwordx4 v[152:153], off
	s_add_i32 m0, s22, 0x2000
	v_lshl_add_u64 v[152:153], s[10:11], 0, v[140:141]
	global_load_lds_dwordx4 v[152:153], off
	s_mov_b32 m0, s14
	v_lshl_add_u64 v[152:153], v[238:239], 0, s[66:67]
	global_load_lds_dwordx4 v[152:153], off
	s_mov_b32 m0, s15
	v_lshl_add_u64 v[152:153], v[240:241], 0, s[66:67]
	global_load_lds_dwordx4 v[152:153], off
	s_waitcnt vmcnt(8) lgkmcnt(0)
	s_barrier
	s_setprio 1
	v_mfma_f32_16x16x32_bf16 v[60:63], v[130:133], v[184:187], v[60:63]
	v_mfma_f32_16x16x32_bf16 v[56:59], v[156:159], v[184:187], v[56:59]
	v_mfma_f32_16x16x32_bf16 v[44:47], v[130:133], v[214:217], v[44:47]
	v_mfma_f32_16x16x32_bf16 v[40:43], v[156:159], v[214:217], v[40:43]
	v_mfma_f32_16x16x32_bf16 v[28:31], v[130:133], v[222:225], v[28:31]
	v_mfma_f32_16x16x32_bf16 v[24:27], v[156:159], v[222:225], v[24:27]
	v_mfma_f32_16x16x32_bf16 v[12:15], v[130:133], v[230:233], v[12:15]
	v_mfma_f32_16x16x32_bf16 v[8:11], v[156:159], v[230:233], v[8:11]
	v_mfma_f32_16x16x32_bf16 v[60:63], v[148:151], v[188:191], v[60:63]
	v_mfma_f32_16x16x32_bf16 v[56:59], v[164:167], v[188:191], v[56:59]
	v_mfma_f32_16x16x32_bf16 v[44:47], v[148:151], v[218:221], v[44:47]
	v_mfma_f32_16x16x32_bf16 v[40:43], v[164:167], v[218:221], v[40:43]
	v_mfma_f32_16x16x32_bf16 v[28:31], v[148:151], v[226:229], v[28:31]
	v_mfma_f32_16x16x32_bf16 v[24:27], v[164:167], v[226:229], v[24:27]
	v_mfma_f32_16x16x32_bf16 v[12:15], v[148:151], v[234:237], v[12:15]
	v_mfma_f32_16x16x32_bf16 v[8:11], v[164:167], v[234:237], v[8:11]
	s_setprio 0
	s_setprio 1
	v_mfma_f32_16x16x32_bf16 v[52:55], v[168:171], v[184:187], v[52:55]
	v_mfma_f32_16x16x32_bf16 v[48:51], v[176:179], v[184:187], v[48:51]
	v_mfma_f32_16x16x32_bf16 v[36:39], v[168:171], v[214:217], v[36:39]
	v_mfma_f32_16x16x32_bf16 v[32:35], v[176:179], v[214:217], v[32:35]
	v_mfma_f32_16x16x32_bf16 v[20:23], v[168:171], v[222:225], v[20:23]
	v_mfma_f32_16x16x32_bf16 v[16:19], v[176:179], v[222:225], v[16:19]
	v_mfma_f32_16x16x32_bf16 v[4:7], v[168:171], v[230:233], v[4:7]
	v_mfma_f32_16x16x32_bf16 v[0:3], v[176:179], v[230:233], v[0:3]
	v_mfma_f32_16x16x32_bf16 v[52:55], v[172:175], v[188:191], v[52:55]
	v_mfma_f32_16x16x32_bf16 v[48:51], v[180:183], v[188:191], v[48:51]
	v_mfma_f32_16x16x32_bf16 v[36:39], v[172:175], v[218:221], v[36:39]
	v_mfma_f32_16x16x32_bf16 v[32:35], v[180:183], v[218:221], v[32:35]
	v_mfma_f32_16x16x32_bf16 v[20:23], v[172:175], v[226:229], v[20:23]
	v_mfma_f32_16x16x32_bf16 v[16:19], v[180:183], v[226:229], v[16:19]
	v_mfma_f32_16x16x32_bf16 v[4:7], v[172:175], v[234:237], v[4:7]
	v_mfma_f32_16x16x32_bf16 v[0:3], v[180:183], v[234:237], v[0:3]
	s_setprio 0
	s_barrier
	s_add_i32 s21, s21, 2
	s_add_u32 s95, s95, 0x100
	s_addc_u32 s20, s20, 0
	s_add_u32 vcc_lo, vcc_lo, 0x100
	s_addc_u32 vcc_hi, vcc_hi, 0
	s_cmp_gt_u32 s21, 13
	s_cbranch_scc0 .LBB0_313
	s_and_b64 vcc, exec, s[88:89]
	s_cbranch_vccz .LBB0_316
	s_barrier

; #define PG8_STAGE(bufoff, gbase, voff) do { _Pragma("unroll") for (int _i = 0; _i < 2; ++_i) \
;         __builtin_amdgcn_global_load_lds((const unsigned*)((const char*)(gbase) + (voff)[_i]), (LAS unsigned*)(lds + (bufoff) + ldsw + _i * 8192), 16, 0, 0); } while (0)
; #define PG8_LDA(dst, b, h) do { _Pragma("unroll") for (int m = 0; m < 4; ++m) _Pragma("unroll") for (int k = 0; k < 2; ++k) dst[m][k] = *(const LAS bf16x8*)(lds + PG8_SA(b, h) + aoff + m * 2048 + k * 1024); } while (0)
; #define PG8_LDB(dst, b, h) do { _Pragma("unroll") for (int n = 0; n < 2; ++n) _Pragma("unroll") for (int k = 0; k < 2; ++k) dst[n][k] = *(const LAS bf16x8*)(lds + PG8_SB(b, h) + boff + n * 2048 + k * 1024); } while (0)
; #define PG8_MMA(ai, bj, At, Bt) do { __builtin_amdgcn_s_setprio(1); _Pragma("unroll") for (int m = 0; m < 4; ++m) _Pragma("unroll") for (int n = 0; n < 2; ++n) _Pragma("unroll") for (int k = 0; k < 2; ++k) \
;         acc[ai][bj][m][n] = __builtin_amdgcn_mfma_f32_16x16x32_bf16(Bt[n][k], At[m][k], acc[ai][bj][m][n], 0, 0, 0); __builtin_amdgcn_s_setprio(0); } while (0)
; #define PG8_WAIT_V(n) asm volatile("s_waitcnt vmcnt(" #n ")" ::: "memory")
; #define PG8_WAIT_L(n) asm volatile("s_waitcnt lgkmcnt(" #n ")" ::: "memory")
; #define PG8_BAR __builtin_amdgcn_s_barrier()
; template <class Epi, bool SP2, class Sched>
; __device__ __forceinline__ void gemm_phase(LAS unsigned char* lds, const Gemm g, const Sched& S, const Epi& E) {
;     ...
;             const bool last = (t == nt - 2);
;             const char* a1 = cA + (size_t)(t + 1) * kstep;
;             const char* a2 = last ? nA : cA + (size_t)(t + 2) * kstep; const char* b2 = last ? nB : cB + (size_t)(t + 2) * kstep;
;             const char* a3 = a2 + kstep; const char* b3 = b2 + kstep;
;             if constexpr (Epi::MID) { if (t == (nt >> 1)) E.mid(acc, cur, wr, fr); }
;             if constexpr (SP2) {
;             PG8_LDB(B0, 0, 0); PG8_LDB(B1, 0, 1); PG8_SCHED; PG8_LDA(At, 0, 0); PG8_STAGE(PG8_SA(1, 1), a1 + hstep, voffA);
;             PG8_WAIT_V(8); PG8_WAIT_L(0); PG8_BAR; PG8_MMA(0, 0, At, B0); PG8_MMA(0, 1, At, B1); PG8_BAR; PG8_SCHED;
;             PG8_LDA(At, 0, 1); PG8_STAGE(PG8_SB(0, 0), b2, voffB); PG8_STAGE(PG8_SB(0, 1), b2 + hstepB, voffB); PG8_STAGE(PG8_SA(0, 0), a2, voffA);
;             PG8_WAIT_V(8); PG8_WAIT_L(0); PG8_BAR; PG8_MMA(1, 0, At, B0); PG8_MMA(1, 1, At, B1); PG8_BAR; PG8_SCHED;
.LBB0_381:
	s_add_u32 s6, s90, 0xfffc0080
	s_addc_u32 s7, s91, -1
	s_add_i32 s22, 0, 0x10000
	s_cmp_eq_u32 s21, 12
	s_cselect_b32 s11, s74, s7
	s_cselect_b32 s10, s75, s6
	s_cselect_b32 s7, s61, s20
	s_cselect_b32 s6, s76, s77
	s_add_i32 s24, 0, 0x14000
	v_add_u32_e32 v110, s22, v163
	v_add_u32_e32 v160, s24, v163
	ds_read_b128 v[98:101], v110
	ds_read_b128 v[102:105], v110 offset:1024
	ds_read_b128 v[106:109], v110 offset:2048
	ds_read_b128 v[110:113], v110 offset:3072
	ds_read_b128 v[156:159], v160
	ds_read_b128 v[166:169], v160 offset:1024
	ds_read_b128 v[170:173], v160 offset:2048
	ds_read_b128 v[174:177], v160 offset:3072
	v_lshl_add_u64 v[160:161], s[90:91], 0, v[154:155]
	s_add_i32 m0, s17, 0xc000
	ds_read_b128 v[178:181], v165
	ds_read_b128 v[182:185], v165 offset:1024
	ds_read_b128 v[186:189], v165 offset:2048
	ds_read_b128 v[190:193], v165 offset:3072
	ds_read_b128 v[214:217], v165 offset:4096
	ds_read_b128 v[218:221], v165 offset:5120
	ds_read_b128 v[222:225], v165 offset:6144
	ds_read_b128 v[226:229], v165 offset:7168
	global_load_lds_dwordx4 v[160:161], off
	s_add_i32 m0, s17, 0xe000
	v_lshl_add_u64 v[160:161], s[90:91], 0, v[152:153]
	global_load_lds_dwordx4 v[160:161], off
	s_waitcnt vmcnt(8) lgkmcnt(0)
	s_barrier
	s_setprio 1
	v_mfma_f32_16x16x32_bf16 v[142:145], v[98:101], v[178:181], v[142:145]
	v_mfma_f32_16x16x32_bf16 v[138:141], v[106:109], v[178:181], v[138:141]
	v_mfma_f32_16x16x32_bf16 v[126:129], v[98:101], v[186:189], v[126:129]
	v_mfma_f32_16x16x32_bf16 v[122:125], v[106:109], v[186:189], v[122:125]
	v_mfma_f32_16x16x32_bf16 v[94:97], v[98:101], v[214:217], v[94:97]
	v_mfma_f32_16x16x32_bf16 v[90:93], v[106:109], v[214:217], v[90:93]
	v_mfma_f32_16x16x32_bf16 v[78:81], v[98:101], v[222:225], v[78:81]
	v_mfma_f32_16x16x32_bf16 v[74:77], v[106:109], v[222:225], v[74:77]
	v_mfma_f32_16x16x32_bf16 v[142:145], v[102:105], v[182:185], v[142:145]
	v_mfma_f32_16x16x32_bf16 v[138:141], v[110:113], v[182:185], v[138:141]
	v_mfma_f32_16x16x32_bf16 v[126:129], v[102:105], v[190:193], v[126:129]
	v_mfma_f32_16x16x32_bf16 v[122:125], v[110:113], v[190:193], v[122:125]
	v_mfma_f32_16x16x32_bf16 v[94:97], v[102:105], v[218:221], v[94:97]
	v_mfma_f32_16x16x32_bf16 v[90:93], v[110:113], v[218:221], v[90:93]
	v_mfma_f32_16x16x32_bf16 v[78:81], v[102:105], v[226:229], v[78:81]
	v_mfma_f32_16x16x32_bf16 v[74:77], v[110:113], v[226:229], v[74:77]
	s_setprio 0
	s_setprio 1
	v_mfma_f32_16x16x32_bf16 v[134:137], v[156:159], v[178:181], v[134:137]
	v_mfma_f32_16x16x32_bf16 v[130:133], v[170:173], v[178:181], v[130:133]
	v_mfma_f32_16x16x32_bf16 v[118:121], v[156:159], v[186:189], v[118:121]
	v_mfma_f32_16x16x32_bf16 v[114:117], v[170:173], v[186:189], v[114:117]
	v_mfma_f32_16x16x32_bf16 v[86:89], v[156:159], v[214:217], v[86:89]
	v_mfma_f32_16x16x32_bf16 v[82:85], v[170:173], v[214:217], v[82:85]
	v_mfma_f32_16x16x32_bf16 v[70:73], v[156:159], v[222:225], v[70:73]
	v_mfma_f32_16x16x32_bf16 v[66:69], v[170:173], v[222:225], v[66:69]
	v_mfma_f32_16x16x32_bf16 v[134:137], v[166:169], v[182:185], v[134:137]
	v_mfma_f32_16x16x32_bf16 v[130:133], v[174:177], v[182:185], v[130:133]
	v_mfma_f32_16x16x32_bf16 v[118:121], v[166:169], v[190:193], v[118:121]
	v_mfma_f32_16x16x32_bf16 v[114:117], v[174:177], v[190:193], v[114:117]
	v_mfma_f32_16x16x32_bf16 v[86:89], v[166:169], v[218:221], v[86:89]
	v_mfma_f32_16x16x32_bf16 v[82:85], v[174:177], v[218:221], v[82:85]
	v_mfma_f32_16x16x32_bf16 v[70:73], v[166:169], v[226:229], v[70:73]
	v_mfma_f32_16x16x32_bf16 v[66:69], v[174:177], v[226:229], v[66:69]
	s_setprio 0
	s_barrier
	s_add_i32 s22, s22, s19
	v_lshl_add_u64 v[160:161], s[6:7], 0, v[64:65]
	s_mov_b32 m0, s22
	ds_read_b128 v[178:181], v165 offset:16384
	ds_read_b128 v[182:185], v165 offset:17408
	ds_read_b128 v[186:189], v165 offset:18432
	ds_read_b128 v[190:193], v165 offset:19456
	ds_read_b128 v[214:217], v165 offset:20480
	ds_read_b128 v[218:221], v165 offset:21504
	ds_read_b128 v[222:225], v165 offset:22528
	ds_read_b128 v[226:229], v165 offset:23552
	global_load_lds_dwordx4 v[160:161], off
	s_add_i32 m0, s22, 0x2000
	s_add_u32 s22, s6, 0x40000
	v_lshl_add_u64 v[230:231], s[6:7], 0, v[150:151]
	s_addc_u32 s23, s7, 0
	s_add_i32 s24, s24, s19
	global_load_lds_dwordx4 v[230:231], off
	v_lshl_add_u64 v[232:233], s[22:23], 0, v[64:65]
	s_mov_b32 m0, s24
	v_lshl_add_u64 v[234:235], s[10:11], 0, v[148:149]
	global_load_lds_dwordx4 v[232:233], off
	s_add_i32 m0, s24, 0x2000
	v_lshl_add_u64 v[232:233], s[22:23], 0, v[150:151]
	global_load_lds_dwordx4 v[232:233], off
	s_mov_b32 m0, s17
	v_lshl_add_u64 v[232:233], s[10:11], 0, v[146:147]
	global_load_lds_dwordx4 v[232:233], off
	s_mov_b32 m0, s33
	s_nop 0
	global_load_lds_dwordx4 v[234:235], off
	s_waitcnt vmcnt(8) lgkmcnt(0)
	s_barrier
; #define PG8_STAGE(bufoff, gbase, voff) do { _Pragma("unroll") for (int _i = 0; _i < 2; ++_i) \
;         __builtin_amdgcn_global_load_lds((const unsigned*)((const char*)(gbase) + (voff)[_i]), (LAS unsigned*)(lds + (bufoff) + ldsw + _i * 8192), 16, 0, 0); } while (0)
; #define PG8_LDA(dst, b, h) do { _Pragma("unroll") for (int m = 0; m < 4; ++m) _Pragma("unroll") for (int k = 0; k < 2; ++k) dst[m][k] = *(const LAS bf16x8*)(lds + PG8_SA(b, h) + aoff + m * 2048 + k * 1024); } while (0)
; #define PG8_LDB(dst, b, h) do { _Pragma("unroll") for (int n = 0; n < 2; ++n) _Pragma("unroll") for (int k = 0; k < 2; ++k) dst[n][k] = *(const LAS bf16x8*)(lds + PG8_SB(b, h) + boff + n * 2048 + k * 1024); } while (0)
; #define PG8_MMA(ai, bj, At, Bt) do { __builtin_amdgcn_s_setprio(1); _Pragma("unroll") for (int m = 0; m < 4; ++m) _Pragma("unroll") for (int n = 0; n < 2; ++n) _Pragma("unroll") for (int k = 0; k < 2; ++k) \
;         acc[ai][bj][m][n] = __builtin_amdgcn_mfma_f32_16x16x32_bf16(Bt[n][k], At[m][k], acc[ai][bj][m][n], 0, 0, 0); __builtin_amdgcn_s_setprio(0); } while (0)
; #define PG8_WAIT_V(n) asm volatile("s_waitcnt vmcnt(" #n ")" ::: "memory")
; #define PG8_WAIT_L(n) asm volatile("s_waitcnt lgkmcnt(" #n ")" ::: "memory")
; #define PG8_BAR __builtin_amdgcn_s_barrier()
; #define PG8_SCHED __builtin_amdgcn_sched_barrier(0)
; template <class Epi, bool SP2, class Sched>
; __device__ __forceinline__ void gemm_phase(LAS unsigned char* lds, const Gemm g, const Sched& S, const Epi& E) {
;     ...
;             PG8_WAIT_V(8); PG8_WAIT_L(0); PG8_BAR; PG8_MMA(1, 0, At, B0); PG8_MMA(1, 1, At, B1); PG8_BAR; PG8_SCHED;
;             PG8_LDB(B0, 1, 0); PG8_LDB(B1, 1, 1); PG8_SCHED; PG8_LDA(At, 1, 0); PG8_STAGE(PG8_SA(0, 1), a2 + hstep, voffA);
;             PG8_WAIT_V(8); PG8_WAIT_L(0); PG8_BAR; PG8_MMA(0, 0, At, B0); PG8_MMA(0, 1, At, B1); PG8_BAR; PG8_SCHED;
	s_setprio 1
	v_mfma_f32_16x16x32_bf16 v[60:63], v[98:101], v[178:181], v[60:63]
	v_mfma_f32_16x16x32_bf16 v[56:59], v[106:109], v[178:181], v[56:59]
	v_mfma_f32_16x16x32_bf16 v[48:51], v[98:101], v[186:189], v[48:51]
	v_mfma_f32_16x16x32_bf16 v[40:43], v[106:109], v[186:189], v[40:43]
	v_mfma_f32_16x16x32_bf16 v[32:35], v[98:101], v[214:217], v[32:35]
	v_mfma_f32_16x16x32_bf16 v[24:27], v[106:109], v[214:217], v[24:27]
	v_mfma_f32_16x16x32_bf16 v[16:19], v[98:101], v[222:225], v[16:19]
	v_mfma_f32_16x16x32_bf16 v[8:11], v[106:109], v[222:225], v[8:11]
	v_mfma_f32_16x16x32_bf16 v[60:63], v[102:105], v[182:185], v[60:63]
	v_mfma_f32_16x16x32_bf16 v[56:59], v[110:113], v[182:185], v[56:59]
	v_mfma_f32_16x16x32_bf16 v[48:51], v[102:105], v[190:193], v[48:51]
	v_mfma_f32_16x16x32_bf16 v[40:43], v[110:113], v[190:193], v[40:43]
	v_mfma_f32_16x16x32_bf16 v[32:35], v[102:105], v[218:221], v[32:35]
	v_mfma_f32_16x16x32_bf16 v[24:27], v[110:113], v[218:221], v[24:27]
	v_mfma_f32_16x16x32_bf16 v[16:19], v[102:105], v[226:229], v[16:19]
	v_mfma_f32_16x16x32_bf16 v[8:11], v[110:113], v[226:229], v[8:11]
	s_setprio 0
	s_setprio 1
	v_mfma_f32_16x16x32_bf16 v[52:55], v[156:159], v[178:181], v[52:55]
	v_mfma_f32_16x16x32_bf16 v[44:47], v[170:173], v[178:181], v[44:47]
	v_mfma_f32_16x16x32_bf16 v[36:39], v[156:159], v[186:189], v[36:39]
	v_mfma_f32_16x16x32_bf16 v[28:31], v[170:173], v[186:189], v[28:31]
	v_mfma_f32_16x16x32_bf16 v[20:23], v[156:159], v[214:217], v[20:23]
	v_mfma_f32_16x16x32_bf16 v[12:15], v[170:173], v[214:217], v[12:15]
	v_mfma_f32_16x16x32_bf16 v[4:7], v[156:159], v[222:225], v[4:7]
	v_mfma_f32_16x16x32_bf16 v[0:3], v[170:173], v[222:225], v[0:3]
	v_mfma_f32_16x16x32_bf16 v[52:55], v[166:169], v[182:185], v[52:55]
	v_mfma_f32_16x16x32_bf16 v[44:47], v[174:177], v[182:185], v[44:47]
	v_mfma_f32_16x16x32_bf16 v[36:39], v[166:169], v[190:193], v[36:39]
	v_mfma_f32_16x16x32_bf16 v[28:31], v[174:177], v[190:193], v[28:31]
	v_mfma_f32_16x16x32_bf16 v[20:23], v[166:169], v[218:221], v[20:23]
	v_mfma_f32_16x16x32_bf16 v[12:15], v[174:177], v[218:221], v[12:15]
	v_mfma_f32_16x16x32_bf16 v[4:7], v[166:169], v[226:229], v[4:7]
	v_mfma_f32_16x16x32_bf16 v[0:3], v[174:177], v[226:229], v[0:3]
	s_setprio 0
	s_barrier
	s_add_i32 s22, 0, 0x18000
	s_add_i32 s23, 0, 0x1c000
	v_add_u32_e32 v110, s22, v163
	v_add_u32_e32 v174, s23, v163
	ds_read_b128 v[98:101], v110
	ds_read_b128 v[102:105], v110 offset:1024
	ds_read_b128 v[106:109], v110 offset:2048
	ds_read_b128 v[110:113], v110 offset:3072
	ds_read_b128 v[156:159], v174
	ds_read_b128 v[166:169], v174 offset:1024
	ds_read_b128 v[170:173], v174 offset:2048
	ds_read_b128 v[174:177], v174 offset:3072
	s_add_u32 s10, s10, 0x40000
	s_addc_u32 s11, s11, 0
	s_mov_b32 m0, s62
	v_lshl_add_u64 v[236:237], s[10:11], 0, v[146:147]
	ds_read_b128 v[178:181], v165 offset:32768
	ds_read_b128 v[182:185], v165 offset:33792
	ds_read_b128 v[186:189], v165 offset:34816
	ds_read_b128 v[190:193], v165 offset:35840
	ds_read_b128 v[214:217], v165 offset:36864
	ds_read_b128 v[218:221], v165 offset:37888
	ds_read_b128 v[222:225], v165 offset:38912
	ds_read_b128 v[226:229], v165 offset:39936
	global_load_lds_dwordx4 v[236:237], off
	s_mov_b32 m0, s64
	v_lshl_add_u64 v[236:237], s[10:11], 0, v[148:149]
	global_load_lds_dwordx4 v[236:237], off
	s_waitcnt vmcnt(8) lgkmcnt(0)
	s_barrier
	s_setprio 1
	v_mfma_f32_16x16x32_bf16 v[142:145], v[98:101], v[178:181], v[142:145]
	v_mfma_f32_16x16x32_bf16 v[138:141], v[106:109], v[178:181], v[138:141]
	v_mfma_f32_16x16x32_bf16 v[126:129], v[98:101], v[186:189], v[126:129]
	v_mfma_f32_16x16x32_bf16 v[122:125], v[106:109], v[186:189], v[122:125]
	v_mfma_f32_16x16x32_bf16 v[94:97], v[98:101], v[214:217], v[94:97]
	v_mfma_f32_16x16x32_bf16 v[90:93], v[106:109], v[214:217], v[90:93]
	v_mfma_f32_16x16x32_bf16 v[78:81], v[98:101], v[222:225], v[78:81]
	v_mfma_f32_16x16x32_bf16 v[74:77], v[106:109], v[222:225], v[74:77]
	v_mfma_f32_16x16x32_bf16 v[142:145], v[102:105], v[182:185], v[142:145]
	v_mfma_f32_16x16x32_bf16 v[138:141], v[110:113], v[182:185], v[138:141]
	v_mfma_f32_16x16x32_bf16 v[126:129], v[102:105], v[190:193], v[126:129]
	v_mfma_f32_16x16x32_bf16 v[122:125], v[110:113], v[190:193], v[122:125]
	v_mfma_f32_16x16x32_bf16 v[94:97], v[102:105], v[218:221], v[94:97]
	v_mfma_f32_16x16x32_bf16 v[90:93], v[110:113], v[218:221], v[90:93]
	v_mfma_f32_16x16x32_bf16 v[78:81], v[102:105], v[226:229], v[78:81]
	v_mfma_f32_16x16x32_bf16 v[74:77], v[110:113], v[226:229], v[74:77]
	s_setprio 0
	s_setprio 1
	v_mfma_f32_16x16x32_bf16 v[134:137], v[156:159], v[178:181], v[134:137]
	v_mfma_f32_16x16x32_bf16 v[130:133], v[170:173], v[178:181], v[130:133]
	v_mfma_f32_16x16x32_bf16 v[118:121], v[156:159], v[186:189], v[118:121]
	v_mfma_f32_16x16x32_bf16 v[114:117], v[170:173], v[186:189], v[114:117]
	v_mfma_f32_16x16x32_bf16 v[86:89], v[156:159], v[214:217], v[86:89]
	v_mfma_f32_16x16x32_bf16 v[82:85], v[170:173], v[214:217], v[82:85]
	v_mfma_f32_16x16x32_bf16 v[70:73], v[156:159], v[222:225], v[70:73]
	v_mfma_f32_16x16x32_bf16 v[66:69], v[170:173], v[222:225], v[66:69]
	v_mfma_f32_16x16x32_bf16 v[134:137], v[166:169], v[182:185], v[134:137]
	v_mfma_f32_16x16x32_bf16 v[130:133], v[174:177], v[182:185], v[130:133]
	v_mfma_f32_16x16x32_bf16 v[118:121], v[166:169], v[190:193], v[118:121]
	v_mfma_f32_16x16x32_bf16 v[114:117], v[174:177], v[190:193], v[114:117]
	v_mfma_f32_16x16x32_bf16 v[86:89], v[166:169], v[218:221], v[86:89]
	v_mfma_f32_16x16x32_bf16 v[82:85], v[174:177], v[218:221], v[82:85]
	v_mfma_f32_16x16x32_bf16 v[70:73], v[166:169], v[226:229], v[70:73]
	v_mfma_f32_16x16x32_bf16 v[66:69], v[174:177], v[226:229], v[66:69]
	s_setprio 0
	s_barrier
; #define PG8_STAGE(bufoff, gbase, voff) do { _Pragma("unroll") for (int _i = 0; _i < 2; ++_i) \
;         __builtin_amdgcn_global_load_lds((const unsigned*)((const char*)(gbase) + (voff)[_i]), (LAS unsigned*)(lds + (bufoff) + ldsw + _i * 8192), 16, 0, 0); } while (0)
; #define PG8_LDA(dst, b, h) do { _Pragma("unroll") for (int m = 0; m < 4; ++m) _Pragma("unroll") for (int k = 0; k < 2; ++k) dst[m][k] = *(const LAS bf16x8*)(lds + PG8_SA(b, h) + aoff + m * 2048 + k * 1024); } while (0)
; #define PG8_MMA(ai, bj, At, Bt) do { __builtin_amdgcn_s_setprio(1); _Pragma("unroll") for (int m = 0; m < 4; ++m) _Pragma("unroll") for (int n = 0; n < 2; ++n) _Pragma("unroll") for (int k = 0; k < 2; ++k) \
;         acc[ai][bj][m][n] = __builtin_amdgcn_mfma_f32_16x16x32_bf16(Bt[n][k], At[m][k], acc[ai][bj][m][n], 0, 0, 0); __builtin_amdgcn_s_setprio(0); } while (0)
; #define PG8_WAIT_V(n) asm volatile("s_waitcnt vmcnt(" #n ")" ::: "memory")
; #define PG8_WAIT_L(n) asm volatile("s_waitcnt lgkmcnt(" #n ")" ::: "memory")
; #define PG8_BAR __builtin_amdgcn_s_barrier()
; #define PG8_SCHED __builtin_amdgcn_sched_barrier(0)
; template <class Epi, bool SP2, class Sched>
; __device__ __forceinline__ void gemm_phase(LAS unsigned char* lds, const Gemm g, const Sched& S, const Epi& E) {
;     ...
;             PG8_LDA(At, 1, 1); PG8_STAGE(PG8_SB(1, 0), b3, voffB); PG8_STAGE(PG8_SB(1, 1), b3 + hstepB, voffB); PG8_STAGE(PG8_SA(1, 0), a3, voffA);
;             PG8_WAIT_V(8); PG8_WAIT_L(0); PG8_BAR; PG8_MMA(1, 0, At, B0); PG8_MMA(1, 1, At, B1); PG8_BAR; PG8_SCHED;
;     ...
;         if (wr == 0) PG8_BAR;
	s_add_i32 s10, s22, s19
	v_lshl_add_u64 v[160:161], v[160:161], 0, s[66:67]
	s_mov_b32 m0, s10
	ds_read_b128 v[178:181], v165 offset:49152
	ds_read_b128 v[182:185], v165 offset:50176
	ds_read_b128 v[186:189], v165 offset:51200
	ds_read_b128 v[190:193], v165 offset:52224
	ds_read_b128 v[214:217], v165 offset:53248
	ds_read_b128 v[218:221], v165 offset:54272
	ds_read_b128 v[222:225], v165 offset:55296
	ds_read_b128 v[226:229], v165 offset:56320
	global_load_lds_dwordx4 v[160:161], off
	s_add_i32 m0, s10, 0x2000
	s_add_u32 s6, s6, 0x40080
	v_lshl_add_u64 v[160:161], v[230:231], 0, s[66:67]
	s_addc_u32 s7, s7, 0
	s_add_i32 s10, s23, s19
	global_load_lds_dwordx4 v[160:161], off
	s_mov_b32 m0, s10
	v_lshl_add_u64 v[160:161], s[6:7], 0, v[64:65]
	global_load_lds_dwordx4 v[160:161], off
	s_add_i32 m0, s10, 0x2000
	v_lshl_add_u64 v[160:161], s[6:7], 0, v[150:151]
	global_load_lds_dwordx4 v[160:161], off
	s_mov_b32 m0, s65
	v_lshl_add_u64 v[160:161], v[232:233], 0, s[66:67]
	global_load_lds_dwordx4 v[160:161], off
	s_mov_b32 m0, s68
	v_lshl_add_u64 v[160:161], v[234:235], 0, s[66:67]
	global_load_lds_dwordx4 v[160:161], off
	s_waitcnt vmcnt(8) lgkmcnt(0)
	s_barrier
	s_setprio 1
	v_mfma_f32_16x16x32_bf16 v[60:63], v[98:101], v[178:181], v[60:63]
	v_mfma_f32_16x16x32_bf16 v[56:59], v[106:109], v[178:181], v[56:59]
	v_mfma_f32_16x16x32_bf16 v[48:51], v[98:101], v[186:189], v[48:51]
	v_mfma_f32_16x16x32_bf16 v[40:43], v[106:109], v[186:189], v[40:43]
	v_mfma_f32_16x16x32_bf16 v[32:35], v[98:101], v[214:217], v[32:35]
	v_mfma_f32_16x16x32_bf16 v[24:27], v[106:109], v[214:217], v[24:27]
	v_mfma_f32_16x16x32_bf16 v[16:19], v[98:101], v[222:225], v[16:19]
	v_mfma_f32_16x16x32_bf16 v[8:11], v[106:109], v[222:225], v[8:11]
	v_mfma_f32_16x16x32_bf16 v[60:63], v[102:105], v[182:185], v[60:63]
	v_mfma_f32_16x16x32_bf16 v[56:59], v[110:113], v[182:185], v[56:59]
	v_mfma_f32_16x16x32_bf16 v[48:51], v[102:105], v[190:193], v[48:51]
	v_mfma_f32_16x16x32_bf16 v[40:43], v[110:113], v[190:193], v[40:43]
	v_mfma_f32_16x16x32_bf16 v[32:35], v[102:105], v[218:221], v[32:35]
	v_mfma_f32_16x16x32_bf16 v[24:27], v[110:113], v[218:221], v[24:27]
	v_mfma_f32_16x16x32_bf16 v[16:19], v[102:105], v[226:229], v[16:19]
	v_mfma_f32_16x16x32_bf16 v[8:11], v[110:113], v[226:229], v[8:11]
	s_setprio 0
	s_setprio 1
	v_mfma_f32_16x16x32_bf16 v[52:55], v[156:159], v[178:181], v[52:55]
	v_mfma_f32_16x16x32_bf16 v[44:47], v[170:173], v[178:181], v[44:47]
	v_mfma_f32_16x16x32_bf16 v[36:39], v[156:159], v[186:189], v[36:39]
	v_mfma_f32_16x16x32_bf16 v[28:31], v[170:173], v[186:189], v[28:31]
	v_mfma_f32_16x16x32_bf16 v[20:23], v[156:159], v[214:217], v[20:23]
	v_mfma_f32_16x16x32_bf16 v[12:15], v[170:173], v[214:217], v[12:15]
	v_mfma_f32_16x16x32_bf16 v[4:7], v[156:159], v[222:225], v[4:7]
	v_mfma_f32_16x16x32_bf16 v[0:3], v[170:173], v[222:225], v[0:3]
	v_mfma_f32_16x16x32_bf16 v[52:55], v[166:169], v[182:185], v[52:55]
	v_mfma_f32_16x16x32_bf16 v[44:47], v[174:177], v[182:185], v[44:47]
	v_mfma_f32_16x16x32_bf16 v[36:39], v[166:169], v[190:193], v[36:39]
	v_mfma_f32_16x16x32_bf16 v[28:31], v[174:177], v[190:193], v[28:31]
	v_mfma_f32_16x16x32_bf16 v[20:23], v[166:169], v[218:221], v[20:23]
	v_mfma_f32_16x16x32_bf16 v[12:15], v[174:177], v[218:221], v[12:15]
	v_mfma_f32_16x16x32_bf16 v[4:7], v[166:169], v[226:229], v[4:7]
	v_mfma_f32_16x16x32_bf16 v[0:3], v[174:177], v[226:229], v[0:3]
	s_setprio 0
	s_barrier
	s_add_i32 s21, s21, 2
	s_add_u32 s77, s77, 0x100
	s_addc_u32 s20, s20, 0
	s_add_u32 s90, s90, 0x100
	s_addc_u32 s91, s91, 0
	s_cmp_gt_u32 s21, 13
	s_cbranch_scc0 .LBB0_381
	s_and_b64 vcc, exec, s[58:59]
	s_cbranch_vccz .LBB0_384
	s_barrier

; #define PG8_STAGE(bufoff, gbase, voff) do { _Pragma("unroll") for (int _i = 0; _i < 2; ++_i) \
;         __builtin_amdgcn_global_load_lds((const unsigned*)((const char*)(gbase) + (voff)[_i]), (LAS unsigned*)(lds + (bufoff) + ldsw + _i * 8192), 16, 0, 0); } while (0)
; #define PG8_LDA(dst, b, h) do { _Pragma("unroll") for (int m = 0; m < 4; ++m) _Pragma("unroll") for (int k = 0; k < 2; ++k) dst[m][k] = *(const LAS bf16x8*)(lds + PG8_SA(b, h) + aoff + m * 2048 + k * 1024); } while (0)
; #define PG8_LDB(dst, b, h) do { _Pragma("unroll") for (int n = 0; n < 2; ++n) _Pragma("unroll") for (int k = 0; k < 2; ++k) dst[n][k] = *(const LAS bf16x8*)(lds + PG8_SB(b, h) + boff + n * 2048 + k * 1024); } while (0)
; #define PG8_MMA(ai, bj, At, Bt) do { __builtin_amdgcn_s_setprio(1); _Pragma("unroll") for (int m = 0; m < 4; ++m) _Pragma("unroll") for (int n = 0; n < 2; ++n) _Pragma("unroll") for (int k = 0; k < 2; ++k) \
;         acc[ai][bj][m][n] = __builtin_amdgcn_mfma_f32_16x16x32_bf16(Bt[n][k], At[m][k], acc[ai][bj][m][n], 0, 0, 0); __builtin_amdgcn_s_setprio(0); } while (0)
; #define PG8_WAIT_V(n) asm volatile("s_waitcnt vmcnt(" #n ")" ::: "memory")
; #define PG8_WAIT_L(n) asm volatile("s_waitcnt lgkmcnt(" #n ")" ::: "memory")
; #define PG8_BAR __builtin_amdgcn_s_barrier()
; template <class Epi, bool SP2, class Sched>
; __device__ __forceinline__ void gemm_phase(LAS unsigned char* lds, const Gemm g, const Sched& S, const Epi& E) {
;     ...
;             const bool last = (t == nt - 2);
;             const char* a1 = cA + (size_t)(t + 1) * kstep;
;             const char* a2 = last ? nA : cA + (size_t)(t + 2) * kstep; const char* b2 = last ? nB : cB + (size_t)(t + 2) * kstep;
;             const char* a3 = a2 + kstep; const char* b3 = b2 + kstep;
;             if constexpr (Epi::MID) { if (t == (nt >> 1)) E.mid(acc, cur, wr, fr); }
;             if constexpr (SP2) {
;             PG8_LDB(B0, 0, 0); PG8_LDB(B1, 0, 1); PG8_SCHED; PG8_LDA(At, 0, 0); PG8_STAGE(PG8_SA(1, 1), a1 + hstep, voffA);
;             PG8_WAIT_V(8); PG8_WAIT_L(0); PG8_BAR; PG8_MMA(0, 0, At, B0); PG8_MMA(0, 1, At, B1); PG8_BAR; PG8_SCHED;
;             PG8_LDA(At, 0, 1); PG8_STAGE(PG8_SB(0, 0), b2, voffB); PG8_STAGE(PG8_SB(0, 1), b2 + hstepB, voffB); PG8_STAGE(PG8_SA(0, 0), a2, voffA);
;             PG8_WAIT_V(8); PG8_WAIT_L(0); PG8_BAR; PG8_MMA(1, 0, At, B0); PG8_MMA(1, 1, At, B1); PG8_BAR; PG8_SCHED;
.LBB0_587:
	s_add_u32 s6, s94, 0xfffe0080
	s_addc_u32 s7, s95, -1
	s_add_i32 s20, 0, 0x10000
	s_cmp_eq_u32 s19, 4
	s_cselect_b32 s11, s5, s7
	s_cselect_b32 s10, s12, s6
	s_cselect_b32 s7, s13, s18
	s_cselect_b32 s6, s14, s15
	s_add_i32 s22, 0, 0x14000
	v_add_u32_e32 v156, s20, v145
	v_add_u32_e32 v172, s22, v145
	ds_read_b128 v[140:143], v156
	ds_read_b128 v[148:151], v156 offset:1024
	ds_read_b128 v[152:155], v156 offset:2048
	ds_read_b128 v[156:159], v156 offset:3072
	ds_read_b128 v[160:163], v172
	ds_read_b128 v[164:167], v172 offset:1024
	ds_read_b128 v[168:171], v172 offset:2048
	ds_read_b128 v[172:175], v172 offset:3072
	v_lshl_add_u64 v[192:193], s[94:95], 0, v[138:139]
	s_add_i32 m0, s17, 0xc000
	ds_read_b128 v[176:179], v147
	ds_read_b128 v[180:183], v147 offset:1024
	ds_read_b128 v[184:187], v147 offset:2048
	ds_read_b128 v[188:191], v147 offset:3072
	ds_read_b128 v[214:217], v147 offset:4096
	ds_read_b128 v[218:221], v147 offset:5120
	ds_read_b128 v[222:225], v147 offset:6144
	ds_read_b128 v[226:229], v147 offset:7168
	global_load_lds_dwordx4 v[192:193], off
	s_add_i32 m0, s17, 0xe000
	v_lshl_add_u64 v[192:193], s[94:95], 0, v[136:137]
	global_load_lds_dwordx4 v[192:193], off
	s_waitcnt vmcnt(8) lgkmcnt(0)
	s_barrier
	s_setprio 1
	v_mfma_f32_16x16x32_bf16 v[126:129], v[140:143], v[176:179], v[126:129]
	v_mfma_f32_16x16x32_bf16 v[122:125], v[152:155], v[176:179], v[122:125]
	v_mfma_f32_16x16x32_bf16 v[110:113], v[140:143], v[184:187], v[110:113]
	v_mfma_f32_16x16x32_bf16 v[106:109], v[152:155], v[184:187], v[106:109]
	v_mfma_f32_16x16x32_bf16 v[94:97], v[140:143], v[214:217], v[94:97]
	v_mfma_f32_16x16x32_bf16 v[90:93], v[152:155], v[214:217], v[90:93]
	v_mfma_f32_16x16x32_bf16 v[78:81], v[140:143], v[222:225], v[78:81]
	v_mfma_f32_16x16x32_bf16 v[74:77], v[152:155], v[222:225], v[74:77]
	v_mfma_f32_16x16x32_bf16 v[126:129], v[148:151], v[180:183], v[126:129]
	v_mfma_f32_16x16x32_bf16 v[122:125], v[156:159], v[180:183], v[122:125]
	v_mfma_f32_16x16x32_bf16 v[110:113], v[148:151], v[188:191], v[110:113]
	v_mfma_f32_16x16x32_bf16 v[106:109], v[156:159], v[188:191], v[106:109]
	v_mfma_f32_16x16x32_bf16 v[94:97], v[148:151], v[218:221], v[94:97]
	v_mfma_f32_16x16x32_bf16 v[90:93], v[156:159], v[218:221], v[90:93]
	v_mfma_f32_16x16x32_bf16 v[78:81], v[148:151], v[226:229], v[78:81]
	v_mfma_f32_16x16x32_bf16 v[74:77], v[156:159], v[226:229], v[74:77]
	s_setprio 0
	s_setprio 1
	v_mfma_f32_16x16x32_bf16 v[118:121], v[160:163], v[176:179], v[118:121]
	v_mfma_f32_16x16x32_bf16 v[114:117], v[168:171], v[176:179], v[114:117]
	v_mfma_f32_16x16x32_bf16 v[102:105], v[160:163], v[184:187], v[102:105]
	v_mfma_f32_16x16x32_bf16 v[98:101], v[168:171], v[184:187], v[98:101]
	v_mfma_f32_16x16x32_bf16 v[86:89], v[160:163], v[214:217], v[86:89]
	v_mfma_f32_16x16x32_bf16 v[82:85], v[168:171], v[214:217], v[82:85]
	v_mfma_f32_16x16x32_bf16 v[70:73], v[160:163], v[222:225], v[70:73]
	v_mfma_f32_16x16x32_bf16 v[66:69], v[168:171], v[222:225], v[66:69]
	v_mfma_f32_16x16x32_bf16 v[118:121], v[164:167], v[180:183], v[118:121]
	v_mfma_f32_16x16x32_bf16 v[114:117], v[172:175], v[180:183], v[114:117]
	v_mfma_f32_16x16x32_bf16 v[102:105], v[164:167], v[188:191], v[102:105]
	v_mfma_f32_16x16x32_bf16 v[98:101], v[172:175], v[188:191], v[98:101]
	v_mfma_f32_16x16x32_bf16 v[86:89], v[164:167], v[218:221], v[86:89]
	v_mfma_f32_16x16x32_bf16 v[82:85], v[172:175], v[218:221], v[82:85]
	v_mfma_f32_16x16x32_bf16 v[70:73], v[164:167], v[226:229], v[70:73]
	v_mfma_f32_16x16x32_bf16 v[66:69], v[172:175], v[226:229], v[66:69]
	s_setprio 0
	s_barrier
	s_add_i32 s20, s20, s65
	v_lshl_add_u64 v[192:193], s[6:7], 0, v[64:65]
	s_mov_b32 m0, s20
	ds_read_b128 v[176:179], v147 offset:16384
	ds_read_b128 v[180:183], v147 offset:17408
	ds_read_b128 v[184:187], v147 offset:18432
	ds_read_b128 v[188:191], v147 offset:19456
	ds_read_b128 v[214:217], v147 offset:20480
	ds_read_b128 v[218:221], v147 offset:21504
	ds_read_b128 v[222:225], v147 offset:22528
	ds_read_b128 v[226:229], v147 offset:23552
	global_load_lds_dwordx4 v[192:193], off
	s_add_i32 m0, s20, 0x2000
	s_add_u32 s20, s6, 0x20000
	v_lshl_add_u64 v[230:231], s[6:7], 0, v[134:135]
	s_addc_u32 s21, s7, 0
	s_add_i32 s22, s22, s65
	global_load_lds_dwordx4 v[230:231], off
	v_lshl_add_u64 v[232:233], s[20:21], 0, v[64:65]
	s_mov_b32 m0, s22
	v_lshl_add_u64 v[234:235], s[10:11], 0, v[132:133]
	global_load_lds_dwordx4 v[232:233], off
	s_add_i32 m0, s22, 0x2000
	v_lshl_add_u64 v[232:233], s[20:21], 0, v[134:135]
	global_load_lds_dwordx4 v[232:233], off
	s_mov_b32 m0, s17
	v_lshl_add_u64 v[232:233], s[10:11], 0, v[130:131]
	global_load_lds_dwordx4 v[232:233], off
	s_mov_b32 m0, s68
	s_nop 0
	global_load_lds_dwordx4 v[234:235], off
	s_waitcnt vmcnt(8) lgkmcnt(0)
	s_barrier
; #define PG8_STAGE(bufoff, gbase, voff) do { _Pragma("unroll") for (int _i = 0; _i < 2; ++_i) \
;         __builtin_amdgcn_global_load_lds((const unsigned*)((const char*)(gbase) + (voff)[_i]), (LAS unsigned*)(lds + (bufoff) + ldsw + _i * 8192), 16, 0, 0); } while (0)
; #define PG8_LDA(dst, b, h) do { _Pragma("unroll") for (int m = 0; m < 4; ++m) _Pragma("unroll") for (int k = 0; k < 2; ++k) dst[m][k] = *(const LAS bf16x8*)(lds + PG8_SA(b, h) + aoff + m * 2048 + k * 1024); } while (0)
; #define PG8_LDB(dst, b, h) do { _Pragma("unroll") for (int n = 0; n < 2; ++n) _Pragma("unroll") for (int k = 0; k < 2; ++k) dst[n][k] = *(const LAS bf16x8*)(lds + PG8_SB(b, h) + boff + n * 2048 + k * 1024); } while (0)
; #define PG8_MMA(ai, bj, At, Bt) do { __builtin_amdgcn_s_setprio(1); _Pragma("unroll") for (int m = 0; m < 4; ++m) _Pragma("unroll") for (int n = 0; n < 2; ++n) _Pragma("unroll") for (int k = 0; k < 2; ++k) \
;         acc[ai][bj][m][n] = __builtin_amdgcn_mfma_f32_16x16x32_bf16(Bt[n][k], At[m][k], acc[ai][bj][m][n], 0, 0, 0); __builtin_amdgcn_s_setprio(0); } while (0)
; #define PG8_WAIT_V(n) asm volatile("s_waitcnt vmcnt(" #n ")" ::: "memory")
; #define PG8_WAIT_L(n) asm volatile("s_waitcnt lgkmcnt(" #n ")" ::: "memory")
; #define PG8_BAR __builtin_amdgcn_s_barrier()
; #define PG8_SCHED __builtin_amdgcn_sched_barrier(0)
; template <class Epi, bool SP2, class Sched>
; __device__ __forceinline__ void gemm_phase(LAS unsigned char* lds, const Gemm g, const Sched& S, const Epi& E) {
;     ...
;             PG8_WAIT_V(8); PG8_WAIT_L(0); PG8_BAR; PG8_MMA(1, 0, At, B0); PG8_MMA(1, 1, At, B1); PG8_BAR; PG8_SCHED;
;             PG8_LDB(B0, 1, 0); PG8_LDB(B1, 1, 1); PG8_SCHED; PG8_LDA(At, 1, 0); PG8_STAGE(PG8_SA(0, 1), a2 + hstep, voffA);
;             PG8_WAIT_V(8); PG8_WAIT_L(0); PG8_BAR; PG8_MMA(0, 0, At, B0); PG8_MMA(0, 1, At, B1); PG8_BAR; PG8_SCHED;
	s_setprio 1
	v_mfma_f32_16x16x32_bf16 v[60:63], v[140:143], v[176:179], v[60:63]
	v_mfma_f32_16x16x32_bf16 v[56:59], v[152:155], v[176:179], v[56:59]
	v_mfma_f32_16x16x32_bf16 v[44:47], v[140:143], v[184:187], v[44:47]
	v_mfma_f32_16x16x32_bf16 v[40:43], v[152:155], v[184:187], v[40:43]
	v_mfma_f32_16x16x32_bf16 v[28:31], v[140:143], v[214:217], v[28:31]
	v_mfma_f32_16x16x32_bf16 v[24:27], v[152:155], v[214:217], v[24:27]
	v_mfma_f32_16x16x32_bf16 v[12:15], v[140:143], v[222:225], v[12:15]
	v_mfma_f32_16x16x32_bf16 v[8:11], v[152:155], v[222:225], v[8:11]
	v_mfma_f32_16x16x32_bf16 v[60:63], v[148:151], v[180:183], v[60:63]
	v_mfma_f32_16x16x32_bf16 v[56:59], v[156:159], v[180:183], v[56:59]
	v_mfma_f32_16x16x32_bf16 v[44:47], v[148:151], v[188:191], v[44:47]
	v_mfma_f32_16x16x32_bf16 v[40:43], v[156:159], v[188:191], v[40:43]
	v_mfma_f32_16x16x32_bf16 v[28:31], v[148:151], v[218:221], v[28:31]
	v_mfma_f32_16x16x32_bf16 v[24:27], v[156:159], v[218:221], v[24:27]
	v_mfma_f32_16x16x32_bf16 v[12:15], v[148:151], v[226:229], v[12:15]
	v_mfma_f32_16x16x32_bf16 v[8:11], v[156:159], v[226:229], v[8:11]
	s_setprio 0
	s_setprio 1
	v_mfma_f32_16x16x32_bf16 v[52:55], v[160:163], v[176:179], v[52:55]
	v_mfma_f32_16x16x32_bf16 v[48:51], v[168:171], v[176:179], v[48:51]
	v_mfma_f32_16x16x32_bf16 v[36:39], v[160:163], v[184:187], v[36:39]
	v_mfma_f32_16x16x32_bf16 v[32:35], v[168:171], v[184:187], v[32:35]
	v_mfma_f32_16x16x32_bf16 v[20:23], v[160:163], v[214:217], v[20:23]
	v_mfma_f32_16x16x32_bf16 v[16:19], v[168:171], v[214:217], v[16:19]
	v_mfma_f32_16x16x32_bf16 v[4:7], v[160:163], v[222:225], v[4:7]
	v_mfma_f32_16x16x32_bf16 v[0:3], v[168:171], v[222:225], v[0:3]
	v_mfma_f32_16x16x32_bf16 v[52:55], v[164:167], v[180:183], v[52:55]
	v_mfma_f32_16x16x32_bf16 v[48:51], v[172:175], v[180:183], v[48:51]
	v_mfma_f32_16x16x32_bf16 v[36:39], v[164:167], v[188:191], v[36:39]
	v_mfma_f32_16x16x32_bf16 v[32:35], v[172:175], v[188:191], v[32:35]
	v_mfma_f32_16x16x32_bf16 v[20:23], v[164:167], v[218:221], v[20:23]
	v_mfma_f32_16x16x32_bf16 v[16:19], v[172:175], v[218:221], v[16:19]
	v_mfma_f32_16x16x32_bf16 v[4:7], v[164:167], v[226:229], v[4:7]
	v_mfma_f32_16x16x32_bf16 v[0:3], v[172:175], v[226:229], v[0:3]
	s_setprio 0
	s_barrier
	s_add_i32 s20, 0, 0x18000
	s_add_i32 s21, 0, 0x1c000
	v_add_u32_e32 v156, s20, v145
	v_add_u32_e32 v172, s21, v145
	ds_read_b128 v[140:143], v156
	ds_read_b128 v[148:151], v156 offset:1024
	ds_read_b128 v[152:155], v156 offset:2048
	ds_read_b128 v[156:159], v156 offset:3072
	ds_read_b128 v[160:163], v172
	ds_read_b128 v[164:167], v172 offset:1024
	ds_read_b128 v[168:171], v172 offset:2048
	ds_read_b128 v[172:175], v172 offset:3072
	s_add_u32 s10, s10, 0x20000
	s_addc_u32 s11, s11, 0
	s_mov_b32 m0, s69
	v_lshl_add_u64 v[236:237], s[10:11], 0, v[130:131]
	ds_read_b128 v[176:179], v147 offset:32768
	ds_read_b128 v[180:183], v147 offset:33792
	ds_read_b128 v[184:187], v147 offset:34816
	ds_read_b128 v[188:191], v147 offset:35840
	ds_read_b128 v[214:217], v147 offset:36864
	ds_read_b128 v[218:221], v147 offset:37888
	ds_read_b128 v[222:225], v147 offset:38912
	ds_read_b128 v[226:229], v147 offset:39936
	global_load_lds_dwordx4 v[236:237], off
	s_mov_b32 m0, s72
	v_lshl_add_u64 v[236:237], s[10:11], 0, v[132:133]
	global_load_lds_dwordx4 v[236:237], off
	s_waitcnt vmcnt(8) lgkmcnt(0)
	s_barrier
	s_setprio 1
	v_mfma_f32_16x16x32_bf16 v[126:129], v[140:143], v[176:179], v[126:129]
	v_mfma_f32_16x16x32_bf16 v[122:125], v[152:155], v[176:179], v[122:125]
	v_mfma_f32_16x16x32_bf16 v[110:113], v[140:143], v[184:187], v[110:113]
	v_mfma_f32_16x16x32_bf16 v[106:109], v[152:155], v[184:187], v[106:109]
	v_mfma_f32_16x16x32_bf16 v[94:97], v[140:143], v[214:217], v[94:97]
	v_mfma_f32_16x16x32_bf16 v[90:93], v[152:155], v[214:217], v[90:93]
	v_mfma_f32_16x16x32_bf16 v[78:81], v[140:143], v[222:225], v[78:81]
	v_mfma_f32_16x16x32_bf16 v[74:77], v[152:155], v[222:225], v[74:77]
	v_mfma_f32_16x16x32_bf16 v[126:129], v[148:151], v[180:183], v[126:129]
	v_mfma_f32_16x16x32_bf16 v[122:125], v[156:159], v[180:183], v[122:125]
	v_mfma_f32_16x16x32_bf16 v[110:113], v[148:151], v[188:191], v[110:113]
	v_mfma_f32_16x16x32_bf16 v[106:109], v[156:159], v[188:191], v[106:109]
	v_mfma_f32_16x16x32_bf16 v[94:97], v[148:151], v[218:221], v[94:97]
	v_mfma_f32_16x16x32_bf16 v[90:93], v[156:159], v[218:221], v[90:93]
	v_mfma_f32_16x16x32_bf16 v[78:81], v[148:151], v[226:229], v[78:81]
	v_mfma_f32_16x16x32_bf16 v[74:77], v[156:159], v[226:229], v[74:77]
	s_setprio 0
	s_setprio 1
	v_mfma_f32_16x16x32_bf16 v[118:121], v[160:163], v[176:179], v[118:121]
	v_mfma_f32_16x16x32_bf16 v[114:117], v[168:171], v[176:179], v[114:117]
	v_mfma_f32_16x16x32_bf16 v[102:105], v[160:163], v[184:187], v[102:105]
	v_mfma_f32_16x16x32_bf16 v[98:101], v[168:171], v[184:187], v[98:101]
	v_mfma_f32_16x16x32_bf16 v[86:89], v[160:163], v[214:217], v[86:89]
	v_mfma_f32_16x16x32_bf16 v[82:85], v[168:171], v[214:217], v[82:85]
	v_mfma_f32_16x16x32_bf16 v[70:73], v[160:163], v[222:225], v[70:73]
	v_mfma_f32_16x16x32_bf16 v[66:69], v[168:171], v[222:225], v[66:69]
	v_mfma_f32_16x16x32_bf16 v[118:121], v[164:167], v[180:183], v[118:121]
	v_mfma_f32_16x16x32_bf16 v[114:117], v[172:175], v[180:183], v[114:117]
	v_mfma_f32_16x16x32_bf16 v[102:105], v[164:167], v[188:191], v[102:105]
	v_mfma_f32_16x16x32_bf16 v[98:101], v[172:175], v[188:191], v[98:101]
	v_mfma_f32_16x16x32_bf16 v[86:89], v[164:167], v[218:221], v[86:89]
	v_mfma_f32_16x16x32_bf16 v[82:85], v[172:175], v[218:221], v[82:85]
	v_mfma_f32_16x16x32_bf16 v[70:73], v[164:167], v[226:229], v[70:73]
	v_mfma_f32_16x16x32_bf16 v[66:69], v[172:175], v[226:229], v[66:69]
	s_setprio 0
	s_barrier
; #define PG8_STAGE(bufoff, gbase, voff) do { _Pragma("unroll") for (int _i = 0; _i < 2; ++_i) \
;         __builtin_amdgcn_global_load_lds((const unsigned*)((const char*)(gbase) + (voff)[_i]), (LAS unsigned*)(lds + (bufoff) + ldsw + _i * 8192), 16, 0, 0); } while (0)
; #define PG8_LDA(dst, b, h) do { _Pragma("unroll") for (int m = 0; m < 4; ++m) _Pragma("unroll") for (int k = 0; k < 2; ++k) dst[m][k] = *(const LAS bf16x8*)(lds + PG8_SA(b, h) + aoff + m * 2048 + k * 1024); } while (0)
; #define PG8_MMA(ai, bj, At, Bt) do { __builtin_amdgcn_s_setprio(1); _Pragma("unroll") for (int m = 0; m < 4; ++m) _Pragma("unroll") for (int n = 0; n < 2; ++n) _Pragma("unroll") for (int k = 0; k < 2; ++k) \
;         acc[ai][bj][m][n] = __builtin_amdgcn_mfma_f32_16x16x32_bf16(Bt[n][k], At[m][k], acc[ai][bj][m][n], 0, 0, 0); __builtin_amdgcn_s_setprio(0); } while (0)
; #define PG8_WAIT_V(n) asm volatile("s_waitcnt vmcnt(" #n ")" ::: "memory")
; #define PG8_WAIT_L(n) asm volatile("s_waitcnt lgkmcnt(" #n ")" ::: "memory")
; #define PG8_BAR __builtin_amdgcn_s_barrier()
; #define PG8_SCHED __builtin_amdgcn_sched_barrier(0)
; template <class Epi, bool SP2, class Sched>
; __device__ __forceinline__ void gemm_phase(LAS unsigned char* lds, const Gemm g, const Sched& S, const Epi& E) {
;     ...
;             PG8_LDA(At, 1, 1); PG8_STAGE(PG8_SB(1, 0), b3, voffB); PG8_STAGE(PG8_SB(1, 1), b3 + hstepB, voffB); PG8_STAGE(PG8_SA(1, 0), a3, voffA);
;             PG8_WAIT_V(8); PG8_WAIT_L(0); PG8_BAR; PG8_MMA(1, 0, At, B0); PG8_MMA(1, 1, At, B1); PG8_BAR; PG8_SCHED;
;     ...
;         if (wr == 0) PG8_BAR;
	s_add_i32 s10, s20, s65
	v_lshl_add_u64 v[192:193], v[192:193], 0, s[66:67]
	s_mov_b32 m0, s10
	ds_read_b128 v[176:179], v147 offset:49152
	ds_read_b128 v[180:183], v147 offset:50176
	ds_read_b128 v[184:187], v147 offset:51200
	ds_read_b128 v[188:191], v147 offset:52224
	ds_read_b128 v[214:217], v147 offset:53248
	ds_read_b128 v[218:221], v147 offset:54272
	ds_read_b128 v[222:225], v147 offset:55296
	ds_read_b128 v[226:229], v147 offset:56320
	global_load_lds_dwordx4 v[192:193], off
	s_add_i32 m0, s10, 0x2000
	s_add_u32 s6, s6, 0x20080
	v_lshl_add_u64 v[192:193], v[230:231], 0, s[66:67]
	s_addc_u32 s7, s7, 0
	s_add_i32 s10, s21, s65
	global_load_lds_dwordx4 v[192:193], off
	s_mov_b32 m0, s10
	v_lshl_add_u64 v[192:193], s[6:7], 0, v[64:65]
	global_load_lds_dwordx4 v[192:193], off
	s_add_i32 m0, s10, 0x2000
	v_lshl_add_u64 v[192:193], s[6:7], 0, v[134:135]
	global_load_lds_dwordx4 v[192:193], off
	s_mov_b32 m0, s73
	v_lshl_add_u64 v[192:193], v[232:233], 0, s[66:67]
	global_load_lds_dwordx4 v[192:193], off
	s_mov_b32 m0, s74
	v_lshl_add_u64 v[192:193], v[234:235], 0, s[66:67]
	global_load_lds_dwordx4 v[192:193], off
	s_waitcnt vmcnt(8) lgkmcnt(0)
	s_barrier
	s_setprio 1
	v_mfma_f32_16x16x32_bf16 v[60:63], v[140:143], v[176:179], v[60:63]
	v_mfma_f32_16x16x32_bf16 v[56:59], v[152:155], v[176:179], v[56:59]
	v_mfma_f32_16x16x32_bf16 v[44:47], v[140:143], v[184:187], v[44:47]
	v_mfma_f32_16x16x32_bf16 v[40:43], v[152:155], v[184:187], v[40:43]
	v_mfma_f32_16x16x32_bf16 v[28:31], v[140:143], v[214:217], v[28:31]
	v_mfma_f32_16x16x32_bf16 v[24:27], v[152:155], v[214:217], v[24:27]
	v_mfma_f32_16x16x32_bf16 v[12:15], v[140:143], v[222:225], v[12:15]
	v_mfma_f32_16x16x32_bf16 v[8:11], v[152:155], v[222:225], v[8:11]
	v_mfma_f32_16x16x32_bf16 v[60:63], v[148:151], v[180:183], v[60:63]
	v_mfma_f32_16x16x32_bf16 v[56:59], v[156:159], v[180:183], v[56:59]
	v_mfma_f32_16x16x32_bf16 v[44:47], v[148:151], v[188:191], v[44:47]
	v_mfma_f32_16x16x32_bf16 v[40:43], v[156:159], v[188:191], v[40:43]
	v_mfma_f32_16x16x32_bf16 v[28:31], v[148:151], v[218:221], v[28:31]
	v_mfma_f32_16x16x32_bf16 v[24:27], v[156:159], v[218:221], v[24:27]
	v_mfma_f32_16x16x32_bf16 v[12:15], v[148:151], v[226:229], v[12:15]
	v_mfma_f32_16x16x32_bf16 v[8:11], v[156:159], v[226:229], v[8:11]
	s_setprio 0
	s_setprio 1
	v_mfma_f32_16x16x32_bf16 v[52:55], v[160:163], v[176:179], v[52:55]
	v_mfma_f32_16x16x32_bf16 v[48:51], v[168:171], v[176:179], v[48:51]
	v_mfma_f32_16x16x32_bf16 v[36:39], v[160:163], v[184:187], v[36:39]
	v_mfma_f32_16x16x32_bf16 v[32:35], v[168:171], v[184:187], v[32:35]
	v_mfma_f32_16x16x32_bf16 v[20:23], v[160:163], v[214:217], v[20:23]
	v_mfma_f32_16x16x32_bf16 v[16:19], v[168:171], v[214:217], v[16:19]
	v_mfma_f32_16x16x32_bf16 v[4:7], v[160:163], v[222:225], v[4:7]
	v_mfma_f32_16x16x32_bf16 v[0:3], v[168:171], v[222:225], v[0:3]
	v_mfma_f32_16x16x32_bf16 v[52:55], v[164:167], v[180:183], v[52:55]
	v_mfma_f32_16x16x32_bf16 v[48:51], v[172:175], v[180:183], v[48:51]
	v_mfma_f32_16x16x32_bf16 v[36:39], v[164:167], v[188:191], v[36:39]
	v_mfma_f32_16x16x32_bf16 v[32:35], v[172:175], v[188:191], v[32:35]
	v_mfma_f32_16x16x32_bf16 v[20:23], v[164:167], v[218:221], v[20:23]
	v_mfma_f32_16x16x32_bf16 v[16:19], v[172:175], v[218:221], v[16:19]
	v_mfma_f32_16x16x32_bf16 v[4:7], v[164:167], v[226:229], v[4:7]
	v_mfma_f32_16x16x32_bf16 v[0:3], v[172:175], v[226:229], v[0:3]
	s_setprio 0
	s_barrier
	s_add_i32 s19, s19, 2
	s_add_u32 s15, s15, 0x100
	s_addc_u32 s18, s18, 0
	s_add_u32 s94, s94, 0x100
	s_addc_u32 s95, s95, 0
	s_cmp_gt_u32 s19, 5
	s_cbranch_scc0 .LBB0_587
	s_and_b64 vcc, exec, s[84:85]
	s_cbranch_vccz .LBB0_590
	s_barrier

; #define PG8_STAGE(bufoff, gbase, voff) do { _Pragma("unroll") for (int _i = 0; _i < 2; ++_i) \
;         __builtin_amdgcn_global_load_lds((const unsigned*)((const char*)(gbase) + (voff)[_i]), (LAS unsigned*)(lds + (bufoff) + ldsw + _i * 8192), 16, 0, 0); } while (0)
; #define PG8_LDA(dst, b, h) do { _Pragma("unroll") for (int m = 0; m < 4; ++m) _Pragma("unroll") for (int k = 0; k < 2; ++k) dst[m][k] = *(const LAS bf16x8*)(lds + PG8_SA(b, h) + aoff + m * 2048 + k * 1024); } while (0)
; #define PG8_LDB(dst, b, h) do { _Pragma("unroll") for (int n = 0; n < 2; ++n) _Pragma("unroll") for (int k = 0; k < 2; ++k) dst[n][k] = *(const LAS bf16x8*)(lds + PG8_SB(b, h) + boff + n * 2048 + k * 1024); } while (0)
; #define PG8_MMA(ai, bj, At, Bt) do { __builtin_amdgcn_s_setprio(1); _Pragma("unroll") for (int m = 0; m < 4; ++m) _Pragma("unroll") for (int n = 0; n < 2; ++n) _Pragma("unroll") for (int k = 0; k < 2; ++k) \
;         acc[ai][bj][m][n] = __builtin_amdgcn_mfma_f32_16x16x32_bf16(Bt[n][k], At[m][k], acc[ai][bj][m][n], 0, 0, 0); __builtin_amdgcn_s_setprio(0); } while (0)
; #define PG8_WAIT_V(n) asm volatile("s_waitcnt vmcnt(" #n ")" ::: "memory")
; #define PG8_WAIT_L(n) asm volatile("s_waitcnt lgkmcnt(" #n ")" ::: "memory")
; #define PG8_BAR __builtin_amdgcn_s_barrier()
; template <class Epi, bool SP2, class Sched>
; __device__ __forceinline__ void gemm_phase(LAS unsigned char* lds, const Gemm g, const Sched& S, const Epi& E) {
;     ...
;             const bool last = (t == nt - 2);
;             const char* a1 = cA + (size_t)(t + 1) * kstep;
;             const char* a2 = last ? nA : cA + (size_t)(t + 2) * kstep; const char* b2 = last ? nB : cB + (size_t)(t + 2) * kstep;
;             const char* a3 = a2 + kstep; const char* b3 = b2 + kstep;
;             if constexpr (Epi::MID) { if (t == (nt >> 1)) E.mid(acc, cur, wr, fr); }
;             if constexpr (SP2) {
;             PG8_LDB(B0, 0, 0); PG8_LDB(B1, 0, 1); PG8_SCHED; PG8_LDA(At, 0, 0); PG8_STAGE(PG8_SA(1, 1), a1 + hstep, voffA);
;             PG8_WAIT_V(8); PG8_WAIT_L(0); PG8_BAR; PG8_MMA(0, 0, At, B0); PG8_MMA(0, 1, At, B1); PG8_BAR; PG8_SCHED;
;             PG8_LDA(At, 0, 1); PG8_STAGE(PG8_SB(0, 0), b2, voffB); PG8_STAGE(PG8_SB(0, 1), b2 + hstepB, voffB); PG8_STAGE(PG8_SA(0, 0), a2, voffA);
;             PG8_WAIT_V(8); PG8_WAIT_L(0); PG8_BAR; PG8_MMA(1, 0, At, B0); PG8_MMA(1, 1, At, B1); PG8_BAR; PG8_SCHED;
.LBB0_673:
	s_add_u32 s6, s94, s96
	s_addc_u32 s7, s95, s97
	s_add_u32 s6, s6, 0x100
	s_addc_u32 s7, s7, 0
	s_add_u32 s19, s15, s96
	s_addc_u32 s20, s16, s97
	s_cmpk_eq_i32 s96, 0x700
	s_cselect_b32 s11, s5, s7
	s_cselect_b32 s10, s12, s6
	s_cselect_b32 s7, s13, s20
	s_cselect_b32 s6, s14, s19
	s_add_i32 s19, 0, 0x10000
	v_add_u32_e32 v64, s19, v153
	s_add_i32 s22, 0, 0x14000
	ds_read_b128 v[156:159], v64
	ds_read_b128 v[160:163], v64 offset:1024
	ds_read_b128 v[164:167], v64 offset:2048
	ds_read_b128 v[168:171], v64 offset:3072
	v_add_u32_e32 v64, s22, v153
	ds_read_b128 v[172:175], v64
	ds_read_b128 v[176:179], v64 offset:1024
	ds_read_b128 v[180:183], v64 offset:2048
	ds_read_b128 v[184:187], v64 offset:3072
	v_lshl_add_u64 v[66:67], v[150:151], 0, s[96:97]
	s_add_i32 m0, s17, 0xc000
	ds_read_b128 v[188:191], v155
	ds_read_b128 v[214:217], v155 offset:1024
	ds_read_b128 v[218:221], v155 offset:2048
	ds_read_b128 v[222:225], v155 offset:3072
	ds_read_b128 v[226:229], v155 offset:4096
	ds_read_b128 v[230:233], v155 offset:5120
	ds_read_b128 v[234:237], v155 offset:6144
	ds_read_b128 v[238:241], v155 offset:7168
	global_load_lds_dwordx4 v[66:67], off
	s_add_i32 m0, s17, 0xe000
	v_lshl_add_u64 v[66:67], v[148:149], 0, s[96:97]
	global_load_lds_dwordx4 v[66:67], off
	s_waitcnt vmcnt(8) lgkmcnt(0)
	s_barrier
	s_setprio 1
	v_mfma_f32_16x16x32_bf16 v[128:131], v[156:159], v[188:191], v[128:131]
	v_mfma_f32_16x16x32_bf16 v[124:127], v[164:167], v[188:191], v[124:127]
	v_mfma_f32_16x16x32_bf16 v[112:115], v[156:159], v[218:221], v[112:115]
	v_mfma_f32_16x16x32_bf16 v[108:111], v[164:167], v[218:221], v[108:111]
	v_mfma_f32_16x16x32_bf16 v[96:99], v[156:159], v[226:229], v[96:99]
	v_mfma_f32_16x16x32_bf16 v[92:95], v[164:167], v[226:229], v[92:95]
	v_mfma_f32_16x16x32_bf16 v[80:83], v[156:159], v[234:237], v[80:83]
	v_mfma_f32_16x16x32_bf16 v[76:79], v[164:167], v[234:237], v[76:79]
	v_mfma_f32_16x16x32_bf16 v[128:131], v[160:163], v[214:217], v[128:131]
	v_mfma_f32_16x16x32_bf16 v[124:127], v[168:171], v[214:217], v[124:127]
	v_mfma_f32_16x16x32_bf16 v[112:115], v[160:163], v[222:225], v[112:115]
	v_mfma_f32_16x16x32_bf16 v[108:111], v[168:171], v[222:225], v[108:111]
	v_mfma_f32_16x16x32_bf16 v[96:99], v[160:163], v[230:233], v[96:99]
	v_mfma_f32_16x16x32_bf16 v[92:95], v[168:171], v[230:233], v[92:95]
	v_mfma_f32_16x16x32_bf16 v[80:83], v[160:163], v[238:241], v[80:83]
	v_mfma_f32_16x16x32_bf16 v[76:79], v[168:171], v[238:241], v[76:79]
	s_setprio 0
	s_setprio 1
	v_mfma_f32_16x16x32_bf16 v[120:123], v[172:175], v[188:191], v[120:123]
	v_mfma_f32_16x16x32_bf16 v[116:119], v[180:183], v[188:191], v[116:119]
	v_mfma_f32_16x16x32_bf16 v[104:107], v[172:175], v[218:221], v[104:107]
	v_mfma_f32_16x16x32_bf16 v[100:103], v[180:183], v[218:221], v[100:103]
	v_mfma_f32_16x16x32_bf16 v[88:91], v[172:175], v[226:229], v[88:91]
	v_mfma_f32_16x16x32_bf16 v[84:87], v[180:183], v[226:229], v[84:87]
	v_mfma_f32_16x16x32_bf16 v[72:75], v[172:175], v[234:237], v[72:75]
	v_mfma_f32_16x16x32_bf16 v[66:69], v[180:183], v[234:237], v[68:71]
	v_mfma_f32_16x16x32_bf16 v[120:123], v[176:179], v[214:217], v[120:123]
	v_mfma_f32_16x16x32_bf16 v[116:119], v[184:187], v[214:217], v[116:119]
	v_mfma_f32_16x16x32_bf16 v[104:107], v[176:179], v[222:225], v[104:107]
	v_mfma_f32_16x16x32_bf16 v[100:103], v[184:187], v[222:225], v[100:103]
	v_mfma_f32_16x16x32_bf16 v[88:91], v[176:179], v[230:233], v[88:91]
	v_mfma_f32_16x16x32_bf16 v[84:87], v[184:187], v[230:233], v[84:87]
	v_mfma_f32_16x16x32_bf16 v[72:75], v[176:179], v[238:241], v[72:75]
	v_mfma_f32_16x16x32_bf16 v[66:69], v[184:187], v[238:241], v[66:69]
	s_setprio 0
	s_barrier
	s_add_i32 s19, s19, s73
	v_lshl_add_u64 v[192:193], s[6:7], 0, v[134:135]
	s_mov_b32 m0, s19
	ds_read_b128 v[188:191], v155 offset:16384
	ds_read_b128 v[214:217], v155 offset:17408
	ds_read_b128 v[218:221], v155 offset:18432
	ds_read_b128 v[222:225], v155 offset:19456
	ds_read_b128 v[226:229], v155 offset:20480
	ds_read_b128 v[230:233], v155 offset:21504
	ds_read_b128 v[234:237], v155 offset:22528
	ds_read_b128 v[238:241], v155 offset:23552
	global_load_lds_dwordx4 v[192:193], off
	s_add_i32 m0, s19, 0x2000
	s_add_u32 s20, s6, 0x40000
	v_lshl_add_u64 v[248:249], s[6:7], 0, v[138:139]
	s_addc_u32 s21, s7, 0
	s_add_i32 s19, s22, s73
	global_load_lds_dwordx4 v[248:249], off
	v_lshl_add_u64 v[70:71], s[20:21], 0, v[134:135]
	s_mov_b32 m0, s19
	v_lshl_add_u64 v[250:251], s[10:11], 0, v[132:133]
	global_load_lds_dwordx4 v[70:71], off
	v_lshl_add_u64 v[70:71], s[20:21], 0, v[138:139]
	s_add_i32 m0, s19, 0x2000
	v_lshl_add_u64 v[252:253], s[10:11], 0, v[136:137]
	global_load_lds_dwordx4 v[70:71], off
	s_mov_b32 m0, s17
	s_nop 0
	global_load_lds_dwordx4 v[250:251], off
	s_mov_b32 m0, s79
	s_nop 0
	global_load_lds_dwordx4 v[252:253], off
	s_waitcnt vmcnt(8) lgkmcnt(0)
	s_barrier
; #define PG8_STAGE(bufoff, gbase, voff) do { _Pragma("unroll") for (int _i = 0; _i < 2; ++_i) \
;         __builtin_amdgcn_global_load_lds((const unsigned*)((const char*)(gbase) + (voff)[_i]), (LAS unsigned*)(lds + (bufoff) + ldsw + _i * 8192), 16, 0, 0); } while (0)
; #define PG8_LDA(dst, b, h) do { _Pragma("unroll") for (int m = 0; m < 4; ++m) _Pragma("unroll") for (int k = 0; k < 2; ++k) dst[m][k] = *(const LAS bf16x8*)(lds + PG8_SA(b, h) + aoff + m * 2048 + k * 1024); } while (0)
; #define PG8_LDB(dst, b, h) do { _Pragma("unroll") for (int n = 0; n < 2; ++n) _Pragma("unroll") for (int k = 0; k < 2; ++k) dst[n][k] = *(const LAS bf16x8*)(lds + PG8_SB(b, h) + boff + n * 2048 + k * 1024); } while (0)
; #define PG8_MMA(ai, bj, At, Bt) do { __builtin_amdgcn_s_setprio(1); _Pragma("unroll") for (int m = 0; m < 4; ++m) _Pragma("unroll") for (int n = 0; n < 2; ++n) _Pragma("unroll") for (int k = 0; k < 2; ++k) \
;         acc[ai][bj][m][n] = __builtin_amdgcn_mfma_f32_16x16x32_bf16(Bt[n][k], At[m][k], acc[ai][bj][m][n], 0, 0, 0); __builtin_amdgcn_s_setprio(0); } while (0)
; #define PG8_WAIT_V(n) asm volatile("s_waitcnt vmcnt(" #n ")" ::: "memory")
; #define PG8_WAIT_L(n) asm volatile("s_waitcnt lgkmcnt(" #n ")" ::: "memory")
; #define PG8_BAR __builtin_amdgcn_s_barrier()
; #define PG8_SCHED __builtin_amdgcn_sched_barrier(0)
; template <class Epi, bool SP2, class Sched>
; __device__ __forceinline__ void gemm_phase(LAS unsigned char* lds, const Gemm g, const Sched& S, const Epi& E) {
;     ...
;             PG8_WAIT_V(8); PG8_WAIT_L(0); PG8_BAR; PG8_MMA(1, 0, At, B0); PG8_MMA(1, 1, At, B1); PG8_BAR; PG8_SCHED;
;             PG8_LDB(B0, 1, 0); PG8_LDB(B1, 1, 1); PG8_SCHED; PG8_LDA(At, 1, 0); PG8_STAGE(PG8_SA(0, 1), a2 + hstep, voffA);
;             PG8_WAIT_V(8); PG8_WAIT_L(0); PG8_BAR; PG8_MMA(0, 0, At, B0); PG8_MMA(0, 1, At, B1); PG8_BAR; PG8_SCHED;
	s_setprio 1
	v_mfma_f32_16x16x32_bf16 v[60:63], v[156:159], v[188:191], v[60:63]
	v_mfma_f32_16x16x32_bf16 v[56:59], v[164:167], v[188:191], v[56:59]
	v_mfma_f32_16x16x32_bf16 v[44:47], v[156:159], v[218:221], v[44:47]
	v_mfma_f32_16x16x32_bf16 v[40:43], v[164:167], v[218:221], v[40:43]
	v_mfma_f32_16x16x32_bf16 v[28:31], v[156:159], v[226:229], v[28:31]
	v_mfma_f32_16x16x32_bf16 v[24:27], v[164:167], v[226:229], v[24:27]
	v_mfma_f32_16x16x32_bf16 v[12:15], v[156:159], v[234:237], v[12:15]
	v_mfma_f32_16x16x32_bf16 v[8:11], v[164:167], v[234:237], v[8:11]
	v_mfma_f32_16x16x32_bf16 v[60:63], v[160:163], v[214:217], v[60:63]
	v_mfma_f32_16x16x32_bf16 v[56:59], v[168:171], v[214:217], v[56:59]
	v_mfma_f32_16x16x32_bf16 v[44:47], v[160:163], v[222:225], v[44:47]
	v_mfma_f32_16x16x32_bf16 v[40:43], v[168:171], v[222:225], v[40:43]
	v_mfma_f32_16x16x32_bf16 v[28:31], v[160:163], v[230:233], v[28:31]
	v_mfma_f32_16x16x32_bf16 v[24:27], v[168:171], v[230:233], v[24:27]
	v_mfma_f32_16x16x32_bf16 v[12:15], v[160:163], v[238:241], v[12:15]
	v_mfma_f32_16x16x32_bf16 v[8:11], v[168:171], v[238:241], v[8:11]
	s_setprio 0
	s_setprio 1
	v_mfma_f32_16x16x32_bf16 v[52:55], v[172:175], v[188:191], v[52:55]
	v_mfma_f32_16x16x32_bf16 v[48:51], v[180:183], v[188:191], v[48:51]
	v_mfma_f32_16x16x32_bf16 v[36:39], v[172:175], v[218:221], v[36:39]
	v_mfma_f32_16x16x32_bf16 v[32:35], v[180:183], v[218:221], v[32:35]
	v_mfma_f32_16x16x32_bf16 v[20:23], v[172:175], v[226:229], v[20:23]
	v_mfma_f32_16x16x32_bf16 v[16:19], v[180:183], v[226:229], v[16:19]
	v_mfma_f32_16x16x32_bf16 v[4:7], v[172:175], v[234:237], v[4:7]
	v_mfma_f32_16x16x32_bf16 v[0:3], v[180:183], v[234:237], v[0:3]
	v_mfma_f32_16x16x32_bf16 v[52:55], v[176:179], v[214:217], v[52:55]
	v_mfma_f32_16x16x32_bf16 v[48:51], v[184:187], v[214:217], v[48:51]
	v_mfma_f32_16x16x32_bf16 v[36:39], v[176:179], v[222:225], v[36:39]
	v_mfma_f32_16x16x32_bf16 v[32:35], v[184:187], v[222:225], v[32:35]
	v_mfma_f32_16x16x32_bf16 v[20:23], v[176:179], v[230:233], v[20:23]
	v_mfma_f32_16x16x32_bf16 v[16:19], v[184:187], v[230:233], v[16:19]
	v_mfma_f32_16x16x32_bf16 v[4:7], v[176:179], v[238:241], v[4:7]
	v_mfma_f32_16x16x32_bf16 v[0:3], v[184:187], v[238:241], v[0:3]
	s_setprio 0
	s_barrier
	s_add_i32 s19, 0, 0x18000
	v_add_u32_e32 v64, s19, v153
	s_add_i32 s20, 0, 0x1c000
	ds_read_b128 v[156:159], v64
	ds_read_b128 v[160:163], v64 offset:1024
	ds_read_b128 v[164:167], v64 offset:2048
	ds_read_b128 v[168:171], v64 offset:3072
	v_add_u32_e32 v64, s20, v153
	ds_read_b128 v[172:175], v64
	ds_read_b128 v[176:179], v64 offset:1024
	ds_read_b128 v[180:183], v64 offset:2048
	ds_read_b128 v[184:187], v64 offset:3072
	s_add_u32 s10, s10, 0x40000
	s_addc_u32 s11, s11, 0
	s_mov_b32 m0, s83
	v_lshl_add_u64 v[70:71], s[10:11], 0, v[132:133]
	ds_read_b128 v[188:191], v155 offset:32768
	ds_read_b128 v[214:217], v155 offset:33792
	ds_read_b128 v[218:221], v155 offset:34816
	ds_read_b128 v[222:225], v155 offset:35840
	ds_read_b128 v[226:229], v155 offset:36864
	ds_read_b128 v[230:233], v155 offset:37888
	ds_read_b128 v[234:237], v155 offset:38912
	ds_read_b128 v[238:241], v155 offset:39936
	global_load_lds_dwordx4 v[70:71], off
	s_mov_b32 m0, s74
	v_lshl_add_u64 v[70:71], s[10:11], 0, v[136:137]
	global_load_lds_dwordx4 v[70:71], off
	s_waitcnt vmcnt(8) lgkmcnt(0)
	s_barrier
	s_setprio 1
	v_mfma_f32_16x16x32_bf16 v[128:131], v[156:159], v[188:191], v[128:131]
	v_mfma_f32_16x16x32_bf16 v[124:127], v[164:167], v[188:191], v[124:127]
	v_mfma_f32_16x16x32_bf16 v[112:115], v[156:159], v[218:221], v[112:115]
	v_mfma_f32_16x16x32_bf16 v[108:111], v[164:167], v[218:221], v[108:111]
	v_mfma_f32_16x16x32_bf16 v[96:99], v[156:159], v[226:229], v[96:99]
	v_mfma_f32_16x16x32_bf16 v[92:95], v[164:167], v[226:229], v[92:95]
	v_mfma_f32_16x16x32_bf16 v[80:83], v[156:159], v[234:237], v[80:83]
	v_mfma_f32_16x16x32_bf16 v[76:79], v[164:167], v[234:237], v[76:79]
	v_mfma_f32_16x16x32_bf16 v[128:131], v[160:163], v[214:217], v[128:131]
	v_mfma_f32_16x16x32_bf16 v[124:127], v[168:171], v[214:217], v[124:127]
	v_mfma_f32_16x16x32_bf16 v[112:115], v[160:163], v[222:225], v[112:115]
	v_mfma_f32_16x16x32_bf16 v[108:111], v[168:171], v[222:225], v[108:111]
	v_mfma_f32_16x16x32_bf16 v[96:99], v[160:163], v[230:233], v[96:99]
	v_mfma_f32_16x16x32_bf16 v[92:95], v[168:171], v[230:233], v[92:95]
	v_mfma_f32_16x16x32_bf16 v[80:83], v[160:163], v[238:241], v[80:83]
	v_mfma_f32_16x16x32_bf16 v[76:79], v[168:171], v[238:241], v[76:79]
	s_setprio 0
	s_setprio 1
	v_mfma_f32_16x16x32_bf16 v[120:123], v[172:175], v[188:191], v[120:123]
	v_mfma_f32_16x16x32_bf16 v[116:119], v[180:183], v[188:191], v[116:119]
	v_mfma_f32_16x16x32_bf16 v[104:107], v[172:175], v[218:221], v[104:107]
	v_mfma_f32_16x16x32_bf16 v[100:103], v[180:183], v[218:221], v[100:103]
	v_mfma_f32_16x16x32_bf16 v[88:91], v[172:175], v[226:229], v[88:91]
	v_mfma_f32_16x16x32_bf16 v[84:87], v[180:183], v[226:229], v[84:87]
	v_mfma_f32_16x16x32_bf16 v[70:73], v[172:175], v[234:237], v[72:75]
	v_mfma_f32_16x16x32_bf16 v[66:69], v[180:183], v[234:237], v[66:69]
	v_mfma_f32_16x16x32_bf16 v[120:123], v[176:179], v[214:217], v[120:123]
	v_mfma_f32_16x16x32_bf16 v[116:119], v[184:187], v[214:217], v[116:119]
	v_mfma_f32_16x16x32_bf16 v[104:107], v[176:179], v[222:225], v[104:107]
	v_mfma_f32_16x16x32_bf16 v[100:103], v[184:187], v[222:225], v[100:103]
	v_mfma_f32_16x16x32_bf16 v[88:91], v[176:179], v[230:233], v[88:91]
	v_mfma_f32_16x16x32_bf16 v[84:87], v[184:187], v[230:233], v[84:87]
	v_mfma_f32_16x16x32_bf16 v[72:75], v[176:179], v[238:241], v[70:73]
	v_mfma_f32_16x16x32_bf16 v[68:71], v[184:187], v[238:241], v[66:69]
	s_setprio 0
	s_barrier
; #define PG8_STAGE(bufoff, gbase, voff) do { _Pragma("unroll") for (int _i = 0; _i < 2; ++_i) \
;         __builtin_amdgcn_global_load_lds((const unsigned*)((const char*)(gbase) + (voff)[_i]), (LAS unsigned*)(lds + (bufoff) + ldsw + _i * 8192), 16, 0, 0); } while (0)
; #define PG8_LDA(dst, b, h) do { _Pragma("unroll") for (int m = 0; m < 4; ++m) _Pragma("unroll") for (int k = 0; k < 2; ++k) dst[m][k] = *(const LAS bf16x8*)(lds + PG8_SA(b, h) + aoff + m * 2048 + k * 1024); } while (0)
; #define PG8_MMA(ai, bj, At, Bt) do { __builtin_amdgcn_s_setprio(1); _Pragma("unroll") for (int m = 0; m < 4; ++m) _Pragma("unroll") for (int n = 0; n < 2; ++n) _Pragma("unroll") for (int k = 0; k < 2; ++k) \
;         acc[ai][bj][m][n] = __builtin_amdgcn_mfma_f32_16x16x32_bf16(Bt[n][k], At[m][k], acc[ai][bj][m][n], 0, 0, 0); __builtin_amdgcn_s_setprio(0); } while (0)
; #define PG8_WAIT_V(n) asm volatile("s_waitcnt vmcnt(" #n ")" ::: "memory")
; #define PG8_WAIT_L(n) asm volatile("s_waitcnt lgkmcnt(" #n ")" ::: "memory")
; #define PG8_BAR __builtin_amdgcn_s_barrier()
; #define PG8_SCHED __builtin_amdgcn_sched_barrier(0)
; template <class Epi, bool SP2, class Sched>
; __device__ __forceinline__ void gemm_phase(LAS unsigned char* lds, const Gemm g, const Sched& S, const Epi& E) {
;     ...
;         for (int t = 0; t < nt; t += 2) {
;     ...
;             PG8_LDA(At, 1, 1); PG8_STAGE(PG8_SB(1, 0), b3, voffB); PG8_STAGE(PG8_SB(1, 1), b3 + hstepB, voffB); PG8_STAGE(PG8_SA(1, 0), a3, voffA);
;             PG8_WAIT_V(8); PG8_WAIT_L(0); PG8_BAR; PG8_MMA(1, 0, At, B0); PG8_MMA(1, 1, At, B1); PG8_BAR; PG8_SCHED;
	s_add_i32 s10, s19, s73
	v_lshl_add_u64 v[66:67], v[192:193], 0, s[66:67]
	s_mov_b32 m0, s10
	ds_read_b128 v[188:191], v155 offset:49152
	ds_read_b128 v[214:217], v155 offset:50176
	ds_read_b128 v[218:221], v155 offset:51200
	ds_read_b128 v[222:225], v155 offset:52224
	ds_read_b128 v[226:229], v155 offset:53248
	ds_read_b128 v[230:233], v155 offset:54272
	ds_read_b128 v[234:237], v155 offset:55296
	ds_read_b128 v[238:241], v155 offset:56320
	global_load_lds_dwordx4 v[66:67], off
	s_add_i32 m0, s10, 0x2000
	s_add_u32 s6, s6, 0x40080
	v_lshl_add_u64 v[66:67], v[248:249], 0, s[66:67]
	s_addc_u32 s7, s7, 0
	s_add_i32 s10, s20, s73
	global_load_lds_dwordx4 v[66:67], off
	s_mov_b32 m0, s10
	v_lshl_add_u64 v[66:67], s[6:7], 0, v[134:135]
	global_load_lds_dwordx4 v[66:67], off
	s_add_i32 m0, s10, 0x2000
	v_lshl_add_u64 v[66:67], s[6:7], 0, v[138:139]
	global_load_lds_dwordx4 v[66:67], off
	s_mov_b32 m0, s75
	v_lshl_add_u64 v[66:67], v[250:251], 0, s[66:67]
	global_load_lds_dwordx4 v[66:67], off
	s_mov_b32 m0, s76
	v_lshl_add_u64 v[66:67], v[252:253], 0, s[66:67]
	global_load_lds_dwordx4 v[66:67], off
	s_waitcnt vmcnt(8) lgkmcnt(0)
	s_barrier
	s_setprio 1
	v_mfma_f32_16x16x32_bf16 v[60:63], v[156:159], v[188:191], v[60:63]
	v_mfma_f32_16x16x32_bf16 v[56:59], v[164:167], v[188:191], v[56:59]
	v_mfma_f32_16x16x32_bf16 v[44:47], v[156:159], v[218:221], v[44:47]
	v_mfma_f32_16x16x32_bf16 v[40:43], v[164:167], v[218:221], v[40:43]
	v_mfma_f32_16x16x32_bf16 v[28:31], v[156:159], v[226:229], v[28:31]
	v_mfma_f32_16x16x32_bf16 v[24:27], v[164:167], v[226:229], v[24:27]
	v_mfma_f32_16x16x32_bf16 v[12:15], v[156:159], v[234:237], v[12:15]
	v_mfma_f32_16x16x32_bf16 v[8:11], v[164:167], v[234:237], v[8:11]
	v_mfma_f32_16x16x32_bf16 v[60:63], v[160:163], v[214:217], v[60:63]
	v_mfma_f32_16x16x32_bf16 v[56:59], v[168:171], v[214:217], v[56:59]
	v_mfma_f32_16x16x32_bf16 v[44:47], v[160:163], v[222:225], v[44:47]
	v_mfma_f32_16x16x32_bf16 v[40:43], v[168:171], v[222:225], v[40:43]
	v_mfma_f32_16x16x32_bf16 v[28:31], v[160:163], v[230:233], v[28:31]
	v_mfma_f32_16x16x32_bf16 v[24:27], v[168:171], v[230:233], v[24:27]
	v_mfma_f32_16x16x32_bf16 v[12:15], v[160:163], v[238:241], v[12:15]
	v_mfma_f32_16x16x32_bf16 v[8:11], v[168:171], v[238:241], v[8:11]
	s_setprio 0
	s_setprio 1
	v_mfma_f32_16x16x32_bf16 v[52:55], v[172:175], v[188:191], v[52:55]
	v_mfma_f32_16x16x32_bf16 v[48:51], v[180:183], v[188:191], v[48:51]
	v_mfma_f32_16x16x32_bf16 v[36:39], v[172:175], v[218:221], v[36:39]
	v_mfma_f32_16x16x32_bf16 v[32:35], v[180:183], v[218:221], v[32:35]
	v_mfma_f32_16x16x32_bf16 v[20:23], v[172:175], v[226:229], v[20:23]
	v_mfma_f32_16x16x32_bf16 v[16:19], v[180:183], v[226:229], v[16:19]
	v_mfma_f32_16x16x32_bf16 v[4:7], v[172:175], v[234:237], v[4:7]
	v_mfma_f32_16x16x32_bf16 v[0:3], v[180:183], v[234:237], v[0:3]
	v_mfma_f32_16x16x32_bf16 v[52:55], v[176:179], v[214:217], v[52:55]
	v_mfma_f32_16x16x32_bf16 v[48:51], v[184:187], v[214:217], v[48:51]
	v_mfma_f32_16x16x32_bf16 v[36:39], v[176:179], v[222:225], v[36:39]
	v_mfma_f32_16x16x32_bf16 v[32:35], v[184:187], v[222:225], v[32:35]
	v_mfma_f32_16x16x32_bf16 v[20:23], v[176:179], v[230:233], v[20:23]
	v_mfma_f32_16x16x32_bf16 v[16:19], v[184:187], v[230:233], v[16:19]
	v_mfma_f32_16x16x32_bf16 v[4:7], v[176:179], v[238:241], v[4:7]
	v_mfma_f32_16x16x32_bf16 v[0:3], v[184:187], v[238:241], v[0:3]
	s_setprio 0
	s_barrier
	s_add_i32 s18, s18, 2
	s_add_u32 s96, s96, 0x100
	s_addc_u32 s97, s97, 0
	s_cmp_gt_u32 s18, 13
	s_cbranch_scc1 .LBB0_676

; #define PG8_STAGE(bufoff, gbase, voff) do { _Pragma("unroll") for (int _i = 0; _i < 2; ++_i) \
;         __builtin_amdgcn_global_load_lds((const unsigned*)((const char*)(gbase) + (voff)[_i]), (LAS unsigned*)(lds + (bufoff) + ldsw + _i * 8192), 16, 0, 0); } while (0)
; #define PG8_LDA(dst, b, h) do { _Pragma("unroll") for (int m = 0; m < 4; ++m) _Pragma("unroll") for (int k = 0; k < 2; ++k) dst[m][k] = *(const LAS bf16x8*)(lds + PG8_SA(b, h) + aoff + m * 2048 + k * 1024); } while (0)
; #define PG8_LDB(dst, b, h) do { _Pragma("unroll") for (int n = 0; n < 2; ++n) _Pragma("unroll") for (int k = 0; k < 2; ++k) dst[n][k] = *(const LAS bf16x8*)(lds + PG8_SB(b, h) + boff + n * 2048 + k * 1024); } while (0)
; #define PG8_MMA(ai, bj, At, Bt) do { __builtin_amdgcn_s_setprio(1); _Pragma("unroll") for (int m = 0; m < 4; ++m) _Pragma("unroll") for (int n = 0; n < 2; ++n) _Pragma("unroll") for (int k = 0; k < 2; ++k) \
;         acc[ai][bj][m][n] = __builtin_amdgcn_mfma_f32_16x16x32_bf16(Bt[n][k], At[m][k], acc[ai][bj][m][n], 0, 0, 0); __builtin_amdgcn_s_setprio(0); } while (0)
; #define PG8_WAIT_V(n) asm volatile("s_waitcnt vmcnt(" #n ")" ::: "memory")
; #define PG8_WAIT_L(n) asm volatile("s_waitcnt lgkmcnt(" #n ")" ::: "memory")
; #define PG8_BAR __builtin_amdgcn_s_barrier()
; template <class Epi, bool SP2, class Sched>
; __device__ __forceinline__ void gemm_phase(LAS unsigned char* lds, const Gemm g, const Sched& S, const Epi& E) {
;     ...
;             const bool last = (t == nt - 2);
;             const char* a1 = cA + (size_t)(t + 1) * kstep;
;             const char* a2 = last ? nA : cA + (size_t)(t + 2) * kstep; const char* b2 = last ? nB : cB + (size_t)(t + 2) * kstep;
;             const char* a3 = a2 + kstep; const char* b3 = b2 + kstep;
;             if constexpr (Epi::MID) { if (t == (nt >> 1)) E.mid(acc, cur, wr, fr); }
;             if constexpr (SP2) {
;             PG8_LDB(B0, 0, 0); PG8_LDB(B1, 0, 1); PG8_SCHED; PG8_LDA(At, 0, 0); PG8_STAGE(PG8_SA(1, 1), a1 + hstep, voffA);
;             PG8_WAIT_V(8); PG8_WAIT_L(0); PG8_BAR; PG8_MMA(0, 0, At, B0); PG8_MMA(0, 1, At, B1); PG8_BAR; PG8_SCHED;
;             PG8_LDA(At, 0, 1); PG8_STAGE(PG8_SB(0, 0), b2, voffB); PG8_STAGE(PG8_SB(0, 1), b2 + hstepB, voffB); PG8_STAGE(PG8_SA(0, 0), a2, voffA);
;             PG8_WAIT_V(8); PG8_WAIT_L(0); PG8_BAR; PG8_MMA(1, 0, At, B0); PG8_MMA(1, 1, At, B1); PG8_BAR; PG8_SCHED;
.LBB0_715:
	s_add_u32 s6, s90, 0xfffc0080
	s_addc_u32 s7, s91, -1
	s_add_i32 s22, 0, 0x10000
	s_cmp_eq_u32 s21, 12
	s_cselect_b32 s11, s19, s7
	s_cselect_b32 s10, s33, s6
	v_add_u32_e32 v140, s22, v143
	s_cselect_b32 s7, s76, s20
	s_cselect_b32 s6, s77, s79
	s_add_i32 s24, 0, 0x14000
	ds_read_b128 v[136:139], v140
	ds_read_b128 v[146:149], v140 offset:1024
	ds_read_b128 v[150:153], v140 offset:2048
	ds_read_b128 v[154:157], v140 offset:3072
	v_add_u32_e32 v140, s24, v143
	ds_read_b128 v[158:161], v140
	ds_read_b128 v[162:165], v140 offset:1024
	ds_read_b128 v[166:169], v140 offset:2048
	ds_read_b128 v[170:173], v140 offset:3072
	v_lshl_add_u64 v[140:141], s[90:91], 0, v[134:135]
	s_add_i32 m0, s17, 0xc000
	ds_read_b128 v[174:177], v145
	ds_read_b128 v[178:181], v145 offset:1024
	ds_read_b128 v[182:185], v145 offset:2048
	ds_read_b128 v[186:189], v145 offset:3072
	ds_read_b128 v[190:193], v145 offset:4096
	ds_read_b128 v[214:217], v145 offset:5120
	ds_read_b128 v[218:221], v145 offset:6144
	ds_read_b128 v[222:225], v145 offset:7168
	global_load_lds_dwordx4 v[140:141], off
	s_add_i32 m0, s17, 0xe000
	v_lshl_add_u64 v[140:141], s[90:91], 0, v[132:133]
	global_load_lds_dwordx4 v[140:141], off
	s_waitcnt vmcnt(8) lgkmcnt(0)
	s_barrier
	s_setprio 1
	v_mfma_f32_16x16x32_bf16 v[126:129], v[136:139], v[174:177], v[126:129]
	v_mfma_f32_16x16x32_bf16 v[122:125], v[150:153], v[174:177], v[122:125]
	v_mfma_f32_16x16x32_bf16 v[110:113], v[136:139], v[182:185], v[110:113]
	v_mfma_f32_16x16x32_bf16 v[106:109], v[150:153], v[182:185], v[106:109]
	v_mfma_f32_16x16x32_bf16 v[94:97], v[136:139], v[190:193], v[94:97]
	v_mfma_f32_16x16x32_bf16 v[90:93], v[150:153], v[190:193], v[90:93]
	v_mfma_f32_16x16x32_bf16 v[78:81], v[136:139], v[218:221], v[78:81]
	v_mfma_f32_16x16x32_bf16 v[74:77], v[150:153], v[218:221], v[74:77]
	v_mfma_f32_16x16x32_bf16 v[126:129], v[146:149], v[178:181], v[126:129]
	v_mfma_f32_16x16x32_bf16 v[122:125], v[154:157], v[178:181], v[122:125]
	v_mfma_f32_16x16x32_bf16 v[110:113], v[146:149], v[186:189], v[110:113]
	v_mfma_f32_16x16x32_bf16 v[106:109], v[154:157], v[186:189], v[106:109]
	v_mfma_f32_16x16x32_bf16 v[94:97], v[146:149], v[214:217], v[94:97]
	v_mfma_f32_16x16x32_bf16 v[90:93], v[154:157], v[214:217], v[90:93]
	v_mfma_f32_16x16x32_bf16 v[78:81], v[146:149], v[222:225], v[78:81]
	v_mfma_f32_16x16x32_bf16 v[74:77], v[154:157], v[222:225], v[74:77]
	s_setprio 0
	s_setprio 1
	v_mfma_f32_16x16x32_bf16 v[118:121], v[158:161], v[174:177], v[118:121]
	v_mfma_f32_16x16x32_bf16 v[114:117], v[166:169], v[174:177], v[114:117]
	v_mfma_f32_16x16x32_bf16 v[102:105], v[158:161], v[182:185], v[102:105]
	v_mfma_f32_16x16x32_bf16 v[98:101], v[166:169], v[182:185], v[98:101]
	v_mfma_f32_16x16x32_bf16 v[86:89], v[158:161], v[190:193], v[86:89]
	v_mfma_f32_16x16x32_bf16 v[82:85], v[166:169], v[190:193], v[82:85]
	v_mfma_f32_16x16x32_bf16 v[70:73], v[158:161], v[218:221], v[70:73]
	v_mfma_f32_16x16x32_bf16 v[66:69], v[166:169], v[218:221], v[66:69]
	v_mfma_f32_16x16x32_bf16 v[118:121], v[162:165], v[178:181], v[118:121]
	v_mfma_f32_16x16x32_bf16 v[114:117], v[170:173], v[178:181], v[114:117]
	v_mfma_f32_16x16x32_bf16 v[102:105], v[162:165], v[186:189], v[102:105]
	v_mfma_f32_16x16x32_bf16 v[98:101], v[170:173], v[186:189], v[98:101]
	v_mfma_f32_16x16x32_bf16 v[86:89], v[162:165], v[214:217], v[86:89]
	v_mfma_f32_16x16x32_bf16 v[82:85], v[170:173], v[214:217], v[82:85]
	v_mfma_f32_16x16x32_bf16 v[70:73], v[162:165], v[222:225], v[70:73]
	v_mfma_f32_16x16x32_bf16 v[66:69], v[170:173], v[222:225], v[66:69]
	s_setprio 0
	s_barrier
	s_add_i32 s22, s22, s72
	v_lshl_add_u64 v[140:141], s[6:7], 0, v[64:65]
	s_mov_b32 m0, s22
	ds_read_b128 v[174:177], v145 offset:16384
	ds_read_b128 v[178:181], v145 offset:17408
	ds_read_b128 v[182:185], v145 offset:18432
	ds_read_b128 v[186:189], v145 offset:19456
	ds_read_b128 v[190:193], v145 offset:20480
	ds_read_b128 v[214:217], v145 offset:21504
	ds_read_b128 v[218:221], v145 offset:22528
	ds_read_b128 v[222:225], v145 offset:23552
	global_load_lds_dwordx4 v[140:141], off
	s_add_i32 m0, s22, 0x2000
	s_add_u32 s22, s6, 0x40000
	v_lshl_add_u64 v[226:227], s[6:7], 0, v[130:131]
	s_addc_u32 s23, s7, 0
	s_add_i32 s24, s24, s72
	global_load_lds_dwordx4 v[226:227], off
	v_lshl_add_u64 v[228:229], s[22:23], 0, v[64:65]
	s_mov_b32 m0, s24
	v_lshl_add_u64 v[230:231], s[10:11], 0, v[130:131]
	global_load_lds_dwordx4 v[228:229], off
	s_add_i32 m0, s24, 0x2000
	v_lshl_add_u64 v[228:229], s[22:23], 0, v[130:131]
	global_load_lds_dwordx4 v[228:229], off
	s_mov_b32 m0, s17
	v_lshl_add_u64 v[228:229], s[10:11], 0, v[64:65]
	global_load_lds_dwordx4 v[228:229], off
	s_mov_b32 m0, s73
	s_nop 0
	global_load_lds_dwordx4 v[230:231], off
	s_waitcnt vmcnt(8) lgkmcnt(0)
	s_barrier
; #define PG8_STAGE(bufoff, gbase, voff) do { _Pragma("unroll") for (int _i = 0; _i < 2; ++_i) \
;         __builtin_amdgcn_global_load_lds((const unsigned*)((const char*)(gbase) + (voff)[_i]), (LAS unsigned*)(lds + (bufoff) + ldsw + _i * 8192), 16, 0, 0); } while (0)
; #define PG8_LDA(dst, b, h) do { _Pragma("unroll") for (int m = 0; m < 4; ++m) _Pragma("unroll") for (int k = 0; k < 2; ++k) dst[m][k] = *(const LAS bf16x8*)(lds + PG8_SA(b, h) + aoff + m * 2048 + k * 1024); } while (0)
; #define PG8_LDB(dst, b, h) do { _Pragma("unroll") for (int n = 0; n < 2; ++n) _Pragma("unroll") for (int k = 0; k < 2; ++k) dst[n][k] = *(const LAS bf16x8*)(lds + PG8_SB(b, h) + boff + n * 2048 + k * 1024); } while (0)
; #define PG8_MMA(ai, bj, At, Bt) do { __builtin_amdgcn_s_setprio(1); _Pragma("unroll") for (int m = 0; m < 4; ++m) _Pragma("unroll") for (int n = 0; n < 2; ++n) _Pragma("unroll") for (int k = 0; k < 2; ++k) \
;         acc[ai][bj][m][n] = __builtin_amdgcn_mfma_f32_16x16x32_bf16(Bt[n][k], At[m][k], acc[ai][bj][m][n], 0, 0, 0); __builtin_amdgcn_s_setprio(0); } while (0)
; #define PG8_WAIT_V(n) asm volatile("s_waitcnt vmcnt(" #n ")" ::: "memory")
; #define PG8_WAIT_L(n) asm volatile("s_waitcnt lgkmcnt(" #n ")" ::: "memory")
; #define PG8_BAR __builtin_amdgcn_s_barrier()
; #define PG8_SCHED __builtin_amdgcn_sched_barrier(0)
; template <class Epi, bool SP2, class Sched>
; __device__ __forceinline__ void gemm_phase(LAS unsigned char* lds, const Gemm g, const Sched& S, const Epi& E) {
;     ...
;             PG8_WAIT_V(8); PG8_WAIT_L(0); PG8_BAR; PG8_MMA(1, 0, At, B0); PG8_MMA(1, 1, At, B1); PG8_BAR; PG8_SCHED;
;             PG8_LDB(B0, 1, 0); PG8_LDB(B1, 1, 1); PG8_SCHED; PG8_LDA(At, 1, 0); PG8_STAGE(PG8_SA(0, 1), a2 + hstep, voffA);
;             PG8_WAIT_V(8); PG8_WAIT_L(0); PG8_BAR; PG8_MMA(0, 0, At, B0); PG8_MMA(0, 1, At, B1); PG8_BAR; PG8_SCHED;
	s_setprio 1
	v_mfma_f32_16x16x32_bf16 v[60:63], v[136:139], v[174:177], v[60:63]
	v_mfma_f32_16x16x32_bf16 v[56:59], v[150:153], v[174:177], v[56:59]
	v_mfma_f32_16x16x32_bf16 v[44:47], v[136:139], v[182:185], v[44:47]
	v_mfma_f32_16x16x32_bf16 v[40:43], v[150:153], v[182:185], v[40:43]
	v_mfma_f32_16x16x32_bf16 v[28:31], v[136:139], v[190:193], v[28:31]
	v_mfma_f32_16x16x32_bf16 v[24:27], v[150:153], v[190:193], v[24:27]
	v_mfma_f32_16x16x32_bf16 v[12:15], v[136:139], v[218:221], v[12:15]
	v_mfma_f32_16x16x32_bf16 v[8:11], v[150:153], v[218:221], v[8:11]
	v_mfma_f32_16x16x32_bf16 v[60:63], v[146:149], v[178:181], v[60:63]
	v_mfma_f32_16x16x32_bf16 v[56:59], v[154:157], v[178:181], v[56:59]
	v_mfma_f32_16x16x32_bf16 v[44:47], v[146:149], v[186:189], v[44:47]
	v_mfma_f32_16x16x32_bf16 v[40:43], v[154:157], v[186:189], v[40:43]
	v_mfma_f32_16x16x32_bf16 v[28:31], v[146:149], v[214:217], v[28:31]
	v_mfma_f32_16x16x32_bf16 v[24:27], v[154:157], v[214:217], v[24:27]
	v_mfma_f32_16x16x32_bf16 v[12:15], v[146:149], v[222:225], v[12:15]
	v_mfma_f32_16x16x32_bf16 v[8:11], v[154:157], v[222:225], v[8:11]
	s_setprio 0
	s_setprio 1
	v_mfma_f32_16x16x32_bf16 v[52:55], v[158:161], v[174:177], v[52:55]
	v_mfma_f32_16x16x32_bf16 v[48:51], v[166:169], v[174:177], v[48:51]
	v_mfma_f32_16x16x32_bf16 v[36:39], v[158:161], v[182:185], v[36:39]
	v_mfma_f32_16x16x32_bf16 v[32:35], v[166:169], v[182:185], v[32:35]
	v_mfma_f32_16x16x32_bf16 v[20:23], v[158:161], v[190:193], v[20:23]
	v_mfma_f32_16x16x32_bf16 v[16:19], v[166:169], v[190:193], v[16:19]
	v_mfma_f32_16x16x32_bf16 v[4:7], v[158:161], v[218:221], v[4:7]
	v_mfma_f32_16x16x32_bf16 v[0:3], v[166:169], v[218:221], v[0:3]
	v_mfma_f32_16x16x32_bf16 v[52:55], v[162:165], v[178:181], v[52:55]
	v_mfma_f32_16x16x32_bf16 v[48:51], v[170:173], v[178:181], v[48:51]
	v_mfma_f32_16x16x32_bf16 v[36:39], v[162:165], v[186:189], v[36:39]
	v_mfma_f32_16x16x32_bf16 v[32:35], v[170:173], v[186:189], v[32:35]
	v_mfma_f32_16x16x32_bf16 v[20:23], v[162:165], v[214:217], v[20:23]
	v_mfma_f32_16x16x32_bf16 v[16:19], v[170:173], v[214:217], v[16:19]
	v_mfma_f32_16x16x32_bf16 v[4:7], v[162:165], v[222:225], v[4:7]
	v_mfma_f32_16x16x32_bf16 v[0:3], v[170:173], v[222:225], v[0:3]
	s_setprio 0
	s_barrier
	s_add_i32 s22, 0, 0x18000
	s_add_i32 s23, 0, 0x1c000
	v_add_u32_e32 v154, s22, v143
	v_add_u32_e32 v170, s23, v143
	ds_read_b128 v[136:139], v154
	ds_read_b128 v[146:149], v154 offset:1024
	ds_read_b128 v[150:153], v154 offset:2048
	ds_read_b128 v[154:157], v154 offset:3072
	ds_read_b128 v[158:161], v170
	ds_read_b128 v[162:165], v170 offset:1024
	ds_read_b128 v[166:169], v170 offset:2048
	ds_read_b128 v[170:173], v170 offset:3072
	s_add_u32 s10, s10, 0x40000
	s_addc_u32 s11, s11, 0
	s_mov_b32 m0, s74
	v_lshl_add_u64 v[232:233], s[10:11], 0, v[64:65]
	ds_read_b128 v[174:177], v145 offset:32768
	ds_read_b128 v[178:181], v145 offset:33792
	ds_read_b128 v[182:185], v145 offset:34816
	ds_read_b128 v[186:189], v145 offset:35840
	ds_read_b128 v[190:193], v145 offset:36864
	ds_read_b128 v[214:217], v145 offset:37888
	ds_read_b128 v[218:221], v145 offset:38912
	ds_read_b128 v[222:225], v145 offset:39936
	global_load_lds_dwordx4 v[232:233], off
	s_mov_b32 m0, s75
	v_lshl_add_u64 v[232:233], s[10:11], 0, v[130:131]
	global_load_lds_dwordx4 v[232:233], off
	s_waitcnt vmcnt(8) lgkmcnt(0)
	s_barrier
	s_setprio 1
	v_mfma_f32_16x16x32_bf16 v[126:129], v[136:139], v[174:177], v[126:129]
	v_mfma_f32_16x16x32_bf16 v[122:125], v[150:153], v[174:177], v[122:125]
	v_mfma_f32_16x16x32_bf16 v[110:113], v[136:139], v[182:185], v[110:113]
	v_mfma_f32_16x16x32_bf16 v[106:109], v[150:153], v[182:185], v[106:109]
	v_mfma_f32_16x16x32_bf16 v[94:97], v[136:139], v[190:193], v[94:97]
	v_mfma_f32_16x16x32_bf16 v[90:93], v[150:153], v[190:193], v[90:93]
	v_mfma_f32_16x16x32_bf16 v[78:81], v[136:139], v[218:221], v[78:81]
	v_mfma_f32_16x16x32_bf16 v[74:77], v[150:153], v[218:221], v[74:77]
	v_mfma_f32_16x16x32_bf16 v[126:129], v[146:149], v[178:181], v[126:129]
	v_mfma_f32_16x16x32_bf16 v[122:125], v[154:157], v[178:181], v[122:125]
	v_mfma_f32_16x16x32_bf16 v[110:113], v[146:149], v[186:189], v[110:113]
	v_mfma_f32_16x16x32_bf16 v[106:109], v[154:157], v[186:189], v[106:109]
	v_mfma_f32_16x16x32_bf16 v[94:97], v[146:149], v[214:217], v[94:97]
	v_mfma_f32_16x16x32_bf16 v[90:93], v[154:157], v[214:217], v[90:93]
	v_mfma_f32_16x16x32_bf16 v[78:81], v[146:149], v[222:225], v[78:81]
	v_mfma_f32_16x16x32_bf16 v[74:77], v[154:157], v[222:225], v[74:77]
	s_setprio 0
	s_setprio 1
	v_mfma_f32_16x16x32_bf16 v[118:121], v[158:161], v[174:177], v[118:121]
	v_mfma_f32_16x16x32_bf16 v[114:117], v[166:169], v[174:177], v[114:117]
	v_mfma_f32_16x16x32_bf16 v[102:105], v[158:161], v[182:185], v[102:105]
	v_mfma_f32_16x16x32_bf16 v[98:101], v[166:169], v[182:185], v[98:101]
	v_mfma_f32_16x16x32_bf16 v[86:89], v[158:161], v[190:193], v[86:89]
	v_mfma_f32_16x16x32_bf16 v[82:85], v[166:169], v[190:193], v[82:85]
	v_mfma_f32_16x16x32_bf16 v[70:73], v[158:161], v[218:221], v[70:73]
	v_mfma_f32_16x16x32_bf16 v[66:69], v[166:169], v[218:221], v[66:69]
	v_mfma_f32_16x16x32_bf16 v[118:121], v[162:165], v[178:181], v[118:121]
	v_mfma_f32_16x16x32_bf16 v[114:117], v[170:173], v[178:181], v[114:117]
	v_mfma_f32_16x16x32_bf16 v[102:105], v[162:165], v[186:189], v[102:105]
	v_mfma_f32_16x16x32_bf16 v[98:101], v[170:173], v[186:189], v[98:101]
	v_mfma_f32_16x16x32_bf16 v[86:89], v[162:165], v[214:217], v[86:89]
	v_mfma_f32_16x16x32_bf16 v[82:85], v[170:173], v[214:217], v[82:85]
	v_mfma_f32_16x16x32_bf16 v[70:73], v[162:165], v[222:225], v[70:73]
	v_mfma_f32_16x16x32_bf16 v[66:69], v[170:173], v[222:225], v[66:69]
	s_setprio 0
	s_barrier
; #define PG8_STAGE(bufoff, gbase, voff) do { _Pragma("unroll") for (int _i = 0; _i < 2; ++_i) \
;         __builtin_amdgcn_global_load_lds((const unsigned*)((const char*)(gbase) + (voff)[_i]), (LAS unsigned*)(lds + (bufoff) + ldsw + _i * 8192), 16, 0, 0); } while (0)
; #define PG8_LDA(dst, b, h) do { _Pragma("unroll") for (int m = 0; m < 4; ++m) _Pragma("unroll") for (int k = 0; k < 2; ++k) dst[m][k] = *(const LAS bf16x8*)(lds + PG8_SA(b, h) + aoff + m * 2048 + k * 1024); } while (0)
; #define PG8_MMA(ai, bj, At, Bt) do { __builtin_amdgcn_s_setprio(1); _Pragma("unroll") for (int m = 0; m < 4; ++m) _Pragma("unroll") for (int n = 0; n < 2; ++n) _Pragma("unroll") for (int k = 0; k < 2; ++k) \
;         acc[ai][bj][m][n] = __builtin_amdgcn_mfma_f32_16x16x32_bf16(Bt[n][k], At[m][k], acc[ai][bj][m][n], 0, 0, 0); __builtin_amdgcn_s_setprio(0); } while (0)
; #define PG8_WAIT_V(n) asm volatile("s_waitcnt vmcnt(" #n ")" ::: "memory")
; #define PG8_WAIT_L(n) asm volatile("s_waitcnt lgkmcnt(" #n ")" ::: "memory")
; #define PG8_BAR __builtin_amdgcn_s_barrier()
; #define PG8_SCHED __builtin_amdgcn_sched_barrier(0)
; template <class Epi, bool SP2, class Sched>
; __device__ __forceinline__ void gemm_phase(LAS unsigned char* lds, const Gemm g, const Sched& S, const Epi& E) {
;     ...
;             PG8_LDA(At, 1, 1); PG8_STAGE(PG8_SB(1, 0), b3, voffB); PG8_STAGE(PG8_SB(1, 1), b3 + hstepB, voffB); PG8_STAGE(PG8_SA(1, 0), a3, voffA);
;             PG8_WAIT_V(8); PG8_WAIT_L(0); PG8_BAR; PG8_MMA(1, 0, At, B0); PG8_MMA(1, 1, At, B1); PG8_BAR; PG8_SCHED;
;     ...
;         if (wr == 0) PG8_BAR;
	s_add_i32 s10, s22, s72
	v_lshl_add_u64 v[140:141], v[140:141], 0, s[66:67]
	s_mov_b32 m0, s10
	ds_read_b128 v[174:177], v145 offset:49152
	ds_read_b128 v[178:181], v145 offset:50176
	ds_read_b128 v[182:185], v145 offset:51200
	ds_read_b128 v[186:189], v145 offset:52224
	ds_read_b128 v[190:193], v145 offset:53248
	ds_read_b128 v[214:217], v145 offset:54272
	ds_read_b128 v[218:221], v145 offset:55296
	ds_read_b128 v[222:225], v145 offset:56320
	global_load_lds_dwordx4 v[140:141], off
	s_add_i32 m0, s10, 0x2000
	s_add_u32 s6, s6, 0x40080
	v_lshl_add_u64 v[140:141], v[226:227], 0, s[66:67]
	s_addc_u32 s7, s7, 0
	s_add_i32 s10, s23, s72
	global_load_lds_dwordx4 v[140:141], off
	s_mov_b32 m0, s10
	v_lshl_add_u64 v[140:141], s[6:7], 0, v[64:65]
	global_load_lds_dwordx4 v[140:141], off
	s_add_i32 m0, s10, 0x2000
	v_lshl_add_u64 v[140:141], s[6:7], 0, v[130:131]
	global_load_lds_dwordx4 v[140:141], off
	s_mov_b32 m0, s12
	v_lshl_add_u64 v[140:141], v[228:229], 0, s[66:67]
	global_load_lds_dwordx4 v[140:141], off
	s_mov_b32 m0, s13
	v_lshl_add_u64 v[140:141], v[230:231], 0, s[66:67]
	global_load_lds_dwordx4 v[140:141], off
	s_waitcnt vmcnt(8) lgkmcnt(0)
	s_barrier
	s_setprio 1
	v_mfma_f32_16x16x32_bf16 v[60:63], v[136:139], v[174:177], v[60:63]
	v_mfma_f32_16x16x32_bf16 v[56:59], v[150:153], v[174:177], v[56:59]
	v_mfma_f32_16x16x32_bf16 v[44:47], v[136:139], v[182:185], v[44:47]
	v_mfma_f32_16x16x32_bf16 v[40:43], v[150:153], v[182:185], v[40:43]
	v_mfma_f32_16x16x32_bf16 v[28:31], v[136:139], v[190:193], v[28:31]
	v_mfma_f32_16x16x32_bf16 v[24:27], v[150:153], v[190:193], v[24:27]
	v_mfma_f32_16x16x32_bf16 v[12:15], v[136:139], v[218:221], v[12:15]
	v_mfma_f32_16x16x32_bf16 v[8:11], v[150:153], v[218:221], v[8:11]
	v_mfma_f32_16x16x32_bf16 v[60:63], v[146:149], v[178:181], v[60:63]
	v_mfma_f32_16x16x32_bf16 v[56:59], v[154:157], v[178:181], v[56:59]
	v_mfma_f32_16x16x32_bf16 v[44:47], v[146:149], v[186:189], v[44:47]
	v_mfma_f32_16x16x32_bf16 v[40:43], v[154:157], v[186:189], v[40:43]
	v_mfma_f32_16x16x32_bf16 v[28:31], v[146:149], v[214:217], v[28:31]
	v_mfma_f32_16x16x32_bf16 v[24:27], v[154:157], v[214:217], v[24:27]
	v_mfma_f32_16x16x32_bf16 v[12:15], v[146:149], v[222:225], v[12:15]
	v_mfma_f32_16x16x32_bf16 v[8:11], v[154:157], v[222:225], v[8:11]
	s_setprio 0
	s_setprio 1
	v_mfma_f32_16x16x32_bf16 v[52:55], v[158:161], v[174:177], v[52:55]
	v_mfma_f32_16x16x32_bf16 v[48:51], v[166:169], v[174:177], v[48:51]
	v_mfma_f32_16x16x32_bf16 v[36:39], v[158:161], v[182:185], v[36:39]
	v_mfma_f32_16x16x32_bf16 v[32:35], v[166:169], v[182:185], v[32:35]
	v_mfma_f32_16x16x32_bf16 v[20:23], v[158:161], v[190:193], v[20:23]
	v_mfma_f32_16x16x32_bf16 v[16:19], v[166:169], v[190:193], v[16:19]
	v_mfma_f32_16x16x32_bf16 v[4:7], v[158:161], v[218:221], v[4:7]
	v_mfma_f32_16x16x32_bf16 v[0:3], v[166:169], v[218:221], v[0:3]
	v_mfma_f32_16x16x32_bf16 v[52:55], v[162:165], v[178:181], v[52:55]
	v_mfma_f32_16x16x32_bf16 v[48:51], v[170:173], v[178:181], v[48:51]
	v_mfma_f32_16x16x32_bf16 v[36:39], v[162:165], v[186:189], v[36:39]
	v_mfma_f32_16x16x32_bf16 v[32:35], v[170:173], v[186:189], v[32:35]
	v_mfma_f32_16x16x32_bf16 v[20:23], v[162:165], v[214:217], v[20:23]
	v_mfma_f32_16x16x32_bf16 v[16:19], v[170:173], v[214:217], v[16:19]
	v_mfma_f32_16x16x32_bf16 v[4:7], v[162:165], v[222:225], v[4:7]
	v_mfma_f32_16x16x32_bf16 v[0:3], v[170:173], v[222:225], v[0:3]
	s_setprio 0
	s_barrier
	s_add_i32 s21, s21, 2
	s_add_u32 s79, s79, 0x100
	s_addc_u32 s20, s20, 0
	s_add_u32 s90, s90, 0x100
	s_addc_u32 s91, s91, 0
	s_cmp_gt_u32 s21, 13
	s_cbranch_scc0 .LBB0_715
	s_and_b64 vcc, exec, s[60:61]
	s_cbranch_vccz .LBB0_718
	s_barrier

; #define PG8_STAGE(bufoff, gbase, voff) do { _Pragma("unroll") for (int _i = 0; _i < 2; ++_i) \
;         __builtin_amdgcn_global_load_lds((const unsigned*)((const char*)(gbase) + (voff)[_i]), (LAS unsigned*)(lds + (bufoff) + ldsw + _i * 8192), 16, 0, 0); } while (0)
; #define PG8_LDA(dst, b, h) do { _Pragma("unroll") for (int m = 0; m < 4; ++m) _Pragma("unroll") for (int k = 0; k < 2; ++k) dst[m][k] = *(const LAS bf16x8*)(lds + PG8_SA(b, h) + aoff + m * 2048 + k * 1024); } while (0)
; #define PG8_LDB(dst, b, h) do { _Pragma("unroll") for (int n = 0; n < 2; ++n) _Pragma("unroll") for (int k = 0; k < 2; ++k) dst[n][k] = *(const LAS bf16x8*)(lds + PG8_SB(b, h) + boff + n * 2048 + k * 1024); } while (0)
; #define PG8_MMA(ai, bj, At, Bt) do { __builtin_amdgcn_s_setprio(1); _Pragma("unroll") for (int m = 0; m < 4; ++m) _Pragma("unroll") for (int n = 0; n < 2; ++n) _Pragma("unroll") for (int k = 0; k < 2; ++k) \
;         acc[ai][bj][m][n] = __builtin_amdgcn_mfma_f32_16x16x32_bf16(Bt[n][k], At[m][k], acc[ai][bj][m][n], 0, 0, 0); __builtin_amdgcn_s_setprio(0); } while (0)
; #define PG8_WAIT_V(n) asm volatile("s_waitcnt vmcnt(" #n ")" ::: "memory")
; #define PG8_WAIT_L(n) asm volatile("s_waitcnt lgkmcnt(" #n ")" ::: "memory")
; #define PG8_BAR __builtin_amdgcn_s_barrier()
; template <class Epi, bool SP2, class Sched>
; __device__ __forceinline__ void gemm_phase(LAS unsigned char* lds, const Gemm g, const Sched& S, const Epi& E) {
;     ...
;             const bool last = (t == nt - 2);
;             const char* a1 = cA + (size_t)(t + 1) * kstep;
;             const char* a2 = last ? nA : cA + (size_t)(t + 2) * kstep; const char* b2 = last ? nB : cB + (size_t)(t + 2) * kstep;
;             const char* a3 = a2 + kstep; const char* b3 = b2 + kstep;
;             if constexpr (Epi::MID) { if (t == (nt >> 1)) E.mid(acc, cur, wr, fr); }
;             if constexpr (SP2) {
;             PG8_LDB(B0, 0, 0); PG8_LDB(B1, 0, 1); PG8_SCHED; PG8_LDA(At, 0, 0); PG8_STAGE(PG8_SA(1, 1), a1 + hstep, voffA);
;             PG8_WAIT_V(8); PG8_WAIT_L(0); PG8_BAR; PG8_MMA(0, 0, At, B0); PG8_MMA(0, 1, At, B1); PG8_BAR; PG8_SCHED;
;             PG8_LDA(At, 0, 1); PG8_STAGE(PG8_SB(0, 0), b2, voffB); PG8_STAGE(PG8_SB(0, 1), b2 + hstepB, voffB); PG8_STAGE(PG8_SA(0, 0), a2, voffA);
;             PG8_WAIT_V(8); PG8_WAIT_L(0); PG8_BAR; PG8_MMA(1, 0, At, B0); PG8_MMA(1, 1, At, B1); PG8_BAR; PG8_SCHED;
.LBB0_783:
	s_add_u32 s6, s88, 0xfffc0080
	s_addc_u32 s7, s89, -1
	s_add_i32 s22, 0, 0x10000
	s_cmp_eq_u32 s21, 12
	s_cselect_b32 s11, s61, s7
	s_cselect_b32 s10, s74, s6
	s_cselect_b32 s7, s59, s20
	s_cselect_b32 s6, s75, s76
	s_add_i32 s24, 0, 0x14000
	v_add_u32_e32 v156, s22, v145
	v_add_u32_e32 v172, s24, v145
	ds_read_b128 v[140:143], v156
	ds_read_b128 v[148:151], v156 offset:1024
	ds_read_b128 v[152:155], v156 offset:2048
	ds_read_b128 v[156:159], v156 offset:3072
	ds_read_b128 v[160:163], v172
	ds_read_b128 v[164:167], v172 offset:1024
	ds_read_b128 v[168:171], v172 offset:2048
	ds_read_b128 v[172:175], v172 offset:3072
	v_lshl_add_u64 v[192:193], s[88:89], 0, v[138:139]
	s_add_i32 m0, s12, 0xc000
	ds_read_b128 v[176:179], v147
	ds_read_b128 v[180:183], v147 offset:1024
	ds_read_b128 v[184:187], v147 offset:2048
	ds_read_b128 v[188:191], v147 offset:3072
	ds_read_b128 v[214:217], v147 offset:4096
	ds_read_b128 v[218:221], v147 offset:5120
	ds_read_b128 v[222:225], v147 offset:6144
	ds_read_b128 v[226:229], v147 offset:7168
	global_load_lds_dwordx4 v[192:193], off
	s_add_i32 m0, s12, 0xe000
	v_lshl_add_u64 v[192:193], s[88:89], 0, v[136:137]
	global_load_lds_dwordx4 v[192:193], off
	s_waitcnt vmcnt(8) lgkmcnt(0)
	s_barrier
	s_setprio 1
	v_mfma_f32_16x16x32_bf16 v[126:129], v[140:143], v[176:179], v[126:129]
	v_mfma_f32_16x16x32_bf16 v[122:125], v[152:155], v[176:179], v[122:125]
	v_mfma_f32_16x16x32_bf16 v[110:113], v[140:143], v[184:187], v[110:113]
	v_mfma_f32_16x16x32_bf16 v[106:109], v[152:155], v[184:187], v[106:109]
	v_mfma_f32_16x16x32_bf16 v[94:97], v[140:143], v[214:217], v[94:97]
	v_mfma_f32_16x16x32_bf16 v[90:93], v[152:155], v[214:217], v[90:93]
	v_mfma_f32_16x16x32_bf16 v[78:81], v[140:143], v[222:225], v[78:81]
	v_mfma_f32_16x16x32_bf16 v[74:77], v[152:155], v[222:225], v[74:77]
	v_mfma_f32_16x16x32_bf16 v[126:129], v[148:151], v[180:183], v[126:129]
	v_mfma_f32_16x16x32_bf16 v[122:125], v[156:159], v[180:183], v[122:125]
	v_mfma_f32_16x16x32_bf16 v[110:113], v[148:151], v[188:191], v[110:113]
	v_mfma_f32_16x16x32_bf16 v[106:109], v[156:159], v[188:191], v[106:109]
	v_mfma_f32_16x16x32_bf16 v[94:97], v[148:151], v[218:221], v[94:97]
	v_mfma_f32_16x16x32_bf16 v[90:93], v[156:159], v[218:221], v[90:93]
	v_mfma_f32_16x16x32_bf16 v[78:81], v[148:151], v[226:229], v[78:81]
	v_mfma_f32_16x16x32_bf16 v[74:77], v[156:159], v[226:229], v[74:77]
	s_setprio 0
	s_setprio 1
	v_mfma_f32_16x16x32_bf16 v[118:121], v[160:163], v[176:179], v[118:121]
	v_mfma_f32_16x16x32_bf16 v[114:117], v[168:171], v[176:179], v[114:117]
	v_mfma_f32_16x16x32_bf16 v[102:105], v[160:163], v[184:187], v[102:105]
	v_mfma_f32_16x16x32_bf16 v[98:101], v[168:171], v[184:187], v[98:101]
	v_mfma_f32_16x16x32_bf16 v[86:89], v[160:163], v[214:217], v[86:89]
	v_mfma_f32_16x16x32_bf16 v[82:85], v[168:171], v[214:217], v[82:85]
	v_mfma_f32_16x16x32_bf16 v[70:73], v[160:163], v[222:225], v[70:73]
	v_mfma_f32_16x16x32_bf16 v[66:69], v[168:171], v[222:225], v[66:69]
	v_mfma_f32_16x16x32_bf16 v[118:121], v[164:167], v[180:183], v[118:121]
	v_mfma_f32_16x16x32_bf16 v[114:117], v[172:175], v[180:183], v[114:117]
	v_mfma_f32_16x16x32_bf16 v[102:105], v[164:167], v[188:191], v[102:105]
	v_mfma_f32_16x16x32_bf16 v[98:101], v[172:175], v[188:191], v[98:101]
	v_mfma_f32_16x16x32_bf16 v[86:89], v[164:167], v[218:221], v[86:89]
	v_mfma_f32_16x16x32_bf16 v[82:85], v[172:175], v[218:221], v[82:85]
	v_mfma_f32_16x16x32_bf16 v[70:73], v[164:167], v[226:229], v[70:73]
	v_mfma_f32_16x16x32_bf16 v[66:69], v[172:175], v[226:229], v[66:69]
	s_setprio 0
	s_barrier
	s_add_i32 s22, s22, s69
	v_lshl_add_u64 v[192:193], s[6:7], 0, v[64:65]
	s_mov_b32 m0, s22
	ds_read_b128 v[176:179], v147 offset:16384
	ds_read_b128 v[180:183], v147 offset:17408
	ds_read_b128 v[184:187], v147 offset:18432
	ds_read_b128 v[188:191], v147 offset:19456
	ds_read_b128 v[214:217], v147 offset:20480
	ds_read_b128 v[218:221], v147 offset:21504
	ds_read_b128 v[222:225], v147 offset:22528
	ds_read_b128 v[226:229], v147 offset:23552
	global_load_lds_dwordx4 v[192:193], off
	s_add_i32 m0, s22, 0x2000
	s_add_u32 s22, s6, 0x40000
	v_lshl_add_u64 v[230:231], s[6:7], 0, v[130:131]
	s_addc_u32 s23, s7, 0
	s_add_i32 s24, s24, s69
	global_load_lds_dwordx4 v[230:231], off
	v_lshl_add_u64 v[232:233], s[22:23], 0, v[64:65]
	s_mov_b32 m0, s24
	v_lshl_add_u64 v[234:235], s[10:11], 0, v[132:133]
	global_load_lds_dwordx4 v[232:233], off
	s_add_i32 m0, s24, 0x2000
	v_lshl_add_u64 v[232:233], s[22:23], 0, v[130:131]
	global_load_lds_dwordx4 v[232:233], off
	s_mov_b32 m0, s12
	v_lshl_add_u64 v[232:233], s[10:11], 0, v[134:135]
	global_load_lds_dwordx4 v[232:233], off
	s_mov_b32 m0, s13
	s_nop 0
	global_load_lds_dwordx4 v[234:235], off
	s_waitcnt vmcnt(8) lgkmcnt(0)
	s_barrier
; #define PG8_STAGE(bufoff, gbase, voff) do { _Pragma("unroll") for (int _i = 0; _i < 2; ++_i) \
;         __builtin_amdgcn_global_load_lds((const unsigned*)((const char*)(gbase) + (voff)[_i]), (LAS unsigned*)(lds + (bufoff) + ldsw + _i * 8192), 16, 0, 0); } while (0)
; #define PG8_LDA(dst, b, h) do { _Pragma("unroll") for (int m = 0; m < 4; ++m) _Pragma("unroll") for (int k = 0; k < 2; ++k) dst[m][k] = *(const LAS bf16x8*)(lds + PG8_SA(b, h) + aoff + m * 2048 + k * 1024); } while (0)
; #define PG8_LDB(dst, b, h) do { _Pragma("unroll") for (int n = 0; n < 2; ++n) _Pragma("unroll") for (int k = 0; k < 2; ++k) dst[n][k] = *(const LAS bf16x8*)(lds + PG8_SB(b, h) + boff + n * 2048 + k * 1024); } while (0)
; #define PG8_MMA(ai, bj, At, Bt) do { __builtin_amdgcn_s_setprio(1); _Pragma("unroll") for (int m = 0; m < 4; ++m) _Pragma("unroll") for (int n = 0; n < 2; ++n) _Pragma("unroll") for (int k = 0; k < 2; ++k) \
;         acc[ai][bj][m][n] = __builtin_amdgcn_mfma_f32_16x16x32_bf16(Bt[n][k], At[m][k], acc[ai][bj][m][n], 0, 0, 0); __builtin_amdgcn_s_setprio(0); } while (0)
; #define PG8_WAIT_V(n) asm volatile("s_waitcnt vmcnt(" #n ")" ::: "memory")
; #define PG8_WAIT_L(n) asm volatile("s_waitcnt lgkmcnt(" #n ")" ::: "memory")
; #define PG8_BAR __builtin_amdgcn_s_barrier()
; #define PG8_SCHED __builtin_amdgcn_sched_barrier(0)
; template <class Epi, bool SP2, class Sched>
; __device__ __forceinline__ void gemm_phase(LAS unsigned char* lds, const Gemm g, const Sched& S, const Epi& E) {
;     ...
;             PG8_WAIT_V(8); PG8_WAIT_L(0); PG8_BAR; PG8_MMA(1, 0, At, B0); PG8_MMA(1, 1, At, B1); PG8_BAR; PG8_SCHED;
;             PG8_LDB(B0, 1, 0); PG8_LDB(B1, 1, 1); PG8_SCHED; PG8_LDA(At, 1, 0); PG8_STAGE(PG8_SA(0, 1), a2 + hstep, voffA);
;             PG8_WAIT_V(8); PG8_WAIT_L(0); PG8_BAR; PG8_MMA(0, 0, At, B0); PG8_MMA(0, 1, At, B1); PG8_BAR; PG8_SCHED;
	s_setprio 1
	v_mfma_f32_16x16x32_bf16 v[60:63], v[140:143], v[176:179], v[60:63]
	v_mfma_f32_16x16x32_bf16 v[56:59], v[152:155], v[176:179], v[56:59]
	v_mfma_f32_16x16x32_bf16 v[44:47], v[140:143], v[184:187], v[44:47]
	v_mfma_f32_16x16x32_bf16 v[40:43], v[152:155], v[184:187], v[40:43]
	v_mfma_f32_16x16x32_bf16 v[28:31], v[140:143], v[214:217], v[28:31]
	v_mfma_f32_16x16x32_bf16 v[24:27], v[152:155], v[214:217], v[24:27]
	v_mfma_f32_16x16x32_bf16 v[12:15], v[140:143], v[222:225], v[12:15]
	v_mfma_f32_16x16x32_bf16 v[8:11], v[152:155], v[222:225], v[8:11]
	v_mfma_f32_16x16x32_bf16 v[60:63], v[148:151], v[180:183], v[60:63]
	v_mfma_f32_16x16x32_bf16 v[56:59], v[156:159], v[180:183], v[56:59]
	v_mfma_f32_16x16x32_bf16 v[44:47], v[148:151], v[188:191], v[44:47]
	v_mfma_f32_16x16x32_bf16 v[40:43], v[156:159], v[188:191], v[40:43]
	v_mfma_f32_16x16x32_bf16 v[28:31], v[148:151], v[218:221], v[28:31]
	v_mfma_f32_16x16x32_bf16 v[24:27], v[156:159], v[218:221], v[24:27]
	v_mfma_f32_16x16x32_bf16 v[12:15], v[148:151], v[226:229], v[12:15]
	v_mfma_f32_16x16x32_bf16 v[8:11], v[156:159], v[226:229], v[8:11]
	s_setprio 0
	s_setprio 1
	v_mfma_f32_16x16x32_bf16 v[52:55], v[160:163], v[176:179], v[52:55]
	v_mfma_f32_16x16x32_bf16 v[48:51], v[168:171], v[176:179], v[48:51]
	v_mfma_f32_16x16x32_bf16 v[36:39], v[160:163], v[184:187], v[36:39]
	v_mfma_f32_16x16x32_bf16 v[32:35], v[168:171], v[184:187], v[32:35]
	v_mfma_f32_16x16x32_bf16 v[20:23], v[160:163], v[214:217], v[20:23]
	v_mfma_f32_16x16x32_bf16 v[16:19], v[168:171], v[214:217], v[16:19]
	v_mfma_f32_16x16x32_bf16 v[4:7], v[160:163], v[222:225], v[4:7]
	v_mfma_f32_16x16x32_bf16 v[0:3], v[168:171], v[222:225], v[0:3]
	v_mfma_f32_16x16x32_bf16 v[52:55], v[164:167], v[180:183], v[52:55]
	v_mfma_f32_16x16x32_bf16 v[48:51], v[172:175], v[180:183], v[48:51]
	v_mfma_f32_16x16x32_bf16 v[36:39], v[164:167], v[188:191], v[36:39]
	v_mfma_f32_16x16x32_bf16 v[32:35], v[172:175], v[188:191], v[32:35]
	v_mfma_f32_16x16x32_bf16 v[20:23], v[164:167], v[218:221], v[20:23]
	v_mfma_f32_16x16x32_bf16 v[16:19], v[172:175], v[218:221], v[16:19]
	v_mfma_f32_16x16x32_bf16 v[4:7], v[164:167], v[226:229], v[4:7]
	v_mfma_f32_16x16x32_bf16 v[0:3], v[172:175], v[226:229], v[0:3]
	s_setprio 0
	s_barrier
	s_add_i32 s22, 0, 0x18000
	s_add_i32 s23, 0, 0x1c000
	v_add_u32_e32 v156, s22, v145
	v_add_u32_e32 v172, s23, v145
	ds_read_b128 v[140:143], v156
	ds_read_b128 v[148:151], v156 offset:1024
	ds_read_b128 v[152:155], v156 offset:2048
	ds_read_b128 v[156:159], v156 offset:3072
	ds_read_b128 v[160:163], v172
	ds_read_b128 v[164:167], v172 offset:1024
	ds_read_b128 v[168:171], v172 offset:2048
	ds_read_b128 v[172:175], v172 offset:3072
	s_add_u32 s10, s10, 0x40000
	s_addc_u32 s11, s11, 0
	s_mov_b32 m0, s14
	v_lshl_add_u64 v[236:237], s[10:11], 0, v[134:135]
	ds_read_b128 v[176:179], v147 offset:32768
	ds_read_b128 v[180:183], v147 offset:33792
	ds_read_b128 v[184:187], v147 offset:34816
	ds_read_b128 v[188:191], v147 offset:35840
	ds_read_b128 v[214:217], v147 offset:36864
	ds_read_b128 v[218:221], v147 offset:37888
	ds_read_b128 v[222:225], v147 offset:38912
	ds_read_b128 v[226:229], v147 offset:39936
	global_load_lds_dwordx4 v[236:237], off
	s_mov_b32 m0, s15
	v_lshl_add_u64 v[236:237], s[10:11], 0, v[132:133]
	global_load_lds_dwordx4 v[236:237], off
	s_waitcnt vmcnt(8) lgkmcnt(0)
	s_barrier
	s_setprio 1
	v_mfma_f32_16x16x32_bf16 v[126:129], v[140:143], v[176:179], v[126:129]
	v_mfma_f32_16x16x32_bf16 v[122:125], v[152:155], v[176:179], v[122:125]
	v_mfma_f32_16x16x32_bf16 v[110:113], v[140:143], v[184:187], v[110:113]
	v_mfma_f32_16x16x32_bf16 v[106:109], v[152:155], v[184:187], v[106:109]
	v_mfma_f32_16x16x32_bf16 v[94:97], v[140:143], v[214:217], v[94:97]
	v_mfma_f32_16x16x32_bf16 v[90:93], v[152:155], v[214:217], v[90:93]
	v_mfma_f32_16x16x32_bf16 v[78:81], v[140:143], v[222:225], v[78:81]
	v_mfma_f32_16x16x32_bf16 v[74:77], v[152:155], v[222:225], v[74:77]
	v_mfma_f32_16x16x32_bf16 v[126:129], v[148:151], v[180:183], v[126:129]
	v_mfma_f32_16x16x32_bf16 v[122:125], v[156:159], v[180:183], v[122:125]
	v_mfma_f32_16x16x32_bf16 v[110:113], v[148:151], v[188:191], v[110:113]
	v_mfma_f32_16x16x32_bf16 v[106:109], v[156:159], v[188:191], v[106:109]
	v_mfma_f32_16x16x32_bf16 v[94:97], v[148:151], v[218:221], v[94:97]
	v_mfma_f32_16x16x32_bf16 v[90:93], v[156:159], v[218:221], v[90:93]
	v_mfma_f32_16x16x32_bf16 v[78:81], v[148:151], v[226:229], v[78:81]
	v_mfma_f32_16x16x32_bf16 v[74:77], v[156:159], v[226:229], v[74:77]
	s_setprio 0
	s_setprio 1
	v_mfma_f32_16x16x32_bf16 v[118:121], v[160:163], v[176:179], v[118:121]
	v_mfma_f32_16x16x32_bf16 v[114:117], v[168:171], v[176:179], v[114:117]
	v_mfma_f32_16x16x32_bf16 v[102:105], v[160:163], v[184:187], v[102:105]
	v_mfma_f32_16x16x32_bf16 v[98:101], v[168:171], v[184:187], v[98:101]
	v_mfma_f32_16x16x32_bf16 v[86:89], v[160:163], v[214:217], v[86:89]
	v_mfma_f32_16x16x32_bf16 v[82:85], v[168:171], v[214:217], v[82:85]
	v_mfma_f32_16x16x32_bf16 v[70:73], v[160:163], v[222:225], v[70:73]
	v_mfma_f32_16x16x32_bf16 v[66:69], v[168:171], v[222:225], v[66:69]
	v_mfma_f32_16x16x32_bf16 v[118:121], v[164:167], v[180:183], v[118:121]
	v_mfma_f32_16x16x32_bf16 v[114:117], v[172:175], v[180:183], v[114:117]
	v_mfma_f32_16x16x32_bf16 v[102:105], v[164:167], v[188:191], v[102:105]
	v_mfma_f32_16x16x32_bf16 v[98:101], v[172:175], v[188:191], v[98:101]
	v_mfma_f32_16x16x32_bf16 v[86:89], v[164:167], v[218:221], v[86:89]
	v_mfma_f32_16x16x32_bf16 v[82:85], v[172:175], v[218:221], v[82:85]
	v_mfma_f32_16x16x32_bf16 v[70:73], v[164:167], v[226:229], v[70:73]
	v_mfma_f32_16x16x32_bf16 v[66:69], v[172:175], v[226:229], v[66:69]
	s_setprio 0
	s_barrier
; #define PG8_STAGE(bufoff, gbase, voff) do { _Pragma("unroll") for (int _i = 0; _i < 2; ++_i) \
;         __builtin_amdgcn_global_load_lds((const unsigned*)((const char*)(gbase) + (voff)[_i]), (LAS unsigned*)(lds + (bufoff) + ldsw + _i * 8192), 16, 0, 0); } while (0)
; #define PG8_LDA(dst, b, h) do { _Pragma("unroll") for (int m = 0; m < 4; ++m) _Pragma("unroll") for (int k = 0; k < 2; ++k) dst[m][k] = *(const LAS bf16x8*)(lds + PG8_SA(b, h) + aoff + m * 2048 + k * 1024); } while (0)
; #define PG8_MMA(ai, bj, At, Bt) do { __builtin_amdgcn_s_setprio(1); _Pragma("unroll") for (int m = 0; m < 4; ++m) _Pragma("unroll") for (int n = 0; n < 2; ++n) _Pragma("unroll") for (int k = 0; k < 2; ++k) \
;         acc[ai][bj][m][n] = __builtin_amdgcn_mfma_f32_16x16x32_bf16(Bt[n][k], At[m][k], acc[ai][bj][m][n], 0, 0, 0); __builtin_amdgcn_s_setprio(0); } while (0)
; #define PG8_WAIT_V(n) asm volatile("s_waitcnt vmcnt(" #n ")" ::: "memory")
; #define PG8_WAIT_L(n) asm volatile("s_waitcnt lgkmcnt(" #n ")" ::: "memory")
; #define PG8_BAR __builtin_amdgcn_s_barrier()
; #define PG8_SCHED __builtin_amdgcn_sched_barrier(0)
; template <class Epi, bool SP2, class Sched>
; __device__ __forceinline__ void gemm_phase(LAS unsigned char* lds, const Gemm g, const Sched& S, const Epi& E) {
;     ...
;         for (int t = 0; t < nt; t += 2) {
;             const bool last = (t == nt - 2);
;     ...
;             PG8_LDA(At, 1, 1); PG8_STAGE(PG8_SB(1, 0), b3, voffB); PG8_STAGE(PG8_SB(1, 1), b3 + hstepB, voffB); PG8_STAGE(PG8_SA(1, 0), a3, voffA);
;             PG8_WAIT_V(8); PG8_WAIT_L(0); PG8_BAR; PG8_MMA(1, 0, At, B0); PG8_MMA(1, 1, At, B1); PG8_BAR; PG8_SCHED;
	s_add_i32 s10, s22, s69
	v_lshl_add_u64 v[192:193], v[192:193], 0, s[66:67]
	s_mov_b32 m0, s10
	ds_read_b128 v[176:179], v147 offset:49152
	ds_read_b128 v[180:183], v147 offset:50176
	ds_read_b128 v[184:187], v147 offset:51200
	ds_read_b128 v[188:191], v147 offset:52224
	ds_read_b128 v[214:217], v147 offset:53248
	ds_read_b128 v[218:221], v147 offset:54272
	ds_read_b128 v[222:225], v147 offset:55296
	ds_read_b128 v[226:229], v147 offset:56320
	global_load_lds_dwordx4 v[192:193], off
	s_add_i32 m0, s10, 0x2000
	s_add_u32 s6, s6, 0x40080
	v_lshl_add_u64 v[192:193], v[230:231], 0, s[66:67]
	s_addc_u32 s7, s7, 0
	s_add_i32 s10, s23, s69
	global_load_lds_dwordx4 v[192:193], off
	s_mov_b32 m0, s10
	v_lshl_add_u64 v[192:193], s[6:7], 0, v[64:65]
	global_load_lds_dwordx4 v[192:193], off
	s_add_i32 m0, s10, 0x2000
	v_lshl_add_u64 v[192:193], s[6:7], 0, v[130:131]
	global_load_lds_dwordx4 v[192:193], off
	s_mov_b32 m0, s17
	v_lshl_add_u64 v[192:193], v[232:233], 0, s[66:67]
	global_load_lds_dwordx4 v[192:193], off
	s_mov_b32 m0, s18
	v_lshl_add_u64 v[192:193], v[234:235], 0, s[66:67]
	global_load_lds_dwordx4 v[192:193], off
	s_waitcnt vmcnt(8) lgkmcnt(0)
	s_barrier
	s_setprio 1
	v_mfma_f32_16x16x32_bf16 v[60:63], v[140:143], v[176:179], v[60:63]
	v_mfma_f32_16x16x32_bf16 v[56:59], v[152:155], v[176:179], v[56:59]
	v_mfma_f32_16x16x32_bf16 v[44:47], v[140:143], v[184:187], v[44:47]
	v_mfma_f32_16x16x32_bf16 v[40:43], v[152:155], v[184:187], v[40:43]
	v_mfma_f32_16x16x32_bf16 v[28:31], v[140:143], v[214:217], v[28:31]
	v_mfma_f32_16x16x32_bf16 v[24:27], v[152:155], v[214:217], v[24:27]
	v_mfma_f32_16x16x32_bf16 v[12:15], v[140:143], v[222:225], v[12:15]
	v_mfma_f32_16x16x32_bf16 v[8:11], v[152:155], v[222:225], v[8:11]
	v_mfma_f32_16x16x32_bf16 v[60:63], v[148:151], v[180:183], v[60:63]
	v_mfma_f32_16x16x32_bf16 v[56:59], v[156:159], v[180:183], v[56:59]
	v_mfma_f32_16x16x32_bf16 v[44:47], v[148:151], v[188:191], v[44:47]
	v_mfma_f32_16x16x32_bf16 v[40:43], v[156:159], v[188:191], v[40:43]
	v_mfma_f32_16x16x32_bf16 v[28:31], v[148:151], v[218:221], v[28:31]
	v_mfma_f32_16x16x32_bf16 v[24:27], v[156:159], v[218:221], v[24:27]
	v_mfma_f32_16x16x32_bf16 v[12:15], v[148:151], v[226:229], v[12:15]
	v_mfma_f32_16x16x32_bf16 v[8:11], v[156:159], v[226:229], v[8:11]
	s_setprio 0
	s_setprio 1
	v_mfma_f32_16x16x32_bf16 v[52:55], v[160:163], v[176:179], v[52:55]
	v_mfma_f32_16x16x32_bf16 v[48:51], v[168:171], v[176:179], v[48:51]
	v_mfma_f32_16x16x32_bf16 v[36:39], v[160:163], v[184:187], v[36:39]
	v_mfma_f32_16x16x32_bf16 v[32:35], v[168:171], v[184:187], v[32:35]
	v_mfma_f32_16x16x32_bf16 v[20:23], v[160:163], v[214:217], v[20:23]
	v_mfma_f32_16x16x32_bf16 v[16:19], v[168:171], v[214:217], v[16:19]
	v_mfma_f32_16x16x32_bf16 v[4:7], v[160:163], v[222:225], v[4:7]
	v_mfma_f32_16x16x32_bf16 v[0:3], v[168:171], v[222:225], v[0:3]
	v_mfma_f32_16x16x32_bf16 v[52:55], v[164:167], v[180:183], v[52:55]
	v_mfma_f32_16x16x32_bf16 v[48:51], v[172:175], v[180:183], v[48:51]
	v_mfma_f32_16x16x32_bf16 v[36:39], v[164:167], v[188:191], v[36:39]
	v_mfma_f32_16x16x32_bf16 v[32:35], v[172:175], v[188:191], v[32:35]
	v_mfma_f32_16x16x32_bf16 v[20:23], v[164:167], v[218:221], v[20:23]
	v_mfma_f32_16x16x32_bf16 v[16:19], v[172:175], v[218:221], v[16:19]
	v_mfma_f32_16x16x32_bf16 v[4:7], v[164:167], v[226:229], v[4:7]
	v_mfma_f32_16x16x32_bf16 v[0:3], v[172:175], v[226:229], v[0:3]
	s_setprio 0
	s_barrier
	s_add_i32 s21, s21, 2
	s_add_u32 s76, s76, 0x100
	s_addc_u32 s20, s20, 0
	s_add_u32 s88, s88, 0x100
	s_addc_u32 s89, s89, 0
	s_cmp_gt_u32 s21, 13
	s_cbranch_scc0 .LBB0_783
	s_and_b64 vcc, exec, s[4:5]
	s_cbranch_vccz .LBB0_786
	s_barrier

; #define PG8_STAGE(bufoff, gbase, voff) do { _Pragma("unroll") for (int _i = 0; _i < 2; ++_i) \
;         __builtin_amdgcn_global_load_lds((const unsigned*)((const char*)(gbase) + (voff)[_i]), (LAS unsigned*)(lds + (bufoff) + ldsw + _i * 8192), 16, 0, 0); } while (0)
; #define PG8_LDA(dst, b, h) do { _Pragma("unroll") for (int m = 0; m < 4; ++m) _Pragma("unroll") for (int k = 0; k < 2; ++k) dst[m][k] = *(const LAS bf16x8*)(lds + PG8_SA(b, h) + aoff + m * 2048 + k * 1024); } while (0)
; #define PG8_LDB(dst, b, h) do { _Pragma("unroll") for (int n = 0; n < 2; ++n) _Pragma("unroll") for (int k = 0; k < 2; ++k) dst[n][k] = *(const LAS bf16x8*)(lds + PG8_SB(b, h) + boff + n * 2048 + k * 1024); } while (0)
; #define PG8_MMA(ai, bj, At, Bt) do { __builtin_amdgcn_s_setprio(1); _Pragma("unroll") for (int m = 0; m < 4; ++m) _Pragma("unroll") for (int n = 0; n < 2; ++n) _Pragma("unroll") for (int k = 0; k < 2; ++k) \
;         acc[ai][bj][m][n] = __builtin_amdgcn_mfma_f32_16x16x32_bf16(Bt[n][k], At[m][k], acc[ai][bj][m][n], 0, 0, 0); __builtin_amdgcn_s_setprio(0); } while (0)
; #define PG8_WAIT_V(n) asm volatile("s_waitcnt vmcnt(" #n ")" ::: "memory")
; #define PG8_WAIT_L(n) asm volatile("s_waitcnt lgkmcnt(" #n ")" ::: "memory")
; #define PG8_BAR __builtin_amdgcn_s_barrier()
; template <class Epi, bool SP2, class Sched>
; __device__ __forceinline__ void gemm_phase(LAS unsigned char* lds, const Gemm g, const Sched& S, const Epi& E) {
;     ...
;             const bool last = (t == nt - 2);
;             const char* a1 = cA + (size_t)(t + 1) * kstep;
;             const char* a2 = last ? nA : cA + (size_t)(t + 2) * kstep; const char* b2 = last ? nB : cB + (size_t)(t + 2) * kstep;
;             const char* a3 = a2 + kstep; const char* b3 = b2 + kstep;
;             if constexpr (Epi::MID) { if (t == (nt >> 1)) E.mid(acc, cur, wr, fr); }
;             if constexpr (SP2) {
;             PG8_LDB(B0, 0, 0); PG8_LDB(B1, 0, 1); PG8_SCHED; PG8_LDA(At, 0, 0); PG8_STAGE(PG8_SA(1, 1), a1 + hstep, voffA);
;             PG8_WAIT_V(8); PG8_WAIT_L(0); PG8_BAR; PG8_MMA(0, 0, At, B0); PG8_MMA(0, 1, At, B1); PG8_BAR; PG8_SCHED;
;             PG8_LDA(At, 0, 1); PG8_STAGE(PG8_SB(0, 0), b2, voffB); PG8_STAGE(PG8_SB(0, 1), b2 + hstepB, voffB); PG8_STAGE(PG8_SA(0, 0), a2, voffA);
;             PG8_WAIT_V(8); PG8_WAIT_L(0); PG8_BAR; PG8_MMA(1, 0, At, B0); PG8_MMA(1, 1, At, B1); PG8_BAR; PG8_SCHED;
.LBB0_807:
	s_add_u32 s6, s88, 0xfffc0080
	s_addc_u32 s7, s89, -1
	s_add_i32 s22, 0, 0x10000
	s_cmp_eq_u32 s21, 12
	s_cselect_b32 s11, s59, s7
	s_cselect_b32 s10, s75, s6
	v_add_u32_e32 v64, s22, v143
	s_cselect_b32 s7, s57, s20
	s_cselect_b32 s6, s76, s77
	s_add_i32 s24, 0, 0x14000
	ds_read_b128 v[138:141], v64
	ds_read_b128 v[146:149], v64 offset:1024
	ds_read_b128 v[150:153], v64 offset:2048
	ds_read_b128 v[154:157], v64 offset:3072
	v_add_u32_e32 v64, s24, v143
	ds_read_b128 v[158:161], v64
	ds_read_b128 v[162:165], v64 offset:1024
	ds_read_b128 v[166:169], v64 offset:2048
	ds_read_b128 v[170:173], v64 offset:3072
	v_lshl_add_u64 v[226:227], s[88:89], 0, v[136:137]
	s_add_i32 m0, s33, 0xc000
	ds_read_b128 v[174:177], v145
	ds_read_b128 v[178:181], v145 offset:1024
	ds_read_b128 v[182:185], v145 offset:2048
	ds_read_b128 v[186:189], v145 offset:3072
	ds_read_b128 v[190:193], v145 offset:4096
	ds_read_b128 v[214:217], v145 offset:5120
	ds_read_b128 v[218:221], v145 offset:6144
	ds_read_b128 v[222:225], v145 offset:7168
	global_load_lds_dwordx4 v[226:227], off
	s_add_i32 m0, s33, 0xe000
	v_lshl_add_u64 v[226:227], s[88:89], 0, v[134:135]
	global_load_lds_dwordx4 v[226:227], off
	s_waitcnt vmcnt(8) lgkmcnt(0)
	s_barrier
	s_setprio 1
	v_mfma_f32_16x16x32_bf16 v[126:129], v[138:141], v[174:177], v[126:129]
	v_mfma_f32_16x16x32_bf16 v[122:125], v[150:153], v[174:177], v[122:125]
	v_mfma_f32_16x16x32_bf16 v[114:117], v[138:141], v[182:185], v[114:117]
	v_mfma_f32_16x16x32_bf16 v[106:109], v[150:153], v[182:185], v[106:109]
	v_mfma_f32_16x16x32_bf16 v[98:101], v[138:141], v[190:193], v[98:101]
	v_mfma_f32_16x16x32_bf16 v[90:93], v[150:153], v[190:193], v[90:93]
	v_mfma_f32_16x16x32_bf16 v[82:85], v[138:141], v[218:221], v[82:85]
	v_mfma_f32_16x16x32_bf16 v[74:77], v[150:153], v[218:221], v[74:77]
	v_mfma_f32_16x16x32_bf16 v[126:129], v[146:149], v[178:181], v[126:129]
	v_mfma_f32_16x16x32_bf16 v[122:125], v[154:157], v[178:181], v[122:125]
	v_mfma_f32_16x16x32_bf16 v[114:117], v[146:149], v[186:189], v[114:117]
	v_mfma_f32_16x16x32_bf16 v[106:109], v[154:157], v[186:189], v[106:109]
	v_mfma_f32_16x16x32_bf16 v[98:101], v[146:149], v[214:217], v[98:101]
	v_mfma_f32_16x16x32_bf16 v[90:93], v[154:157], v[214:217], v[90:93]
	v_mfma_f32_16x16x32_bf16 v[82:85], v[146:149], v[222:225], v[82:85]
	v_mfma_f32_16x16x32_bf16 v[74:77], v[154:157], v[222:225], v[74:77]
	s_setprio 0
	s_setprio 1
	v_mfma_f32_16x16x32_bf16 v[118:121], v[158:161], v[174:177], v[118:121]
	v_mfma_f32_16x16x32_bf16 v[110:113], v[166:169], v[174:177], v[110:113]
	v_mfma_f32_16x16x32_bf16 v[102:105], v[158:161], v[182:185], v[102:105]
	v_mfma_f32_16x16x32_bf16 v[94:97], v[166:169], v[182:185], v[94:97]
	v_mfma_f32_16x16x32_bf16 v[86:89], v[158:161], v[190:193], v[86:89]
	v_mfma_f32_16x16x32_bf16 v[78:81], v[166:169], v[190:193], v[78:81]
	v_mfma_f32_16x16x32_bf16 v[70:73], v[158:161], v[218:221], v[70:73]
	v_mfma_f32_16x16x32_bf16 v[66:69], v[166:169], v[218:221], v[66:69]
	v_mfma_f32_16x16x32_bf16 v[118:121], v[162:165], v[178:181], v[118:121]
	v_mfma_f32_16x16x32_bf16 v[110:113], v[170:173], v[178:181], v[110:113]
	v_mfma_f32_16x16x32_bf16 v[102:105], v[162:165], v[186:189], v[102:105]
	v_mfma_f32_16x16x32_bf16 v[94:97], v[170:173], v[186:189], v[94:97]
	v_mfma_f32_16x16x32_bf16 v[86:89], v[162:165], v[214:217], v[86:89]
	v_mfma_f32_16x16x32_bf16 v[78:81], v[170:173], v[214:217], v[78:81]
	v_mfma_f32_16x16x32_bf16 v[70:73], v[162:165], v[222:225], v[70:73]
	v_mfma_f32_16x16x32_bf16 v[66:69], v[170:173], v[222:225], v[66:69]
	s_setprio 0
	s_barrier
	s_add_i32 s22, s22, s19
	v_lshl_add_u64 v[226:227], s[6:7], 0, v[130:131]
	s_mov_b32 m0, s22
	ds_read_b128 v[174:177], v145 offset:16384
	ds_read_b128 v[178:181], v145 offset:17408
	ds_read_b128 v[182:185], v145 offset:18432
	ds_read_b128 v[186:189], v145 offset:19456
	ds_read_b128 v[190:193], v145 offset:20480
	ds_read_b128 v[214:217], v145 offset:21504
	ds_read_b128 v[218:221], v145 offset:22528
	ds_read_b128 v[222:225], v145 offset:23552
	global_load_lds_dwordx4 v[226:227], off
	s_add_i32 m0, s22, 0x2000
	s_add_u32 s22, s6, 0x40000
	v_lshl_add_u64 v[228:229], s[6:7], 0, v[132:133]
	s_addc_u32 s23, s7, 0
	s_add_i32 s24, s24, s19
	global_load_lds_dwordx4 v[228:229], off
	v_lshl_add_u64 v[230:231], s[22:23], 0, v[130:131]
	s_mov_b32 m0, s24
	v_lshl_add_u64 v[232:233], s[10:11], 0, v[132:133]
	global_load_lds_dwordx4 v[230:231], off
	s_add_i32 m0, s24, 0x2000
	v_lshl_add_u64 v[230:231], s[22:23], 0, v[132:133]
	global_load_lds_dwordx4 v[230:231], off
	s_mov_b32 m0, s33
	v_lshl_add_u64 v[230:231], s[10:11], 0, v[130:131]
	global_load_lds_dwordx4 v[230:231], off
	s_mov_b32 m0, s62
	s_nop 0
	global_load_lds_dwordx4 v[232:233], off
	s_waitcnt vmcnt(8) lgkmcnt(0)
	s_barrier
; #define PG8_STAGE(bufoff, gbase, voff) do { _Pragma("unroll") for (int _i = 0; _i < 2; ++_i) \
;         __builtin_amdgcn_global_load_lds((const unsigned*)((const char*)(gbase) + (voff)[_i]), (LAS unsigned*)(lds + (bufoff) + ldsw + _i * 8192), 16, 0, 0); } while (0)
; #define PG8_LDA(dst, b, h) do { _Pragma("unroll") for (int m = 0; m < 4; ++m) _Pragma("unroll") for (int k = 0; k < 2; ++k) dst[m][k] = *(const LAS bf16x8*)(lds + PG8_SA(b, h) + aoff + m * 2048 + k * 1024); } while (0)
; #define PG8_LDB(dst, b, h) do { _Pragma("unroll") for (int n = 0; n < 2; ++n) _Pragma("unroll") for (int k = 0; k < 2; ++k) dst[n][k] = *(const LAS bf16x8*)(lds + PG8_SB(b, h) + boff + n * 2048 + k * 1024); } while (0)
; #define PG8_MMA(ai, bj, At, Bt) do { __builtin_amdgcn_s_setprio(1); _Pragma("unroll") for (int m = 0; m < 4; ++m) _Pragma("unroll") for (int n = 0; n < 2; ++n) _Pragma("unroll") for (int k = 0; k < 2; ++k) \
;         acc[ai][bj][m][n] = __builtin_amdgcn_mfma_f32_16x16x32_bf16(Bt[n][k], At[m][k], acc[ai][bj][m][n], 0, 0, 0); __builtin_amdgcn_s_setprio(0); } while (0)
; #define PG8_WAIT_V(n) asm volatile("s_waitcnt vmcnt(" #n ")" ::: "memory")
; #define PG8_WAIT_L(n) asm volatile("s_waitcnt lgkmcnt(" #n ")" ::: "memory")
; #define PG8_BAR __builtin_amdgcn_s_barrier()
; #define PG8_SCHED __builtin_amdgcn_sched_barrier(0)
; template <class Epi, bool SP2, class Sched>
; __device__ __forceinline__ void gemm_phase(LAS unsigned char* lds, const Gemm g, const Sched& S, const Epi& E) {
;     ...
;             PG8_WAIT_V(8); PG8_WAIT_L(0); PG8_BAR; PG8_MMA(1, 0, At, B0); PG8_MMA(1, 1, At, B1); PG8_BAR; PG8_SCHED;
;             PG8_LDB(B0, 1, 0); PG8_LDB(B1, 1, 1); PG8_SCHED; PG8_LDA(At, 1, 0); PG8_STAGE(PG8_SA(0, 1), a2 + hstep, voffA);
;             PG8_WAIT_V(8); PG8_WAIT_L(0); PG8_BAR; PG8_MMA(0, 0, At, B0); PG8_MMA(0, 1, At, B1); PG8_BAR; PG8_SCHED;
	s_setprio 1
	v_mfma_f32_16x16x32_bf16 v[60:63], v[138:141], v[174:177], v[60:63]
	v_mfma_f32_16x16x32_bf16 v[56:59], v[150:153], v[174:177], v[56:59]
	v_mfma_f32_16x16x32_bf16 v[48:51], v[138:141], v[182:185], v[48:51]
	v_mfma_f32_16x16x32_bf16 v[40:43], v[150:153], v[182:185], v[40:43]
	v_mfma_f32_16x16x32_bf16 v[32:35], v[138:141], v[190:193], v[32:35]
	v_mfma_f32_16x16x32_bf16 v[24:27], v[150:153], v[190:193], v[24:27]
	v_mfma_f32_16x16x32_bf16 v[12:15], v[138:141], v[218:221], v[12:15]
	v_mfma_f32_16x16x32_bf16 v[8:11], v[150:153], v[218:221], v[8:11]
	v_mfma_f32_16x16x32_bf16 v[60:63], v[146:149], v[178:181], v[60:63]
	v_mfma_f32_16x16x32_bf16 v[56:59], v[154:157], v[178:181], v[56:59]
	v_mfma_f32_16x16x32_bf16 v[48:51], v[146:149], v[186:189], v[48:51]
	v_mfma_f32_16x16x32_bf16 v[40:43], v[154:157], v[186:189], v[40:43]
	v_mfma_f32_16x16x32_bf16 v[32:35], v[146:149], v[214:217], v[32:35]
	v_mfma_f32_16x16x32_bf16 v[24:27], v[154:157], v[214:217], v[24:27]
	v_mfma_f32_16x16x32_bf16 v[12:15], v[146:149], v[222:225], v[12:15]
	v_mfma_f32_16x16x32_bf16 v[8:11], v[154:157], v[222:225], v[8:11]
	s_setprio 0
	s_setprio 1
	v_mfma_f32_16x16x32_bf16 v[52:55], v[158:161], v[174:177], v[52:55]
	v_mfma_f32_16x16x32_bf16 v[44:47], v[166:169], v[174:177], v[44:47]
	v_mfma_f32_16x16x32_bf16 v[36:39], v[158:161], v[182:185], v[36:39]
	v_mfma_f32_16x16x32_bf16 v[28:31], v[166:169], v[182:185], v[28:31]
	v_mfma_f32_16x16x32_bf16 v[20:23], v[158:161], v[190:193], v[20:23]
	v_mfma_f32_16x16x32_bf16 v[16:19], v[166:169], v[190:193], v[16:19]
	v_mfma_f32_16x16x32_bf16 v[4:7], v[158:161], v[218:221], v[4:7]
	v_mfma_f32_16x16x32_bf16 v[0:3], v[166:169], v[218:221], v[0:3]
	v_mfma_f32_16x16x32_bf16 v[52:55], v[162:165], v[178:181], v[52:55]
	v_mfma_f32_16x16x32_bf16 v[44:47], v[170:173], v[178:181], v[44:47]
	v_mfma_f32_16x16x32_bf16 v[36:39], v[162:165], v[186:189], v[36:39]
	v_mfma_f32_16x16x32_bf16 v[28:31], v[170:173], v[186:189], v[28:31]
	v_mfma_f32_16x16x32_bf16 v[20:23], v[162:165], v[214:217], v[20:23]
	v_mfma_f32_16x16x32_bf16 v[16:19], v[170:173], v[214:217], v[16:19]
	v_mfma_f32_16x16x32_bf16 v[4:7], v[162:165], v[222:225], v[4:7]
	v_mfma_f32_16x16x32_bf16 v[0:3], v[170:173], v[222:225], v[0:3]
	s_setprio 0
	s_barrier
	s_add_i32 s22, 0, 0x18000
	v_add_u32_e32 v64, s22, v143
	s_add_i32 s23, 0, 0x1c000
	ds_read_b128 v[138:141], v64
	ds_read_b128 v[146:149], v64 offset:1024
	ds_read_b128 v[150:153], v64 offset:2048
	ds_read_b128 v[154:157], v64 offset:3072
	v_add_u32_e32 v64, s23, v143
	ds_read_b128 v[158:161], v64
	ds_read_b128 v[162:165], v64 offset:1024
	ds_read_b128 v[166:169], v64 offset:2048
	ds_read_b128 v[170:173], v64 offset:3072
	s_add_u32 s10, s10, 0x40000
	s_addc_u32 s11, s11, 0
	s_mov_b32 m0, s64
	v_lshl_add_u64 v[234:235], s[10:11], 0, v[130:131]
	ds_read_b128 v[174:177], v145 offset:32768
	ds_read_b128 v[178:181], v145 offset:33792
	ds_read_b128 v[182:185], v145 offset:34816
	ds_read_b128 v[186:189], v145 offset:35840
	ds_read_b128 v[190:193], v145 offset:36864
	ds_read_b128 v[214:217], v145 offset:37888
	ds_read_b128 v[218:221], v145 offset:38912
	ds_read_b128 v[222:225], v145 offset:39936
	global_load_lds_dwordx4 v[234:235], off
	s_mov_b32 m0, s65
	v_lshl_add_u64 v[234:235], s[10:11], 0, v[132:133]
	global_load_lds_dwordx4 v[234:235], off
	s_waitcnt vmcnt(8) lgkmcnt(0)
	s_barrier
	s_setprio 1
	v_mfma_f32_16x16x32_bf16 v[126:129], v[138:141], v[174:177], v[126:129]
	v_mfma_f32_16x16x32_bf16 v[122:125], v[150:153], v[174:177], v[122:125]
	v_mfma_f32_16x16x32_bf16 v[114:117], v[138:141], v[182:185], v[114:117]
	v_mfma_f32_16x16x32_bf16 v[106:109], v[150:153], v[182:185], v[106:109]
	v_mfma_f32_16x16x32_bf16 v[98:101], v[138:141], v[190:193], v[98:101]
	v_mfma_f32_16x16x32_bf16 v[90:93], v[150:153], v[190:193], v[90:93]
	v_mfma_f32_16x16x32_bf16 v[82:85], v[138:141], v[218:221], v[82:85]
	v_mfma_f32_16x16x32_bf16 v[74:77], v[150:153], v[218:221], v[74:77]
	v_mfma_f32_16x16x32_bf16 v[126:129], v[146:149], v[178:181], v[126:129]
	v_mfma_f32_16x16x32_bf16 v[122:125], v[154:157], v[178:181], v[122:125]
	v_mfma_f32_16x16x32_bf16 v[114:117], v[146:149], v[186:189], v[114:117]
	v_mfma_f32_16x16x32_bf16 v[106:109], v[154:157], v[186:189], v[106:109]
	v_mfma_f32_16x16x32_bf16 v[98:101], v[146:149], v[214:217], v[98:101]
	v_mfma_f32_16x16x32_bf16 v[90:93], v[154:157], v[214:217], v[90:93]
	v_mfma_f32_16x16x32_bf16 v[82:85], v[146:149], v[222:225], v[82:85]
	v_mfma_f32_16x16x32_bf16 v[74:77], v[154:157], v[222:225], v[74:77]
	s_setprio 0
	s_setprio 1
	v_mfma_f32_16x16x32_bf16 v[118:121], v[158:161], v[174:177], v[118:121]
	v_mfma_f32_16x16x32_bf16 v[110:113], v[166:169], v[174:177], v[110:113]
	v_mfma_f32_16x16x32_bf16 v[102:105], v[158:161], v[182:185], v[102:105]
	v_mfma_f32_16x16x32_bf16 v[94:97], v[166:169], v[182:185], v[94:97]
	v_mfma_f32_16x16x32_bf16 v[86:89], v[158:161], v[190:193], v[86:89]
	v_mfma_f32_16x16x32_bf16 v[78:81], v[166:169], v[190:193], v[78:81]
	v_mfma_f32_16x16x32_bf16 v[70:73], v[158:161], v[218:221], v[70:73]
	v_mfma_f32_16x16x32_bf16 v[66:69], v[166:169], v[218:221], v[66:69]
	v_mfma_f32_16x16x32_bf16 v[118:121], v[162:165], v[178:181], v[118:121]
	v_mfma_f32_16x16x32_bf16 v[110:113], v[170:173], v[178:181], v[110:113]
	v_mfma_f32_16x16x32_bf16 v[102:105], v[162:165], v[186:189], v[102:105]
	v_mfma_f32_16x16x32_bf16 v[94:97], v[170:173], v[186:189], v[94:97]
	v_mfma_f32_16x16x32_bf16 v[86:89], v[162:165], v[214:217], v[86:89]
	v_mfma_f32_16x16x32_bf16 v[78:81], v[170:173], v[214:217], v[78:81]
	v_mfma_f32_16x16x32_bf16 v[70:73], v[162:165], v[222:225], v[70:73]
	v_mfma_f32_16x16x32_bf16 v[66:69], v[170:173], v[222:225], v[66:69]
	s_setprio 0
	s_barrier
; #define PG8_STAGE(bufoff, gbase, voff) do { _Pragma("unroll") for (int _i = 0; _i < 2; ++_i) \
;         __builtin_amdgcn_global_load_lds((const unsigned*)((const char*)(gbase) + (voff)[_i]), (LAS unsigned*)(lds + (bufoff) + ldsw + _i * 8192), 16, 0, 0); } while (0)
; #define PG8_LDA(dst, b, h) do { _Pragma("unroll") for (int m = 0; m < 4; ++m) _Pragma("unroll") for (int k = 0; k < 2; ++k) dst[m][k] = *(const LAS bf16x8*)(lds + PG8_SA(b, h) + aoff + m * 2048 + k * 1024); } while (0)
; #define PG8_MMA(ai, bj, At, Bt) do { __builtin_amdgcn_s_setprio(1); _Pragma("unroll") for (int m = 0; m < 4; ++m) _Pragma("unroll") for (int n = 0; n < 2; ++n) _Pragma("unroll") for (int k = 0; k < 2; ++k) \
;         acc[ai][bj][m][n] = __builtin_amdgcn_mfma_f32_16x16x32_bf16(Bt[n][k], At[m][k], acc[ai][bj][m][n], 0, 0, 0); __builtin_amdgcn_s_setprio(0); } while (0)
; #define PG8_WAIT_V(n) asm volatile("s_waitcnt vmcnt(" #n ")" ::: "memory")
; #define PG8_WAIT_L(n) asm volatile("s_waitcnt lgkmcnt(" #n ")" ::: "memory")
; #define PG8_BAR __builtin_amdgcn_s_barrier()
; #define PG8_SCHED __builtin_amdgcn_sched_barrier(0)
; template <class Epi, bool SP2, class Sched>
; __device__ __forceinline__ void gemm_phase(LAS unsigned char* lds, const Gemm g, const Sched& S, const Epi& E) {
;     ...
;         for (int t = 0; t < nt; t += 2) {
;             const bool last = (t == nt - 2);
;     ...
;             PG8_LDA(At, 1, 1); PG8_STAGE(PG8_SB(1, 0), b3, voffB); PG8_STAGE(PG8_SB(1, 1), b3 + hstepB, voffB); PG8_STAGE(PG8_SA(1, 0), a3, voffA);
;             PG8_WAIT_V(8); PG8_WAIT_L(0); PG8_BAR; PG8_MMA(1, 0, At, B0); PG8_MMA(1, 1, At, B1); PG8_BAR; PG8_SCHED;
	s_add_i32 s10, s22, s19
	v_lshl_add_u64 v[226:227], v[226:227], 0, s[66:67]
	s_mov_b32 m0, s10
	ds_read_b128 v[174:177], v145 offset:49152
	ds_read_b128 v[178:181], v145 offset:50176
	ds_read_b128 v[182:185], v145 offset:51200
	ds_read_b128 v[186:189], v145 offset:52224
	ds_read_b128 v[190:193], v145 offset:53248
	ds_read_b128 v[214:217], v145 offset:54272
	ds_read_b128 v[218:221], v145 offset:55296
	ds_read_b128 v[222:225], v145 offset:56320
	global_load_lds_dwordx4 v[226:227], off
	s_add_i32 m0, s10, 0x2000
	s_add_u32 s6, s6, 0x40080
	v_lshl_add_u64 v[226:227], v[228:229], 0, s[66:67]
	s_addc_u32 s7, s7, 0
	s_add_i32 s10, s23, s19
	global_load_lds_dwordx4 v[226:227], off
	s_mov_b32 m0, s10
	v_lshl_add_u64 v[226:227], s[6:7], 0, v[130:131]
	global_load_lds_dwordx4 v[226:227], off
	s_add_i32 m0, s10, 0x2000
	v_lshl_add_u64 v[226:227], s[6:7], 0, v[132:133]
	global_load_lds_dwordx4 v[226:227], off
	s_mov_b32 m0, s68
	v_lshl_add_u64 v[226:227], v[230:231], 0, s[66:67]
	global_load_lds_dwordx4 v[226:227], off
	s_mov_b32 m0, s69
	v_lshl_add_u64 v[226:227], v[232:233], 0, s[66:67]
	global_load_lds_dwordx4 v[226:227], off
	s_waitcnt vmcnt(8) lgkmcnt(0)
	s_barrier
	s_setprio 1
	v_mfma_f32_16x16x32_bf16 v[60:63], v[138:141], v[174:177], v[60:63]
	v_mfma_f32_16x16x32_bf16 v[56:59], v[150:153], v[174:177], v[56:59]
	v_mfma_f32_16x16x32_bf16 v[48:51], v[138:141], v[182:185], v[48:51]
	v_mfma_f32_16x16x32_bf16 v[40:43], v[150:153], v[182:185], v[40:43]
	v_mfma_f32_16x16x32_bf16 v[32:35], v[138:141], v[190:193], v[32:35]
	v_mfma_f32_16x16x32_bf16 v[24:27], v[150:153], v[190:193], v[24:27]
	v_mfma_f32_16x16x32_bf16 v[12:15], v[138:141], v[218:221], v[12:15]
	v_mfma_f32_16x16x32_bf16 v[8:11], v[150:153], v[218:221], v[8:11]
	v_mfma_f32_16x16x32_bf16 v[60:63], v[146:149], v[178:181], v[60:63]
	v_mfma_f32_16x16x32_bf16 v[56:59], v[154:157], v[178:181], v[56:59]
	v_mfma_f32_16x16x32_bf16 v[48:51], v[146:149], v[186:189], v[48:51]
	v_mfma_f32_16x16x32_bf16 v[40:43], v[154:157], v[186:189], v[40:43]
	v_mfma_f32_16x16x32_bf16 v[32:35], v[146:149], v[214:217], v[32:35]
	v_mfma_f32_16x16x32_bf16 v[24:27], v[154:157], v[214:217], v[24:27]
	v_mfma_f32_16x16x32_bf16 v[12:15], v[146:149], v[222:225], v[12:15]
	v_mfma_f32_16x16x32_bf16 v[8:11], v[154:157], v[222:225], v[8:11]
	s_setprio 0
	s_setprio 1
	v_mfma_f32_16x16x32_bf16 v[52:55], v[158:161], v[174:177], v[52:55]
	v_mfma_f32_16x16x32_bf16 v[44:47], v[166:169], v[174:177], v[44:47]
	v_mfma_f32_16x16x32_bf16 v[36:39], v[158:161], v[182:185], v[36:39]
	v_mfma_f32_16x16x32_bf16 v[28:31], v[166:169], v[182:185], v[28:31]
	v_mfma_f32_16x16x32_bf16 v[20:23], v[158:161], v[190:193], v[20:23]
	v_mfma_f32_16x16x32_bf16 v[16:19], v[166:169], v[190:193], v[16:19]
	v_mfma_f32_16x16x32_bf16 v[4:7], v[158:161], v[218:221], v[4:7]
	v_mfma_f32_16x16x32_bf16 v[0:3], v[166:169], v[218:221], v[0:3]
	v_mfma_f32_16x16x32_bf16 v[52:55], v[162:165], v[178:181], v[52:55]
	v_mfma_f32_16x16x32_bf16 v[44:47], v[170:173], v[178:181], v[44:47]
	v_mfma_f32_16x16x32_bf16 v[36:39], v[162:165], v[186:189], v[36:39]
	v_mfma_f32_16x16x32_bf16 v[28:31], v[170:173], v[186:189], v[28:31]
	v_mfma_f32_16x16x32_bf16 v[20:23], v[162:165], v[214:217], v[20:23]
	v_mfma_f32_16x16x32_bf16 v[16:19], v[170:173], v[214:217], v[16:19]
	v_mfma_f32_16x16x32_bf16 v[4:7], v[162:165], v[222:225], v[4:7]
	v_mfma_f32_16x16x32_bf16 v[0:3], v[170:173], v[222:225], v[0:3]
	s_setprio 0
	s_barrier
	s_add_i32 s21, s21, 2
	s_add_u32 s77, s77, 0x100
	s_addc_u32 s20, s20, 0
	s_add_u32 s88, s88, 0x100
	s_addc_u32 s89, s89, 0
	s_cmp_gt_u32 s21, 13
	s_cbranch_scc0 .LBB0_807
	s_and_b64 vcc, exec, s[16:17]
	s_cbranch_vccz .LBB0_810
	s_barrier

; #define PG8_STAGE(bufoff, gbase, voff) do { _Pragma("unroll") for (int _i = 0; _i < 2; ++_i) \
;         __builtin_amdgcn_global_load_lds((const unsigned*)((const char*)(gbase) + (voff)[_i]), (LAS unsigned*)(lds + (bufoff) + ldsw + _i * 8192), 16, 0, 0); } while (0)
; #define PG8_LDA(dst, b, h) do { _Pragma("unroll") for (int m = 0; m < 4; ++m) _Pragma("unroll") for (int k = 0; k < 2; ++k) dst[m][k] = *(const LAS bf16x8*)(lds + PG8_SA(b, h) + aoff + m * 2048 + k * 1024); } while (0)
; #define PG8_LDB(dst, b, h) do { _Pragma("unroll") for (int n = 0; n < 2; ++n) _Pragma("unroll") for (int k = 0; k < 2; ++k) dst[n][k] = *(const LAS bf16x8*)(lds + PG8_SB(b, h) + boff + n * 2048 + k * 1024); } while (0)
; #define PG8_MMA(ai, bj, At, Bt) do { __builtin_amdgcn_s_setprio(1); _Pragma("unroll") for (int m = 0; m < 4; ++m) _Pragma("unroll") for (int n = 0; n < 2; ++n) _Pragma("unroll") for (int k = 0; k < 2; ++k) \
;         acc[ai][bj][m][n] = __builtin_amdgcn_mfma_f32_16x16x32_bf16(Bt[n][k], At[m][k], acc[ai][bj][m][n], 0, 0, 0); __builtin_amdgcn_s_setprio(0); } while (0)
; #define PG8_WAIT_V(n) asm volatile("s_waitcnt vmcnt(" #n ")" ::: "memory")
; #define PG8_WAIT_L(n) asm volatile("s_waitcnt lgkmcnt(" #n ")" ::: "memory")
; #define PG8_BAR __builtin_amdgcn_s_barrier()
; template <class Epi, bool SP2, class Sched>
; __device__ __forceinline__ void gemm_phase(LAS unsigned char* lds, const Gemm g, const Sched& S, const Epi& E) {
;     ...
;             const bool last = (t == nt - 2);
;             const char* a1 = cA + (size_t)(t + 1) * kstep;
;             const char* a2 = last ? nA : cA + (size_t)(t + 2) * kstep; const char* b2 = last ? nB : cB + (size_t)(t + 2) * kstep;
;             const char* a3 = a2 + kstep; const char* b3 = b2 + kstep;
;             if constexpr (Epi::MID) { if (t == (nt >> 1)) E.mid(acc, cur, wr, fr); }
;             if constexpr (SP2) {
;             PG8_LDB(B0, 0, 0); PG8_LDB(B1, 0, 1); PG8_SCHED; PG8_LDA(At, 0, 0); PG8_STAGE(PG8_SA(1, 1), a1 + hstep, voffA);
;             PG8_WAIT_V(8); PG8_WAIT_L(0); PG8_BAR; PG8_MMA(0, 0, At, B0); PG8_MMA(0, 1, At, B1); PG8_BAR; PG8_SCHED;
;             PG8_LDA(At, 0, 1); PG8_STAGE(PG8_SB(0, 0), b2, voffB); PG8_STAGE(PG8_SB(0, 1), b2 + hstepB, voffB); PG8_STAGE(PG8_SA(0, 0), a2, voffA);
;             PG8_WAIT_V(8); PG8_WAIT_L(0); PG8_BAR; PG8_MMA(1, 0, At, B0); PG8_MMA(1, 1, At, B1); PG8_BAR; PG8_SCHED;
.LBB0_955:
	s_add_u32 s6, s92, 0xfffc0080
	s_addc_u32 s7, s93, -1
	s_add_i32 s22, 0, 0x10000
	s_cmp_eq_u32 s21, 12
	s_cselect_b32 s11, s73, s7
	s_cselect_b32 s10, s74, s6
	v_add_u32_e32 v144, s22, v147
	s_cselect_b32 s7, s5, s20
	s_cselect_b32 s6, s75, s76
	s_add_i32 s24, 0, 0x14000
	ds_read_b128 v[140:143], v144
	ds_read_b128 v[150:153], v144 offset:1024
	ds_read_b128 v[154:157], v144 offset:2048
	ds_read_b128 v[158:161], v144 offset:3072
	v_add_u32_e32 v144, s24, v147
	ds_read_b128 v[162:165], v144
	ds_read_b128 v[166:169], v144 offset:1024
	ds_read_b128 v[170:173], v144 offset:2048
	ds_read_b128 v[174:177], v144 offset:3072
	v_lshl_add_u64 v[144:145], s[92:93], 0, v[138:139]
	s_add_i32 m0, s13, 0xc000
	ds_read_b128 v[178:181], v149
	ds_read_b128 v[182:185], v149 offset:1024
	ds_read_b128 v[186:189], v149 offset:2048
	ds_read_b128 v[190:193], v149 offset:3072
	ds_read_b128 v[214:217], v149 offset:4096
	ds_read_b128 v[218:221], v149 offset:5120
	ds_read_b128 v[222:225], v149 offset:6144
	ds_read_b128 v[226:229], v149 offset:7168
	global_load_lds_dwordx4 v[144:145], off
	s_add_i32 m0, s13, 0xe000
	v_lshl_add_u64 v[144:145], s[92:93], 0, v[136:137]
	global_load_lds_dwordx4 v[144:145], off
	s_waitcnt vmcnt(8) lgkmcnt(0)
	s_barrier
	s_setprio 1
	v_mfma_f32_16x16x32_bf16 v[126:129], v[140:143], v[178:181], v[126:129]
	v_mfma_f32_16x16x32_bf16 v[122:125], v[154:157], v[178:181], v[122:125]
	v_mfma_f32_16x16x32_bf16 v[110:113], v[140:143], v[186:189], v[110:113]
	v_mfma_f32_16x16x32_bf16 v[106:109], v[154:157], v[186:189], v[106:109]
	v_mfma_f32_16x16x32_bf16 v[94:97], v[140:143], v[214:217], v[94:97]
	v_mfma_f32_16x16x32_bf16 v[90:93], v[154:157], v[214:217], v[90:93]
	v_mfma_f32_16x16x32_bf16 v[78:81], v[140:143], v[222:225], v[78:81]
	v_mfma_f32_16x16x32_bf16 v[74:77], v[154:157], v[222:225], v[74:77]
	v_mfma_f32_16x16x32_bf16 v[126:129], v[150:153], v[182:185], v[126:129]
	v_mfma_f32_16x16x32_bf16 v[122:125], v[158:161], v[182:185], v[122:125]
	v_mfma_f32_16x16x32_bf16 v[110:113], v[150:153], v[190:193], v[110:113]
	v_mfma_f32_16x16x32_bf16 v[106:109], v[158:161], v[190:193], v[106:109]
	v_mfma_f32_16x16x32_bf16 v[94:97], v[150:153], v[218:221], v[94:97]
	v_mfma_f32_16x16x32_bf16 v[90:93], v[158:161], v[218:221], v[90:93]
	v_mfma_f32_16x16x32_bf16 v[78:81], v[150:153], v[226:229], v[78:81]
	v_mfma_f32_16x16x32_bf16 v[74:77], v[158:161], v[226:229], v[74:77]
	s_setprio 0
	s_setprio 1
	v_mfma_f32_16x16x32_bf16 v[118:121], v[162:165], v[178:181], v[118:121]
	v_mfma_f32_16x16x32_bf16 v[114:117], v[170:173], v[178:181], v[114:117]
	v_mfma_f32_16x16x32_bf16 v[102:105], v[162:165], v[186:189], v[102:105]
	v_mfma_f32_16x16x32_bf16 v[98:101], v[170:173], v[186:189], v[98:101]
	v_mfma_f32_16x16x32_bf16 v[86:89], v[162:165], v[214:217], v[86:89]
	v_mfma_f32_16x16x32_bf16 v[82:85], v[170:173], v[214:217], v[82:85]
	v_mfma_f32_16x16x32_bf16 v[70:73], v[162:165], v[222:225], v[70:73]
	v_mfma_f32_16x16x32_bf16 v[66:69], v[170:173], v[222:225], v[66:69]
	v_mfma_f32_16x16x32_bf16 v[118:121], v[166:169], v[182:185], v[118:121]
	v_mfma_f32_16x16x32_bf16 v[114:117], v[174:177], v[182:185], v[114:117]
	v_mfma_f32_16x16x32_bf16 v[102:105], v[166:169], v[190:193], v[102:105]
	v_mfma_f32_16x16x32_bf16 v[98:101], v[174:177], v[190:193], v[98:101]
	v_mfma_f32_16x16x32_bf16 v[86:89], v[166:169], v[218:221], v[86:89]
	v_mfma_f32_16x16x32_bf16 v[82:85], v[174:177], v[218:221], v[82:85]
	v_mfma_f32_16x16x32_bf16 v[70:73], v[166:169], v[226:229], v[70:73]
	v_mfma_f32_16x16x32_bf16 v[66:69], v[174:177], v[226:229], v[66:69]
	s_setprio 0
	s_barrier
	s_add_i32 s22, s22, s12
	v_lshl_add_u64 v[144:145], s[6:7], 0, v[64:65]
	s_mov_b32 m0, s22
	ds_read_b128 v[178:181], v149 offset:16384
	ds_read_b128 v[182:185], v149 offset:17408
	ds_read_b128 v[186:189], v149 offset:18432
	ds_read_b128 v[190:193], v149 offset:19456
	ds_read_b128 v[214:217], v149 offset:20480
	ds_read_b128 v[218:221], v149 offset:21504
	ds_read_b128 v[222:225], v149 offset:22528
	ds_read_b128 v[226:229], v149 offset:23552
	global_load_lds_dwordx4 v[144:145], off
	s_add_i32 m0, s22, 0x2000
	s_add_u32 s22, s6, 0x40000
	v_lshl_add_u64 v[230:231], s[6:7], 0, v[134:135]
	s_addc_u32 s23, s7, 0
	s_add_i32 s24, s24, s12
	global_load_lds_dwordx4 v[230:231], off
	v_lshl_add_u64 v[232:233], s[22:23], 0, v[64:65]
	s_mov_b32 m0, s24
	v_lshl_add_u64 v[234:235], s[10:11], 0, v[132:133]
	global_load_lds_dwordx4 v[232:233], off
	s_add_i32 m0, s24, 0x2000
	v_lshl_add_u64 v[232:233], s[22:23], 0, v[134:135]
	global_load_lds_dwordx4 v[232:233], off
	s_mov_b32 m0, s13
	v_lshl_add_u64 v[232:233], s[10:11], 0, v[130:131]
	global_load_lds_dwordx4 v[232:233], off
	s_mov_b32 m0, s14
	s_nop 0
	global_load_lds_dwordx4 v[234:235], off
	s_waitcnt vmcnt(8) lgkmcnt(0)
	s_barrier
; #define PG8_STAGE(bufoff, gbase, voff) do { _Pragma("unroll") for (int _i = 0; _i < 2; ++_i) \
;         __builtin_amdgcn_global_load_lds((const unsigned*)((const char*)(gbase) + (voff)[_i]), (LAS unsigned*)(lds + (bufoff) + ldsw + _i * 8192), 16, 0, 0); } while (0)
; #define PG8_LDA(dst, b, h) do { _Pragma("unroll") for (int m = 0; m < 4; ++m) _Pragma("unroll") for (int k = 0; k < 2; ++k) dst[m][k] = *(const LAS bf16x8*)(lds + PG8_SA(b, h) + aoff + m * 2048 + k * 1024); } while (0)
; #define PG8_LDB(dst, b, h) do { _Pragma("unroll") for (int n = 0; n < 2; ++n) _Pragma("unroll") for (int k = 0; k < 2; ++k) dst[n][k] = *(const LAS bf16x8*)(lds + PG8_SB(b, h) + boff + n * 2048 + k * 1024); } while (0)
; #define PG8_MMA(ai, bj, At, Bt) do { __builtin_amdgcn_s_setprio(1); _Pragma("unroll") for (int m = 0; m < 4; ++m) _Pragma("unroll") for (int n = 0; n < 2; ++n) _Pragma("unroll") for (int k = 0; k < 2; ++k) \
;         acc[ai][bj][m][n] = __builtin_amdgcn_mfma_f32_16x16x32_bf16(Bt[n][k], At[m][k], acc[ai][bj][m][n], 0, 0, 0); __builtin_amdgcn_s_setprio(0); } while (0)
; #define PG8_WAIT_V(n) asm volatile("s_waitcnt vmcnt(" #n ")" ::: "memory")
; #define PG8_WAIT_L(n) asm volatile("s_waitcnt lgkmcnt(" #n ")" ::: "memory")
; #define PG8_BAR __builtin_amdgcn_s_barrier()
; #define PG8_SCHED __builtin_amdgcn_sched_barrier(0)
; template <class Epi, bool SP2, class Sched>
; __device__ __forceinline__ void gemm_phase(LAS unsigned char* lds, const Gemm g, const Sched& S, const Epi& E) {
;     ...
;             PG8_WAIT_V(8); PG8_WAIT_L(0); PG8_BAR; PG8_MMA(1, 0, At, B0); PG8_MMA(1, 1, At, B1); PG8_BAR; PG8_SCHED;
;             PG8_LDB(B0, 1, 0); PG8_LDB(B1, 1, 1); PG8_SCHED; PG8_LDA(At, 1, 0); PG8_STAGE(PG8_SA(0, 1), a2 + hstep, voffA);
;             PG8_WAIT_V(8); PG8_WAIT_L(0); PG8_BAR; PG8_MMA(0, 0, At, B0); PG8_MMA(0, 1, At, B1); PG8_BAR; PG8_SCHED;
	s_setprio 1
	v_mfma_f32_16x16x32_bf16 v[60:63], v[140:143], v[178:181], v[60:63]
	v_mfma_f32_16x16x32_bf16 v[56:59], v[154:157], v[178:181], v[56:59]
	v_mfma_f32_16x16x32_bf16 v[44:47], v[140:143], v[186:189], v[44:47]
	v_mfma_f32_16x16x32_bf16 v[40:43], v[154:157], v[186:189], v[40:43]
	v_mfma_f32_16x16x32_bf16 v[28:31], v[140:143], v[214:217], v[28:31]
	v_mfma_f32_16x16x32_bf16 v[24:27], v[154:157], v[214:217], v[24:27]
	v_mfma_f32_16x16x32_bf16 v[12:15], v[140:143], v[222:225], v[12:15]
	v_mfma_f32_16x16x32_bf16 v[8:11], v[154:157], v[222:225], v[8:11]
	v_mfma_f32_16x16x32_bf16 v[60:63], v[150:153], v[182:185], v[60:63]
	v_mfma_f32_16x16x32_bf16 v[56:59], v[158:161], v[182:185], v[56:59]
	v_mfma_f32_16x16x32_bf16 v[44:47], v[150:153], v[190:193], v[44:47]
	v_mfma_f32_16x16x32_bf16 v[40:43], v[158:161], v[190:193], v[40:43]
	v_mfma_f32_16x16x32_bf16 v[28:31], v[150:153], v[218:221], v[28:31]
	v_mfma_f32_16x16x32_bf16 v[24:27], v[158:161], v[218:221], v[24:27]
	v_mfma_f32_16x16x32_bf16 v[12:15], v[150:153], v[226:229], v[12:15]
	v_mfma_f32_16x16x32_bf16 v[8:11], v[158:161], v[226:229], v[8:11]
	s_setprio 0
	s_setprio 1
	v_mfma_f32_16x16x32_bf16 v[52:55], v[162:165], v[178:181], v[52:55]
	v_mfma_f32_16x16x32_bf16 v[48:51], v[170:173], v[178:181], v[48:51]
	v_mfma_f32_16x16x32_bf16 v[36:39], v[162:165], v[186:189], v[36:39]
	v_mfma_f32_16x16x32_bf16 v[32:35], v[170:173], v[186:189], v[32:35]
	v_mfma_f32_16x16x32_bf16 v[20:23], v[162:165], v[214:217], v[20:23]
	v_mfma_f32_16x16x32_bf16 v[16:19], v[170:173], v[214:217], v[16:19]
	v_mfma_f32_16x16x32_bf16 v[4:7], v[162:165], v[222:225], v[4:7]
	v_mfma_f32_16x16x32_bf16 v[0:3], v[170:173], v[222:225], v[0:3]
	v_mfma_f32_16x16x32_bf16 v[52:55], v[166:169], v[182:185], v[52:55]
	v_mfma_f32_16x16x32_bf16 v[48:51], v[174:177], v[182:185], v[48:51]
	v_mfma_f32_16x16x32_bf16 v[36:39], v[166:169], v[190:193], v[36:39]
	v_mfma_f32_16x16x32_bf16 v[32:35], v[174:177], v[190:193], v[32:35]
	v_mfma_f32_16x16x32_bf16 v[20:23], v[166:169], v[218:221], v[20:23]
	v_mfma_f32_16x16x32_bf16 v[16:19], v[174:177], v[218:221], v[16:19]
	v_mfma_f32_16x16x32_bf16 v[4:7], v[166:169], v[226:229], v[4:7]
	v_mfma_f32_16x16x32_bf16 v[0:3], v[174:177], v[226:229], v[0:3]
	s_setprio 0
	s_barrier
	s_add_i32 s22, 0, 0x18000
	s_add_i32 s23, 0, 0x1c000
	v_add_u32_e32 v158, s22, v147
	v_add_u32_e32 v174, s23, v147
	ds_read_b128 v[140:143], v158
	ds_read_b128 v[150:153], v158 offset:1024
	ds_read_b128 v[154:157], v158 offset:2048
	ds_read_b128 v[158:161], v158 offset:3072
	ds_read_b128 v[162:165], v174
	ds_read_b128 v[166:169], v174 offset:1024
	ds_read_b128 v[170:173], v174 offset:2048
	ds_read_b128 v[174:177], v174 offset:3072
	s_add_u32 s10, s10, 0x40000
	s_addc_u32 s11, s11, 0
	s_mov_b32 m0, s15
	v_lshl_add_u64 v[236:237], s[10:11], 0, v[130:131]
	ds_read_b128 v[178:181], v149 offset:32768
	ds_read_b128 v[182:185], v149 offset:33792
	ds_read_b128 v[186:189], v149 offset:34816
	ds_read_b128 v[190:193], v149 offset:35840
	ds_read_b128 v[214:217], v149 offset:36864
	ds_read_b128 v[218:221], v149 offset:37888
	ds_read_b128 v[222:225], v149 offset:38912
	ds_read_b128 v[226:229], v149 offset:39936
	global_load_lds_dwordx4 v[236:237], off
	s_mov_b32 m0, s17
	v_lshl_add_u64 v[236:237], s[10:11], 0, v[132:133]
	global_load_lds_dwordx4 v[236:237], off
	s_waitcnt vmcnt(8) lgkmcnt(0)
	s_barrier
	s_setprio 1
	v_mfma_f32_16x16x32_bf16 v[126:129], v[140:143], v[178:181], v[126:129]
	v_mfma_f32_16x16x32_bf16 v[122:125], v[154:157], v[178:181], v[122:125]
	v_mfma_f32_16x16x32_bf16 v[110:113], v[140:143], v[186:189], v[110:113]
	v_mfma_f32_16x16x32_bf16 v[106:109], v[154:157], v[186:189], v[106:109]
	v_mfma_f32_16x16x32_bf16 v[94:97], v[140:143], v[214:217], v[94:97]
	v_mfma_f32_16x16x32_bf16 v[90:93], v[154:157], v[214:217], v[90:93]
	v_mfma_f32_16x16x32_bf16 v[78:81], v[140:143], v[222:225], v[78:81]
	v_mfma_f32_16x16x32_bf16 v[74:77], v[154:157], v[222:225], v[74:77]
	v_mfma_f32_16x16x32_bf16 v[126:129], v[150:153], v[182:185], v[126:129]
	v_mfma_f32_16x16x32_bf16 v[122:125], v[158:161], v[182:185], v[122:125]
	v_mfma_f32_16x16x32_bf16 v[110:113], v[150:153], v[190:193], v[110:113]
	v_mfma_f32_16x16x32_bf16 v[106:109], v[158:161], v[190:193], v[106:109]
	v_mfma_f32_16x16x32_bf16 v[94:97], v[150:153], v[218:221], v[94:97]
	v_mfma_f32_16x16x32_bf16 v[90:93], v[158:161], v[218:221], v[90:93]
	v_mfma_f32_16x16x32_bf16 v[78:81], v[150:153], v[226:229], v[78:81]
	v_mfma_f32_16x16x32_bf16 v[74:77], v[158:161], v[226:229], v[74:77]
	s_setprio 0
	s_setprio 1
	v_mfma_f32_16x16x32_bf16 v[118:121], v[162:165], v[178:181], v[118:121]
	v_mfma_f32_16x16x32_bf16 v[114:117], v[170:173], v[178:181], v[114:117]
	v_mfma_f32_16x16x32_bf16 v[102:105], v[162:165], v[186:189], v[102:105]
	v_mfma_f32_16x16x32_bf16 v[98:101], v[170:173], v[186:189], v[98:101]
	v_mfma_f32_16x16x32_bf16 v[86:89], v[162:165], v[214:217], v[86:89]
	v_mfma_f32_16x16x32_bf16 v[82:85], v[170:173], v[214:217], v[82:85]
	v_mfma_f32_16x16x32_bf16 v[70:73], v[162:165], v[222:225], v[70:73]
	v_mfma_f32_16x16x32_bf16 v[66:69], v[170:173], v[222:225], v[66:69]
	v_mfma_f32_16x16x32_bf16 v[118:121], v[166:169], v[182:185], v[118:121]
	v_mfma_f32_16x16x32_bf16 v[114:117], v[174:177], v[182:185], v[114:117]
	v_mfma_f32_16x16x32_bf16 v[102:105], v[166:169], v[190:193], v[102:105]
	v_mfma_f32_16x16x32_bf16 v[98:101], v[174:177], v[190:193], v[98:101]
	v_mfma_f32_16x16x32_bf16 v[86:89], v[166:169], v[218:221], v[86:89]
	v_mfma_f32_16x16x32_bf16 v[82:85], v[174:177], v[218:221], v[82:85]
	v_mfma_f32_16x16x32_bf16 v[70:73], v[166:169], v[226:229], v[70:73]
	v_mfma_f32_16x16x32_bf16 v[66:69], v[174:177], v[226:229], v[66:69]
	s_setprio 0
	s_barrier
; #define PG8_STAGE(bufoff, gbase, voff) do { _Pragma("unroll") for (int _i = 0; _i < 2; ++_i) \
;         __builtin_amdgcn_global_load_lds((const unsigned*)((const char*)(gbase) + (voff)[_i]), (LAS unsigned*)(lds + (bufoff) + ldsw + _i * 8192), 16, 0, 0); } while (0)
; #define PG8_LDA(dst, b, h) do { _Pragma("unroll") for (int m = 0; m < 4; ++m) _Pragma("unroll") for (int k = 0; k < 2; ++k) dst[m][k] = *(const LAS bf16x8*)(lds + PG8_SA(b, h) + aoff + m * 2048 + k * 1024); } while (0)
; #define PG8_MMA(ai, bj, At, Bt) do { __builtin_amdgcn_s_setprio(1); _Pragma("unroll") for (int m = 0; m < 4; ++m) _Pragma("unroll") for (int n = 0; n < 2; ++n) _Pragma("unroll") for (int k = 0; k < 2; ++k) \
;         acc[ai][bj][m][n] = __builtin_amdgcn_mfma_f32_16x16x32_bf16(Bt[n][k], At[m][k], acc[ai][bj][m][n], 0, 0, 0); __builtin_amdgcn_s_setprio(0); } while (0)
; #define PG8_WAIT_V(n) asm volatile("s_waitcnt vmcnt(" #n ")" ::: "memory")
; #define PG8_WAIT_L(n) asm volatile("s_waitcnt lgkmcnt(" #n ")" ::: "memory")
; #define PG8_BAR __builtin_amdgcn_s_barrier()
; #define PG8_SCHED __builtin_amdgcn_sched_barrier(0)
; template <class Epi, bool SP2, class Sched>
; __device__ __forceinline__ void gemm_phase(LAS unsigned char* lds, const Gemm g, const Sched& S, const Epi& E) {
;     ...
;         for (int t = 0; t < nt; t += 2) {
;             const bool last = (t == nt - 2);
;     ...
;             PG8_LDA(At, 1, 1); PG8_STAGE(PG8_SB(1, 0), b3, voffB); PG8_STAGE(PG8_SB(1, 1), b3 + hstepB, voffB); PG8_STAGE(PG8_SA(1, 0), a3, voffA);
;             PG8_WAIT_V(8); PG8_WAIT_L(0); PG8_BAR; PG8_MMA(1, 0, At, B0); PG8_MMA(1, 1, At, B1); PG8_BAR; PG8_SCHED;
	s_add_i32 s10, s22, s12
	v_lshl_add_u64 v[144:145], v[144:145], 0, s[66:67]
	s_mov_b32 m0, s10
	ds_read_b128 v[178:181], v149 offset:49152
	ds_read_b128 v[182:185], v149 offset:50176
	ds_read_b128 v[186:189], v149 offset:51200
	ds_read_b128 v[190:193], v149 offset:52224
	ds_read_b128 v[214:217], v149 offset:53248
	ds_read_b128 v[218:221], v149 offset:54272
	ds_read_b128 v[222:225], v149 offset:55296
	ds_read_b128 v[226:229], v149 offset:56320
	global_load_lds_dwordx4 v[144:145], off
	s_add_i32 m0, s10, 0x2000
	s_add_u32 s6, s6, 0x40080
	v_lshl_add_u64 v[144:145], v[230:231], 0, s[66:67]
	s_addc_u32 s7, s7, 0
	s_add_i32 s10, s23, s12
	global_load_lds_dwordx4 v[144:145], off
	s_mov_b32 m0, s10
	v_lshl_add_u64 v[144:145], s[6:7], 0, v[64:65]
	global_load_lds_dwordx4 v[144:145], off
	s_add_i32 m0, s10, 0x2000
	v_lshl_add_u64 v[144:145], s[6:7], 0, v[134:135]
	global_load_lds_dwordx4 v[144:145], off
	s_mov_b32 m0, s18
	v_lshl_add_u64 v[144:145], v[232:233], 0, s[66:67]
	global_load_lds_dwordx4 v[144:145], off
	s_mov_b32 m0, s19
	v_lshl_add_u64 v[144:145], v[234:235], 0, s[66:67]
	global_load_lds_dwordx4 v[144:145], off
	s_waitcnt vmcnt(8) lgkmcnt(0)
	s_barrier
	s_setprio 1
	v_mfma_f32_16x16x32_bf16 v[60:63], v[140:143], v[178:181], v[60:63]
	v_mfma_f32_16x16x32_bf16 v[56:59], v[154:157], v[178:181], v[56:59]
	v_mfma_f32_16x16x32_bf16 v[44:47], v[140:143], v[186:189], v[44:47]
	v_mfma_f32_16x16x32_bf16 v[40:43], v[154:157], v[186:189], v[40:43]
	v_mfma_f32_16x16x32_bf16 v[28:31], v[140:143], v[214:217], v[28:31]
	v_mfma_f32_16x16x32_bf16 v[24:27], v[154:157], v[214:217], v[24:27]
	v_mfma_f32_16x16x32_bf16 v[12:15], v[140:143], v[222:225], v[12:15]
	v_mfma_f32_16x16x32_bf16 v[8:11], v[154:157], v[222:225], v[8:11]
	v_mfma_f32_16x16x32_bf16 v[60:63], v[150:153], v[182:185], v[60:63]
	v_mfma_f32_16x16x32_bf16 v[56:59], v[158:161], v[182:185], v[56:59]
	v_mfma_f32_16x16x32_bf16 v[44:47], v[150:153], v[190:193], v[44:47]
	v_mfma_f32_16x16x32_bf16 v[40:43], v[158:161], v[190:193], v[40:43]
	v_mfma_f32_16x16x32_bf16 v[28:31], v[150:153], v[218:221], v[28:31]
	v_mfma_f32_16x16x32_bf16 v[24:27], v[158:161], v[218:221], v[24:27]
	v_mfma_f32_16x16x32_bf16 v[12:15], v[150:153], v[226:229], v[12:15]
	v_mfma_f32_16x16x32_bf16 v[8:11], v[158:161], v[226:229], v[8:11]
	s_setprio 0
	s_setprio 1
	v_mfma_f32_16x16x32_bf16 v[52:55], v[162:165], v[178:181], v[52:55]
	v_mfma_f32_16x16x32_bf16 v[48:51], v[170:173], v[178:181], v[48:51]
	v_mfma_f32_16x16x32_bf16 v[36:39], v[162:165], v[186:189], v[36:39]
	v_mfma_f32_16x16x32_bf16 v[32:35], v[170:173], v[186:189], v[32:35]
	v_mfma_f32_16x16x32_bf16 v[20:23], v[162:165], v[214:217], v[20:23]
	v_mfma_f32_16x16x32_bf16 v[16:19], v[170:173], v[214:217], v[16:19]
	v_mfma_f32_16x16x32_bf16 v[4:7], v[162:165], v[222:225], v[4:7]
	v_mfma_f32_16x16x32_bf16 v[0:3], v[170:173], v[222:225], v[0:3]
	v_mfma_f32_16x16x32_bf16 v[52:55], v[166:169], v[182:185], v[52:55]
	v_mfma_f32_16x16x32_bf16 v[48:51], v[174:177], v[182:185], v[48:51]
	v_mfma_f32_16x16x32_bf16 v[36:39], v[166:169], v[190:193], v[36:39]
	v_mfma_f32_16x16x32_bf16 v[32:35], v[174:177], v[190:193], v[32:35]
	v_mfma_f32_16x16x32_bf16 v[20:23], v[166:169], v[218:221], v[20:23]
	v_mfma_f32_16x16x32_bf16 v[16:19], v[174:177], v[218:221], v[16:19]
	v_mfma_f32_16x16x32_bf16 v[4:7], v[166:169], v[226:229], v[4:7]
	v_mfma_f32_16x16x32_bf16 v[0:3], v[174:177], v[226:229], v[0:3]
	s_setprio 0
	s_barrier
	s_add_i32 s21, s21, 2
	s_add_u32 s76, s76, 0x100
	s_addc_u32 s20, s20, 0
	s_add_u32 s92, s92, 0x100
	s_addc_u32 s93, s93, 0
	s_cmp_gt_u32 s21, 13
	s_cbranch_scc0 .LBB0_955
	s_and_b64 vcc, exec, s[60:61]
	s_cbranch_vccz .LBB0_958
	s_barrier

; #define PG8_STAGE(bufoff, gbase, voff) do { _Pragma("unroll") for (int _i = 0; _i < 2; ++_i) \
;         __builtin_amdgcn_global_load_lds((const unsigned*)((const char*)(gbase) + (voff)[_i]), (LAS unsigned*)(lds + (bufoff) + ldsw + _i * 8192), 16, 0, 0); } while (0)
; #define PG8_LDA(dst, b, h) do { _Pragma("unroll") for (int m = 0; m < 4; ++m) _Pragma("unroll") for (int k = 0; k < 2; ++k) dst[m][k] = *(const LAS bf16x8*)(lds + PG8_SA(b, h) + aoff + m * 2048 + k * 1024); } while (0)
; #define PG8_LDB(dst, b, h) do { _Pragma("unroll") for (int n = 0; n < 2; ++n) _Pragma("unroll") for (int k = 0; k < 2; ++k) dst[n][k] = *(const LAS bf16x8*)(lds + PG8_SB(b, h) + boff + n * 2048 + k * 1024); } while (0)
; #define PG8_MMA(ai, bj, At, Bt) do { __builtin_amdgcn_s_setprio(1); _Pragma("unroll") for (int m = 0; m < 4; ++m) _Pragma("unroll") for (int n = 0; n < 2; ++n) _Pragma("unroll") for (int k = 0; k < 2; ++k) \
;         acc[ai][bj][m][n] = __builtin_amdgcn_mfma_f32_16x16x32_bf16(Bt[n][k], At[m][k], acc[ai][bj][m][n], 0, 0, 0); __builtin_amdgcn_s_setprio(0); } while (0)
; #define PG8_WAIT_V(n) asm volatile("s_waitcnt vmcnt(" #n ")" ::: "memory")
; #define PG8_WAIT_L(n) asm volatile("s_waitcnt lgkmcnt(" #n ")" ::: "memory")
; #define PG8_BAR __builtin_amdgcn_s_barrier()
; template <class Epi, bool SP2, class Sched>
; __device__ __forceinline__ void gemm_phase(LAS unsigned char* lds, const Gemm g, const Sched& S, const Epi& E) {
;     ...
;             const bool last = (t == nt - 2);
;             const char* a1 = cA + (size_t)(t + 1) * kstep;
;             const char* a2 = last ? nA : cA + (size_t)(t + 2) * kstep; const char* b2 = last ? nB : cB + (size_t)(t + 2) * kstep;
;             const char* a3 = a2 + kstep; const char* b3 = b2 + kstep;
;             if constexpr (Epi::MID) { if (t == (nt >> 1)) E.mid(acc, cur, wr, fr); }
;             if constexpr (SP2) {
;             PG8_LDB(B0, 0, 0); PG8_LDB(B1, 0, 1); PG8_SCHED; PG8_LDA(At, 0, 0); PG8_STAGE(PG8_SA(1, 1), a1 + hstep, voffA);
;             PG8_WAIT_V(8); PG8_WAIT_L(0); PG8_BAR; PG8_MMA(0, 0, At, B0); PG8_MMA(0, 1, At, B1); PG8_BAR; PG8_SCHED;
;             PG8_LDA(At, 0, 1); PG8_STAGE(PG8_SB(0, 0), b2, voffB); PG8_STAGE(PG8_SB(0, 1), b2 + hstepB, voffB); PG8_STAGE(PG8_SA(0, 0), a2, voffA);
;             PG8_WAIT_V(8); PG8_WAIT_L(0); PG8_BAR; PG8_MMA(1, 0, At, B0); PG8_MMA(1, 1, At, B1); PG8_BAR; PG8_SCHED;
.LBB0_1039:
	s_add_u32 s6, s16, 0xfffc0080
	s_addc_u32 s7, s17, -1
	s_add_i32 s19, 0, 0x10000
	s_cmp_eq_u32 s18, 12
	s_cselect_b32 s11, s8, s7
	s_cselect_b32 s10, s9, s6
	s_cselect_b32 s7, s12, s15
	s_cselect_b32 s6, s13, s14
	s_add_i32 s22, 0, 0x14000
	v_add_u32_e32 v156, s19, v145
	v_add_u32_e32 v172, s22, v145
	ds_read_b128 v[140:143], v156
	ds_read_b128 v[148:151], v156 offset:1024
	ds_read_b128 v[152:155], v156 offset:2048
	ds_read_b128 v[156:159], v156 offset:3072
	ds_read_b128 v[160:163], v172
	ds_read_b128 v[164:167], v172 offset:1024
	ds_read_b128 v[168:171], v172 offset:2048
	ds_read_b128 v[172:175], v172 offset:3072
	v_lshl_add_u64 v[192:193], s[16:17], 0, v[138:139]
	s_add_i32 m0, s83, 0xc000
	ds_read_b128 v[176:179], v147
	ds_read_b128 v[180:183], v147 offset:1024
	ds_read_b128 v[184:187], v147 offset:2048
	ds_read_b128 v[188:191], v147 offset:3072
	ds_read_b128 v[214:217], v147 offset:4096
	ds_read_b128 v[218:221], v147 offset:5120
	ds_read_b128 v[222:225], v147 offset:6144
	ds_read_b128 v[226:229], v147 offset:7168
	global_load_lds_dwordx4 v[192:193], off
	s_add_i32 m0, s83, 0xe000
	v_lshl_add_u64 v[192:193], s[16:17], 0, v[136:137]
	global_load_lds_dwordx4 v[192:193], off
	s_waitcnt vmcnt(8) lgkmcnt(0)
	s_barrier
	s_setprio 1
	v_mfma_f32_16x16x32_bf16 v[126:129], v[140:143], v[176:179], v[126:129]
	v_mfma_f32_16x16x32_bf16 v[122:125], v[152:155], v[176:179], v[122:125]
	v_mfma_f32_16x16x32_bf16 v[110:113], v[140:143], v[184:187], v[110:113]
	v_mfma_f32_16x16x32_bf16 v[106:109], v[152:155], v[184:187], v[106:109]
	v_mfma_f32_16x16x32_bf16 v[94:97], v[140:143], v[214:217], v[94:97]
	v_mfma_f32_16x16x32_bf16 v[90:93], v[152:155], v[214:217], v[90:93]
	v_mfma_f32_16x16x32_bf16 v[78:81], v[140:143], v[222:225], v[78:81]
	v_mfma_f32_16x16x32_bf16 v[74:77], v[152:155], v[222:225], v[74:77]
	v_mfma_f32_16x16x32_bf16 v[126:129], v[148:151], v[180:183], v[126:129]
	v_mfma_f32_16x16x32_bf16 v[122:125], v[156:159], v[180:183], v[122:125]
	v_mfma_f32_16x16x32_bf16 v[110:113], v[148:151], v[188:191], v[110:113]
	v_mfma_f32_16x16x32_bf16 v[106:109], v[156:159], v[188:191], v[106:109]
	v_mfma_f32_16x16x32_bf16 v[94:97], v[148:151], v[218:221], v[94:97]
	v_mfma_f32_16x16x32_bf16 v[90:93], v[156:159], v[218:221], v[90:93]
	v_mfma_f32_16x16x32_bf16 v[78:81], v[148:151], v[226:229], v[78:81]
	v_mfma_f32_16x16x32_bf16 v[74:77], v[156:159], v[226:229], v[74:77]
	s_setprio 0
	s_setprio 1
	v_mfma_f32_16x16x32_bf16 v[118:121], v[160:163], v[176:179], v[118:121]
	v_mfma_f32_16x16x32_bf16 v[114:117], v[168:171], v[176:179], v[114:117]
	v_mfma_f32_16x16x32_bf16 v[102:105], v[160:163], v[184:187], v[102:105]
	v_mfma_f32_16x16x32_bf16 v[98:101], v[168:171], v[184:187], v[98:101]
	v_mfma_f32_16x16x32_bf16 v[86:89], v[160:163], v[214:217], v[86:89]
	v_mfma_f32_16x16x32_bf16 v[82:85], v[168:171], v[214:217], v[82:85]
	v_mfma_f32_16x16x32_bf16 v[70:73], v[160:163], v[222:225], v[70:73]
	v_mfma_f32_16x16x32_bf16 v[66:69], v[168:171], v[222:225], v[66:69]
	v_mfma_f32_16x16x32_bf16 v[118:121], v[164:167], v[180:183], v[118:121]
	v_mfma_f32_16x16x32_bf16 v[114:117], v[172:175], v[180:183], v[114:117]
	v_mfma_f32_16x16x32_bf16 v[102:105], v[164:167], v[188:191], v[102:105]
	v_mfma_f32_16x16x32_bf16 v[98:101], v[172:175], v[188:191], v[98:101]
	v_mfma_f32_16x16x32_bf16 v[86:89], v[164:167], v[218:221], v[86:89]
	v_mfma_f32_16x16x32_bf16 v[82:85], v[172:175], v[218:221], v[82:85]
	v_mfma_f32_16x16x32_bf16 v[70:73], v[164:167], v[226:229], v[70:73]
	v_mfma_f32_16x16x32_bf16 v[66:69], v[172:175], v[226:229], v[66:69]
	s_setprio 0
	s_barrier
	s_add_i32 s19, s19, s79
	v_lshl_add_u64 v[192:193], s[6:7], 0, v[64:65]
	s_mov_b32 m0, s19
	ds_read_b128 v[176:179], v147 offset:16384
	ds_read_b128 v[180:183], v147 offset:17408
	ds_read_b128 v[184:187], v147 offset:18432
	ds_read_b128 v[188:191], v147 offset:19456
	ds_read_b128 v[214:217], v147 offset:20480
	ds_read_b128 v[218:221], v147 offset:21504
	ds_read_b128 v[222:225], v147 offset:22528
	ds_read_b128 v[226:229], v147 offset:23552
	global_load_lds_dwordx4 v[192:193], off
	s_add_i32 m0, s19, 0x2000
	s_add_u32 s20, s6, 0x40000
	v_lshl_add_u64 v[230:231], s[6:7], 0, v[130:131]
	s_addc_u32 s21, s7, 0
	s_add_i32 s19, s22, s79
	global_load_lds_dwordx4 v[230:231], off
	v_lshl_add_u64 v[232:233], s[20:21], 0, v[64:65]
	s_mov_b32 m0, s19
	v_lshl_add_u64 v[234:235], s[10:11], 0, v[132:133]
	global_load_lds_dwordx4 v[232:233], off
	s_add_i32 m0, s19, 0x2000
	v_lshl_add_u64 v[232:233], s[20:21], 0, v[130:131]
	global_load_lds_dwordx4 v[232:233], off
	s_mov_b32 m0, s83
	v_lshl_add_u64 v[232:233], s[10:11], 0, v[134:135]
	global_load_lds_dwordx4 v[232:233], off
	s_mov_b32 m0, s90
	s_nop 0
	global_load_lds_dwordx4 v[234:235], off
	s_waitcnt vmcnt(8) lgkmcnt(0)
	s_barrier
; #define PG8_STAGE(bufoff, gbase, voff) do { _Pragma("unroll") for (int _i = 0; _i < 2; ++_i) \
;         __builtin_amdgcn_global_load_lds((const unsigned*)((const char*)(gbase) + (voff)[_i]), (LAS unsigned*)(lds + (bufoff) + ldsw + _i * 8192), 16, 0, 0); } while (0)
; #define PG8_LDA(dst, b, h) do { _Pragma("unroll") for (int m = 0; m < 4; ++m) _Pragma("unroll") for (int k = 0; k < 2; ++k) dst[m][k] = *(const LAS bf16x8*)(lds + PG8_SA(b, h) + aoff + m * 2048 + k * 1024); } while (0)
; #define PG8_LDB(dst, b, h) do { _Pragma("unroll") for (int n = 0; n < 2; ++n) _Pragma("unroll") for (int k = 0; k < 2; ++k) dst[n][k] = *(const LAS bf16x8*)(lds + PG8_SB(b, h) + boff + n * 2048 + k * 1024); } while (0)
; #define PG8_MMA(ai, bj, At, Bt) do { __builtin_amdgcn_s_setprio(1); _Pragma("unroll") for (int m = 0; m < 4; ++m) _Pragma("unroll") for (int n = 0; n < 2; ++n) _Pragma("unroll") for (int k = 0; k < 2; ++k) \
;         acc[ai][bj][m][n] = __builtin_amdgcn_mfma_f32_16x16x32_bf16(Bt[n][k], At[m][k], acc[ai][bj][m][n], 0, 0, 0); __builtin_amdgcn_s_setprio(0); } while (0)
; #define PG8_WAIT_V(n) asm volatile("s_waitcnt vmcnt(" #n ")" ::: "memory")
; #define PG8_WAIT_L(n) asm volatile("s_waitcnt lgkmcnt(" #n ")" ::: "memory")
; #define PG8_BAR __builtin_amdgcn_s_barrier()
; #define PG8_SCHED __builtin_amdgcn_sched_barrier(0)
; template <class Epi, bool SP2, class Sched>
; __device__ __forceinline__ void gemm_phase(LAS unsigned char* lds, const Gemm g, const Sched& S, const Epi& E) {
;     ...
;             PG8_WAIT_V(8); PG8_WAIT_L(0); PG8_BAR; PG8_MMA(1, 0, At, B0); PG8_MMA(1, 1, At, B1); PG8_BAR; PG8_SCHED;
;             PG8_LDB(B0, 1, 0); PG8_LDB(B1, 1, 1); PG8_SCHED; PG8_LDA(At, 1, 0); PG8_STAGE(PG8_SA(0, 1), a2 + hstep, voffA);
;             PG8_WAIT_V(8); PG8_WAIT_L(0); PG8_BAR; PG8_MMA(0, 0, At, B0); PG8_MMA(0, 1, At, B1); PG8_BAR; PG8_SCHED;
	s_setprio 1
	v_mfma_f32_16x16x32_bf16 v[60:63], v[140:143], v[176:179], v[60:63]
	v_mfma_f32_16x16x32_bf16 v[56:59], v[152:155], v[176:179], v[56:59]
	v_mfma_f32_16x16x32_bf16 v[44:47], v[140:143], v[184:187], v[44:47]
	v_mfma_f32_16x16x32_bf16 v[40:43], v[152:155], v[184:187], v[40:43]
	v_mfma_f32_16x16x32_bf16 v[28:31], v[140:143], v[214:217], v[28:31]
	v_mfma_f32_16x16x32_bf16 v[24:27], v[152:155], v[214:217], v[24:27]
	v_mfma_f32_16x16x32_bf16 v[12:15], v[140:143], v[222:225], v[12:15]
	v_mfma_f32_16x16x32_bf16 v[8:11], v[152:155], v[222:225], v[8:11]
	v_mfma_f32_16x16x32_bf16 v[60:63], v[148:151], v[180:183], v[60:63]
	v_mfma_f32_16x16x32_bf16 v[56:59], v[156:159], v[180:183], v[56:59]
	v_mfma_f32_16x16x32_bf16 v[44:47], v[148:151], v[188:191], v[44:47]
	v_mfma_f32_16x16x32_bf16 v[40:43], v[156:159], v[188:191], v[40:43]
	v_mfma_f32_16x16x32_bf16 v[28:31], v[148:151], v[218:221], v[28:31]
	v_mfma_f32_16x16x32_bf16 v[24:27], v[156:159], v[218:221], v[24:27]
	v_mfma_f32_16x16x32_bf16 v[12:15], v[148:151], v[226:229], v[12:15]
	v_mfma_f32_16x16x32_bf16 v[8:11], v[156:159], v[226:229], v[8:11]
	s_setprio 0
	s_setprio 1
	v_mfma_f32_16x16x32_bf16 v[52:55], v[160:163], v[176:179], v[52:55]
	v_mfma_f32_16x16x32_bf16 v[48:51], v[168:171], v[176:179], v[48:51]
	v_mfma_f32_16x16x32_bf16 v[36:39], v[160:163], v[184:187], v[36:39]
	v_mfma_f32_16x16x32_bf16 v[32:35], v[168:171], v[184:187], v[32:35]
	v_mfma_f32_16x16x32_bf16 v[20:23], v[160:163], v[214:217], v[20:23]
	v_mfma_f32_16x16x32_bf16 v[16:19], v[168:171], v[214:217], v[16:19]
	v_mfma_f32_16x16x32_bf16 v[4:7], v[160:163], v[222:225], v[4:7]
	v_mfma_f32_16x16x32_bf16 v[0:3], v[168:171], v[222:225], v[0:3]
	v_mfma_f32_16x16x32_bf16 v[52:55], v[164:167], v[180:183], v[52:55]
	v_mfma_f32_16x16x32_bf16 v[48:51], v[172:175], v[180:183], v[48:51]
	v_mfma_f32_16x16x32_bf16 v[36:39], v[164:167], v[188:191], v[36:39]
	v_mfma_f32_16x16x32_bf16 v[32:35], v[172:175], v[188:191], v[32:35]
	v_mfma_f32_16x16x32_bf16 v[20:23], v[164:167], v[218:221], v[20:23]
	v_mfma_f32_16x16x32_bf16 v[16:19], v[172:175], v[218:221], v[16:19]
	v_mfma_f32_16x16x32_bf16 v[4:7], v[164:167], v[226:229], v[4:7]
	v_mfma_f32_16x16x32_bf16 v[0:3], v[172:175], v[226:229], v[0:3]
	s_setprio 0
	s_barrier
	s_add_i32 s19, 0, 0x18000
	s_add_i32 s20, 0, 0x1c000
	v_add_u32_e32 v156, s19, v145
	v_add_u32_e32 v172, s20, v145
	ds_read_b128 v[140:143], v156
	ds_read_b128 v[148:151], v156 offset:1024
	ds_read_b128 v[152:155], v156 offset:2048
	ds_read_b128 v[156:159], v156 offset:3072
	ds_read_b128 v[160:163], v172
	ds_read_b128 v[164:167], v172 offset:1024
	ds_read_b128 v[168:171], v172 offset:2048
	ds_read_b128 v[172:175], v172 offset:3072
	s_add_u32 s10, s10, 0x40000
	s_addc_u32 s11, s11, 0
	s_mov_b32 m0, s91
	v_lshl_add_u64 v[236:237], s[10:11], 0, v[134:135]
	ds_read_b128 v[176:179], v147 offset:32768
	ds_read_b128 v[180:183], v147 offset:33792
	ds_read_b128 v[184:187], v147 offset:34816
	ds_read_b128 v[188:191], v147 offset:35840
	ds_read_b128 v[214:217], v147 offset:36864
	ds_read_b128 v[218:221], v147 offset:37888
	ds_read_b128 v[222:225], v147 offset:38912
	ds_read_b128 v[226:229], v147 offset:39936
	global_load_lds_dwordx4 v[236:237], off
	s_mov_b32 m0, s92
	v_lshl_add_u64 v[236:237], s[10:11], 0, v[132:133]
	global_load_lds_dwordx4 v[236:237], off
	s_waitcnt vmcnt(8) lgkmcnt(0)
	s_barrier
	s_setprio 1
	v_mfma_f32_16x16x32_bf16 v[126:129], v[140:143], v[176:179], v[126:129]
	v_mfma_f32_16x16x32_bf16 v[122:125], v[152:155], v[176:179], v[122:125]
	v_mfma_f32_16x16x32_bf16 v[110:113], v[140:143], v[184:187], v[110:113]
	v_mfma_f32_16x16x32_bf16 v[106:109], v[152:155], v[184:187], v[106:109]
	v_mfma_f32_16x16x32_bf16 v[94:97], v[140:143], v[214:217], v[94:97]
	v_mfma_f32_16x16x32_bf16 v[90:93], v[152:155], v[214:217], v[90:93]
	v_mfma_f32_16x16x32_bf16 v[78:81], v[140:143], v[222:225], v[78:81]
	v_mfma_f32_16x16x32_bf16 v[74:77], v[152:155], v[222:225], v[74:77]
	v_mfma_f32_16x16x32_bf16 v[126:129], v[148:151], v[180:183], v[126:129]
	v_mfma_f32_16x16x32_bf16 v[122:125], v[156:159], v[180:183], v[122:125]
	v_mfma_f32_16x16x32_bf16 v[110:113], v[148:151], v[188:191], v[110:113]
	v_mfma_f32_16x16x32_bf16 v[106:109], v[156:159], v[188:191], v[106:109]
	v_mfma_f32_16x16x32_bf16 v[94:97], v[148:151], v[218:221], v[94:97]
	v_mfma_f32_16x16x32_bf16 v[90:93], v[156:159], v[218:221], v[90:93]
	v_mfma_f32_16x16x32_bf16 v[78:81], v[148:151], v[226:229], v[78:81]
	v_mfma_f32_16x16x32_bf16 v[74:77], v[156:159], v[226:229], v[74:77]
	s_setprio 0
	s_setprio 1
	v_mfma_f32_16x16x32_bf16 v[118:121], v[160:163], v[176:179], v[118:121]
	v_mfma_f32_16x16x32_bf16 v[114:117], v[168:171], v[176:179], v[114:117]
	v_mfma_f32_16x16x32_bf16 v[102:105], v[160:163], v[184:187], v[102:105]
	v_mfma_f32_16x16x32_bf16 v[98:101], v[168:171], v[184:187], v[98:101]
	v_mfma_f32_16x16x32_bf16 v[86:89], v[160:163], v[214:217], v[86:89]
	v_mfma_f32_16x16x32_bf16 v[82:85], v[168:171], v[214:217], v[82:85]
	v_mfma_f32_16x16x32_bf16 v[70:73], v[160:163], v[222:225], v[70:73]
	v_mfma_f32_16x16x32_bf16 v[66:69], v[168:171], v[222:225], v[66:69]
	v_mfma_f32_16x16x32_bf16 v[118:121], v[164:167], v[180:183], v[118:121]
	v_mfma_f32_16x16x32_bf16 v[114:117], v[172:175], v[180:183], v[114:117]
	v_mfma_f32_16x16x32_bf16 v[102:105], v[164:167], v[188:191], v[102:105]
	v_mfma_f32_16x16x32_bf16 v[98:101], v[172:175], v[188:191], v[98:101]
	v_mfma_f32_16x16x32_bf16 v[86:89], v[164:167], v[218:221], v[86:89]
	v_mfma_f32_16x16x32_bf16 v[82:85], v[172:175], v[218:221], v[82:85]
	v_mfma_f32_16x16x32_bf16 v[70:73], v[164:167], v[226:229], v[70:73]
	v_mfma_f32_16x16x32_bf16 v[66:69], v[172:175], v[226:229], v[66:69]
	s_setprio 0
	s_barrier
; #define PG8_STAGE(bufoff, gbase, voff) do { _Pragma("unroll") for (int _i = 0; _i < 2; ++_i) \
;         __builtin_amdgcn_global_load_lds((const unsigned*)((const char*)(gbase) + (voff)[_i]), (LAS unsigned*)(lds + (bufoff) + ldsw + _i * 8192), 16, 0, 0); } while (0)
; #define PG8_LDA(dst, b, h) do { _Pragma("unroll") for (int m = 0; m < 4; ++m) _Pragma("unroll") for (int k = 0; k < 2; ++k) dst[m][k] = *(const LAS bf16x8*)(lds + PG8_SA(b, h) + aoff + m * 2048 + k * 1024); } while (0)
; #define PG8_MMA(ai, bj, At, Bt) do { __builtin_amdgcn_s_setprio(1); _Pragma("unroll") for (int m = 0; m < 4; ++m) _Pragma("unroll") for (int n = 0; n < 2; ++n) _Pragma("unroll") for (int k = 0; k < 2; ++k) \
;         acc[ai][bj][m][n] = __builtin_amdgcn_mfma_f32_16x16x32_bf16(Bt[n][k], At[m][k], acc[ai][bj][m][n], 0, 0, 0); __builtin_amdgcn_s_setprio(0); } while (0)
; #define PG8_WAIT_V(n) asm volatile("s_waitcnt vmcnt(" #n ")" ::: "memory")
; #define PG8_WAIT_L(n) asm volatile("s_waitcnt lgkmcnt(" #n ")" ::: "memory")
; #define PG8_BAR __builtin_amdgcn_s_barrier()
; #define PG8_SCHED __builtin_amdgcn_sched_barrier(0)
; template <class Epi, bool SP2, class Sched>
; __device__ __forceinline__ void gemm_phase(LAS unsigned char* lds, const Gemm g, const Sched& S, const Epi& E) {
;     ...
;         for (int t = 0; t < nt; t += 2) {
;             const bool last = (t == nt - 2);
;     ...
;             PG8_LDA(At, 1, 1); PG8_STAGE(PG8_SB(1, 0), b3, voffB); PG8_STAGE(PG8_SB(1, 1), b3 + hstepB, voffB); PG8_STAGE(PG8_SA(1, 0), a3, voffA);
;             PG8_WAIT_V(8); PG8_WAIT_L(0); PG8_BAR; PG8_MMA(1, 0, At, B0); PG8_MMA(1, 1, At, B1); PG8_BAR; PG8_SCHED;
	s_add_i32 s10, s19, s79
	v_lshl_add_u64 v[192:193], v[192:193], 0, s[66:67]
	s_mov_b32 m0, s10
	ds_read_b128 v[176:179], v147 offset:49152
	ds_read_b128 v[180:183], v147 offset:50176
	ds_read_b128 v[184:187], v147 offset:51200
	ds_read_b128 v[188:191], v147 offset:52224
	ds_read_b128 v[214:217], v147 offset:53248
	ds_read_b128 v[218:221], v147 offset:54272
	ds_read_b128 v[222:225], v147 offset:55296
	ds_read_b128 v[226:229], v147 offset:56320
	global_load_lds_dwordx4 v[192:193], off
	s_add_i32 m0, s10, 0x2000
	s_add_u32 s6, s6, 0x40080
	v_lshl_add_u64 v[192:193], v[230:231], 0, s[66:67]
	s_addc_u32 s7, s7, 0
	s_add_i32 s10, s20, s79
	global_load_lds_dwordx4 v[192:193], off
	s_mov_b32 m0, s10
	v_lshl_add_u64 v[192:193], s[6:7], 0, v[64:65]
	global_load_lds_dwordx4 v[192:193], off
	s_add_i32 m0, s10, 0x2000
	v_lshl_add_u64 v[192:193], s[6:7], 0, v[130:131]
	global_load_lds_dwordx4 v[192:193], off
	s_mov_b32 m0, s94
	v_lshl_add_u64 v[192:193], v[232:233], 0, s[66:67]
	global_load_lds_dwordx4 v[192:193], off
	s_mov_b32 m0, s95
	v_lshl_add_u64 v[192:193], v[234:235], 0, s[66:67]
	global_load_lds_dwordx4 v[192:193], off
	s_waitcnt vmcnt(8) lgkmcnt(0)
	s_barrier
	s_setprio 1
	v_mfma_f32_16x16x32_bf16 v[60:63], v[140:143], v[176:179], v[60:63]
	v_mfma_f32_16x16x32_bf16 v[56:59], v[152:155], v[176:179], v[56:59]
	v_mfma_f32_16x16x32_bf16 v[44:47], v[140:143], v[184:187], v[44:47]
	v_mfma_f32_16x16x32_bf16 v[40:43], v[152:155], v[184:187], v[40:43]
	v_mfma_f32_16x16x32_bf16 v[28:31], v[140:143], v[214:217], v[28:31]
	v_mfma_f32_16x16x32_bf16 v[24:27], v[152:155], v[214:217], v[24:27]
	v_mfma_f32_16x16x32_bf16 v[12:15], v[140:143], v[222:225], v[12:15]
	v_mfma_f32_16x16x32_bf16 v[8:11], v[152:155], v[222:225], v[8:11]
	v_mfma_f32_16x16x32_bf16 v[60:63], v[148:151], v[180:183], v[60:63]
	v_mfma_f32_16x16x32_bf16 v[56:59], v[156:159], v[180:183], v[56:59]
	v_mfma_f32_16x16x32_bf16 v[44:47], v[148:151], v[188:191], v[44:47]
	v_mfma_f32_16x16x32_bf16 v[40:43], v[156:159], v[188:191], v[40:43]
	v_mfma_f32_16x16x32_bf16 v[28:31], v[148:151], v[218:221], v[28:31]
	v_mfma_f32_16x16x32_bf16 v[24:27], v[156:159], v[218:221], v[24:27]
	v_mfma_f32_16x16x32_bf16 v[12:15], v[148:151], v[226:229], v[12:15]
	v_mfma_f32_16x16x32_bf16 v[8:11], v[156:159], v[226:229], v[8:11]
	s_setprio 0
	s_setprio 1
	v_mfma_f32_16x16x32_bf16 v[52:55], v[160:163], v[176:179], v[52:55]
	v_mfma_f32_16x16x32_bf16 v[48:51], v[168:171], v[176:179], v[48:51]
	v_mfma_f32_16x16x32_bf16 v[36:39], v[160:163], v[184:187], v[36:39]
	v_mfma_f32_16x16x32_bf16 v[32:35], v[168:171], v[184:187], v[32:35]
	v_mfma_f32_16x16x32_bf16 v[20:23], v[160:163], v[214:217], v[20:23]
	v_mfma_f32_16x16x32_bf16 v[16:19], v[168:171], v[214:217], v[16:19]
	v_mfma_f32_16x16x32_bf16 v[4:7], v[160:163], v[222:225], v[4:7]
	v_mfma_f32_16x16x32_bf16 v[0:3], v[168:171], v[222:225], v[0:3]
	v_mfma_f32_16x16x32_bf16 v[52:55], v[164:167], v[180:183], v[52:55]
	v_mfma_f32_16x16x32_bf16 v[48:51], v[172:175], v[180:183], v[48:51]
	v_mfma_f32_16x16x32_bf16 v[36:39], v[164:167], v[188:191], v[36:39]
	v_mfma_f32_16x16x32_bf16 v[32:35], v[172:175], v[188:191], v[32:35]
	v_mfma_f32_16x16x32_bf16 v[20:23], v[164:167], v[218:221], v[20:23]
	v_mfma_f32_16x16x32_bf16 v[16:19], v[172:175], v[218:221], v[16:19]
	v_mfma_f32_16x16x32_bf16 v[4:7], v[164:167], v[226:229], v[4:7]
	v_mfma_f32_16x16x32_bf16 v[0:3], v[172:175], v[226:229], v[0:3]
	s_setprio 0
	s_barrier
	s_add_i32 s18, s18, 2
	s_add_u32 s14, s14, 0x100
	s_addc_u32 s15, s15, 0
	s_add_u32 s16, s16, 0x100
	s_addc_u32 s17, s17, 0
	s_cmp_gt_u32 s18, 13
	s_cbranch_scc0 .LBB0_1039
	s_and_b64 vcc, exec, s[58:59]
	s_cbranch_vccz .LBB0_1042
	s_barrier

; #define PG8_STAGE(bufoff, gbase, voff) do { _Pragma("unroll") for (int _i = 0; _i < 2; ++_i) \
;         __builtin_amdgcn_global_load_lds((const unsigned*)((const char*)(gbase) + (voff)[_i]), (LAS unsigned*)(lds + (bufoff) + ldsw + _i * 8192), 16, 0, 0); } while (0)
; #define PG8_LDA(dst, b, h) do { _Pragma("unroll") for (int m = 0; m < 4; ++m) _Pragma("unroll") for (int k = 0; k < 2; ++k) dst[m][k] = *(const LAS bf16x8*)(lds + PG8_SA(b, h) + aoff + m * 2048 + k * 1024); } while (0)
; #define PG8_LDB(dst, b, h) do { _Pragma("unroll") for (int n = 0; n < 2; ++n) _Pragma("unroll") for (int k = 0; k < 2; ++k) dst[n][k] = *(const LAS bf16x8*)(lds + PG8_SB(b, h) + boff + n * 2048 + k * 1024); } while (0)
; #define PG8_MMA(ai, bj, At, Bt) do { __builtin_amdgcn_s_setprio(1); _Pragma("unroll") for (int m = 0; m < 4; ++m) _Pragma("unroll") for (int n = 0; n < 2; ++n) _Pragma("unroll") for (int k = 0; k < 2; ++k) \
;         acc[ai][bj][m][n] = __builtin_amdgcn_mfma_f32_16x16x32_bf16(Bt[n][k], At[m][k], acc[ai][bj][m][n], 0, 0, 0); __builtin_amdgcn_s_setprio(0); } while (0)
; #define PG8_WAIT_V(n) asm volatile("s_waitcnt vmcnt(" #n ")" ::: "memory")
; #define PG8_WAIT_L(n) asm volatile("s_waitcnt lgkmcnt(" #n ")" ::: "memory")
; #define PG8_BAR __builtin_amdgcn_s_barrier()
; template <class Epi, bool SP2, class Sched>
; __device__ __forceinline__ void gemm_phase(LAS unsigned char* lds, const Gemm g, const Sched& S, const Epi& E) {
;     ...
;             const bool last = (t == nt - 2);
;             const char* a1 = cA + (size_t)(t + 1) * kstep;
;             const char* a2 = last ? nA : cA + (size_t)(t + 2) * kstep; const char* b2 = last ? nB : cB + (size_t)(t + 2) * kstep;
;             const char* a3 = a2 + kstep; const char* b3 = b2 + kstep;
;             if constexpr (Epi::MID) { if (t == (nt >> 1)) E.mid(acc, cur, wr, fr); }
;             if constexpr (SP2) {
;             PG8_LDB(B0, 0, 0); PG8_LDB(B1, 0, 1); PG8_SCHED; PG8_LDA(At, 0, 0); PG8_STAGE(PG8_SA(1, 1), a1 + hstep, voffA);
;             PG8_WAIT_V(8); PG8_WAIT_L(0); PG8_BAR; PG8_MMA(0, 0, At, B0); PG8_MMA(0, 1, At, B1); PG8_BAR; PG8_SCHED;
;             PG8_LDA(At, 0, 1); PG8_STAGE(PG8_SB(0, 0), b2, voffB); PG8_STAGE(PG8_SB(0, 1), b2 + hstepB, voffB); PG8_STAGE(PG8_SA(0, 0), a2, voffA);
;             PG8_WAIT_V(8); PG8_WAIT_L(0); PG8_BAR; PG8_MMA(1, 0, At, B0); PG8_MMA(1, 1, At, B1); PG8_BAR; PG8_SCHED;
.LBB0_1118:
	s_add_u32 s6, s92, 0xfff00080
	s_addc_u32 s7, s93, -1
	s_add_i32 s22, 0, 0x10000
	s_cmp_eq_u32 s21, 60
	s_cselect_b32 s11, s73, s7
	s_cselect_b32 s10, s74, s6
	v_add_u32_e32 v144, s22, v147
	s_cselect_b32 s7, s5, s20
	s_cselect_b32 s6, s75, s76
	s_add_i32 s24, 0, 0x14000
	ds_read_b128 v[140:143], v144
	ds_read_b128 v[150:153], v144 offset:1024
	ds_read_b128 v[154:157], v144 offset:2048
	ds_read_b128 v[158:161], v144 offset:3072
	v_add_u32_e32 v144, s24, v147
	ds_read_b128 v[162:165], v144
	ds_read_b128 v[166:169], v144 offset:1024
	ds_read_b128 v[170:173], v144 offset:2048
	ds_read_b128 v[174:177], v144 offset:3072
	v_lshl_add_u64 v[144:145], s[92:93], 0, v[138:139]
	s_add_i32 m0, s13, 0xc000
	ds_read_b128 v[178:181], v149
	ds_read_b128 v[182:185], v149 offset:1024
	ds_read_b128 v[186:189], v149 offset:2048
	ds_read_b128 v[190:193], v149 offset:3072
	ds_read_b128 v[214:217], v149 offset:4096
	ds_read_b128 v[218:221], v149 offset:5120
	ds_read_b128 v[222:225], v149 offset:6144
	ds_read_b128 v[226:229], v149 offset:7168
	global_load_lds_dwordx4 v[144:145], off
	s_add_i32 m0, s13, 0xe000
	v_lshl_add_u64 v[144:145], s[92:93], 0, v[136:137]
	global_load_lds_dwordx4 v[144:145], off
	s_waitcnt vmcnt(8) lgkmcnt(0)
	s_barrier
	s_setprio 1
	v_mfma_f32_16x16x32_bf16 v[126:129], v[140:143], v[178:181], v[126:129]
	v_mfma_f32_16x16x32_bf16 v[122:125], v[154:157], v[178:181], v[122:125]
	v_mfma_f32_16x16x32_bf16 v[110:113], v[140:143], v[186:189], v[110:113]
	v_mfma_f32_16x16x32_bf16 v[106:109], v[154:157], v[186:189], v[106:109]
	v_mfma_f32_16x16x32_bf16 v[94:97], v[140:143], v[214:217], v[94:97]
	v_mfma_f32_16x16x32_bf16 v[90:93], v[154:157], v[214:217], v[90:93]
	v_mfma_f32_16x16x32_bf16 v[78:81], v[140:143], v[222:225], v[78:81]
	v_mfma_f32_16x16x32_bf16 v[74:77], v[154:157], v[222:225], v[74:77]
	v_mfma_f32_16x16x32_bf16 v[126:129], v[150:153], v[182:185], v[126:129]
	v_mfma_f32_16x16x32_bf16 v[122:125], v[158:161], v[182:185], v[122:125]
	v_mfma_f32_16x16x32_bf16 v[110:113], v[150:153], v[190:193], v[110:113]
	v_mfma_f32_16x16x32_bf16 v[106:109], v[158:161], v[190:193], v[106:109]
	v_mfma_f32_16x16x32_bf16 v[94:97], v[150:153], v[218:221], v[94:97]
	v_mfma_f32_16x16x32_bf16 v[90:93], v[158:161], v[218:221], v[90:93]
	v_mfma_f32_16x16x32_bf16 v[78:81], v[150:153], v[226:229], v[78:81]
	v_mfma_f32_16x16x32_bf16 v[74:77], v[158:161], v[226:229], v[74:77]
	s_setprio 0
	s_setprio 1
	v_mfma_f32_16x16x32_bf16 v[118:121], v[162:165], v[178:181], v[118:121]
	v_mfma_f32_16x16x32_bf16 v[114:117], v[170:173], v[178:181], v[114:117]
	v_mfma_f32_16x16x32_bf16 v[102:105], v[162:165], v[186:189], v[102:105]
	v_mfma_f32_16x16x32_bf16 v[98:101], v[170:173], v[186:189], v[98:101]
	v_mfma_f32_16x16x32_bf16 v[86:89], v[162:165], v[214:217], v[86:89]
	v_mfma_f32_16x16x32_bf16 v[82:85], v[170:173], v[214:217], v[82:85]
	v_mfma_f32_16x16x32_bf16 v[70:73], v[162:165], v[222:225], v[70:73]
	v_mfma_f32_16x16x32_bf16 v[66:69], v[170:173], v[222:225], v[66:69]
	v_mfma_f32_16x16x32_bf16 v[118:121], v[166:169], v[182:185], v[118:121]
	v_mfma_f32_16x16x32_bf16 v[114:117], v[174:177], v[182:185], v[114:117]
	v_mfma_f32_16x16x32_bf16 v[102:105], v[166:169], v[190:193], v[102:105]
	v_mfma_f32_16x16x32_bf16 v[98:101], v[174:177], v[190:193], v[98:101]
	v_mfma_f32_16x16x32_bf16 v[86:89], v[166:169], v[218:221], v[86:89]
	v_mfma_f32_16x16x32_bf16 v[82:85], v[174:177], v[218:221], v[82:85]
	v_mfma_f32_16x16x32_bf16 v[70:73], v[166:169], v[226:229], v[70:73]
	v_mfma_f32_16x16x32_bf16 v[66:69], v[174:177], v[226:229], v[66:69]
	s_setprio 0
	s_barrier
	s_add_i32 s22, s22, s12
	v_lshl_add_u64 v[144:145], s[6:7], 0, v[64:65]
	s_mov_b32 m0, s22
	ds_read_b128 v[178:181], v149 offset:16384
	ds_read_b128 v[182:185], v149 offset:17408
	ds_read_b128 v[186:189], v149 offset:18432
	ds_read_b128 v[190:193], v149 offset:19456
	ds_read_b128 v[214:217], v149 offset:20480
	ds_read_b128 v[218:221], v149 offset:21504
	ds_read_b128 v[222:225], v149 offset:22528
	ds_read_b128 v[226:229], v149 offset:23552
	global_load_lds_dwordx4 v[144:145], off
	s_add_i32 m0, s22, 0x2000
	s_add_u32 s22, s6, 0x100000
	v_lshl_add_u64 v[230:231], s[6:7], 0, v[134:135]
	s_addc_u32 s23, s7, 0
	s_add_i32 s24, s24, s12
	global_load_lds_dwordx4 v[230:231], off
	v_lshl_add_u64 v[232:233], s[22:23], 0, v[64:65]
	s_mov_b32 m0, s24
	v_lshl_add_u64 v[234:235], s[10:11], 0, v[132:133]
	global_load_lds_dwordx4 v[232:233], off
	s_add_i32 m0, s24, 0x2000
	v_lshl_add_u64 v[232:233], s[22:23], 0, v[134:135]
	global_load_lds_dwordx4 v[232:233], off
	s_mov_b32 m0, s13
	v_lshl_add_u64 v[232:233], s[10:11], 0, v[130:131]
	global_load_lds_dwordx4 v[232:233], off
	s_mov_b32 m0, s14
	s_nop 0
	global_load_lds_dwordx4 v[234:235], off
	s_waitcnt vmcnt(8) lgkmcnt(0)
	s_barrier
; #define PG8_STAGE(bufoff, gbase, voff) do { _Pragma("unroll") for (int _i = 0; _i < 2; ++_i) \
;         __builtin_amdgcn_global_load_lds((const unsigned*)((const char*)(gbase) + (voff)[_i]), (LAS unsigned*)(lds + (bufoff) + ldsw + _i * 8192), 16, 0, 0); } while (0)
; #define PG8_LDA(dst, b, h) do { _Pragma("unroll") for (int m = 0; m < 4; ++m) _Pragma("unroll") for (int k = 0; k < 2; ++k) dst[m][k] = *(const LAS bf16x8*)(lds + PG8_SA(b, h) + aoff + m * 2048 + k * 1024); } while (0)
; #define PG8_LDB(dst, b, h) do { _Pragma("unroll") for (int n = 0; n < 2; ++n) _Pragma("unroll") for (int k = 0; k < 2; ++k) dst[n][k] = *(const LAS bf16x8*)(lds + PG8_SB(b, h) + boff + n * 2048 + k * 1024); } while (0)
; #define PG8_MMA(ai, bj, At, Bt) do { __builtin_amdgcn_s_setprio(1); _Pragma("unroll") for (int m = 0; m < 4; ++m) _Pragma("unroll") for (int n = 0; n < 2; ++n) _Pragma("unroll") for (int k = 0; k < 2; ++k) \
;         acc[ai][bj][m][n] = __builtin_amdgcn_mfma_f32_16x16x32_bf16(Bt[n][k], At[m][k], acc[ai][bj][m][n], 0, 0, 0); __builtin_amdgcn_s_setprio(0); } while (0)
; #define PG8_WAIT_V(n) asm volatile("s_waitcnt vmcnt(" #n ")" ::: "memory")
; #define PG8_WAIT_L(n) asm volatile("s_waitcnt lgkmcnt(" #n ")" ::: "memory")
; #define PG8_BAR __builtin_amdgcn_s_barrier()
; #define PG8_SCHED __builtin_amdgcn_sched_barrier(0)
; template <class Epi, bool SP2, class Sched>
; __device__ __forceinline__ void gemm_phase(LAS unsigned char* lds, const Gemm g, const Sched& S, const Epi& E) {
;     ...
;             PG8_WAIT_V(8); PG8_WAIT_L(0); PG8_BAR; PG8_MMA(1, 0, At, B0); PG8_MMA(1, 1, At, B1); PG8_BAR; PG8_SCHED;
;             PG8_LDB(B0, 1, 0); PG8_LDB(B1, 1, 1); PG8_SCHED; PG8_LDA(At, 1, 0); PG8_STAGE(PG8_SA(0, 1), a2 + hstep, voffA);
;             PG8_WAIT_V(8); PG8_WAIT_L(0); PG8_BAR; PG8_MMA(0, 0, At, B0); PG8_MMA(0, 1, At, B1); PG8_BAR; PG8_SCHED;
	s_setprio 1
	v_mfma_f32_16x16x32_bf16 v[60:63], v[140:143], v[178:181], v[60:63]
	v_mfma_f32_16x16x32_bf16 v[56:59], v[154:157], v[178:181], v[56:59]
	v_mfma_f32_16x16x32_bf16 v[44:47], v[140:143], v[186:189], v[44:47]
	v_mfma_f32_16x16x32_bf16 v[40:43], v[154:157], v[186:189], v[40:43]
	v_mfma_f32_16x16x32_bf16 v[28:31], v[140:143], v[214:217], v[28:31]
	v_mfma_f32_16x16x32_bf16 v[24:27], v[154:157], v[214:217], v[24:27]
	v_mfma_f32_16x16x32_bf16 v[12:15], v[140:143], v[222:225], v[12:15]
	v_mfma_f32_16x16x32_bf16 v[8:11], v[154:157], v[222:225], v[8:11]
	v_mfma_f32_16x16x32_bf16 v[60:63], v[150:153], v[182:185], v[60:63]
	v_mfma_f32_16x16x32_bf16 v[56:59], v[158:161], v[182:185], v[56:59]
	v_mfma_f32_16x16x32_bf16 v[44:47], v[150:153], v[190:193], v[44:47]
	v_mfma_f32_16x16x32_bf16 v[40:43], v[158:161], v[190:193], v[40:43]
	v_mfma_f32_16x16x32_bf16 v[28:31], v[150:153], v[218:221], v[28:31]
	v_mfma_f32_16x16x32_bf16 v[24:27], v[158:161], v[218:221], v[24:27]
	v_mfma_f32_16x16x32_bf16 v[12:15], v[150:153], v[226:229], v[12:15]
	v_mfma_f32_16x16x32_bf16 v[8:11], v[158:161], v[226:229], v[8:11]
	s_setprio 0
	s_setprio 1
	v_mfma_f32_16x16x32_bf16 v[52:55], v[162:165], v[178:181], v[52:55]
	v_mfma_f32_16x16x32_bf16 v[48:51], v[170:173], v[178:181], v[48:51]
	v_mfma_f32_16x16x32_bf16 v[36:39], v[162:165], v[186:189], v[36:39]
	v_mfma_f32_16x16x32_bf16 v[32:35], v[170:173], v[186:189], v[32:35]
	v_mfma_f32_16x16x32_bf16 v[20:23], v[162:165], v[214:217], v[20:23]
	v_mfma_f32_16x16x32_bf16 v[16:19], v[170:173], v[214:217], v[16:19]
	v_mfma_f32_16x16x32_bf16 v[4:7], v[162:165], v[222:225], v[4:7]
	v_mfma_f32_16x16x32_bf16 v[0:3], v[170:173], v[222:225], v[0:3]
	v_mfma_f32_16x16x32_bf16 v[52:55], v[166:169], v[182:185], v[52:55]
	v_mfma_f32_16x16x32_bf16 v[48:51], v[174:177], v[182:185], v[48:51]
	v_mfma_f32_16x16x32_bf16 v[36:39], v[166:169], v[190:193], v[36:39]
	v_mfma_f32_16x16x32_bf16 v[32:35], v[174:177], v[190:193], v[32:35]
	v_mfma_f32_16x16x32_bf16 v[20:23], v[166:169], v[218:221], v[20:23]
	v_mfma_f32_16x16x32_bf16 v[16:19], v[174:177], v[218:221], v[16:19]
	v_mfma_f32_16x16x32_bf16 v[4:7], v[166:169], v[226:229], v[4:7]
	v_mfma_f32_16x16x32_bf16 v[0:3], v[174:177], v[226:229], v[0:3]
	s_setprio 0
	s_barrier
	s_add_i32 s22, 0, 0x18000
	s_add_i32 s23, 0, 0x1c000
	v_add_u32_e32 v158, s22, v147
	v_add_u32_e32 v174, s23, v147
	ds_read_b128 v[140:143], v158
	ds_read_b128 v[150:153], v158 offset:1024
	ds_read_b128 v[154:157], v158 offset:2048
	ds_read_b128 v[158:161], v158 offset:3072
	ds_read_b128 v[162:165], v174
	ds_read_b128 v[166:169], v174 offset:1024
	ds_read_b128 v[170:173], v174 offset:2048
	ds_read_b128 v[174:177], v174 offset:3072
	s_add_u32 s10, s10, 0x100000
	s_addc_u32 s11, s11, 0
	s_mov_b32 m0, s15
	v_lshl_add_u64 v[236:237], s[10:11], 0, v[130:131]
	ds_read_b128 v[178:181], v149 offset:32768
	ds_read_b128 v[182:185], v149 offset:33792
	ds_read_b128 v[186:189], v149 offset:34816
	ds_read_b128 v[190:193], v149 offset:35840
	ds_read_b128 v[214:217], v149 offset:36864
	ds_read_b128 v[218:221], v149 offset:37888
	ds_read_b128 v[222:225], v149 offset:38912
	ds_read_b128 v[226:229], v149 offset:39936
	global_load_lds_dwordx4 v[236:237], off
	s_mov_b32 m0, s17
	v_lshl_add_u64 v[236:237], s[10:11], 0, v[132:133]
	global_load_lds_dwordx4 v[236:237], off
	s_waitcnt vmcnt(8) lgkmcnt(0)
	s_barrier
	s_setprio 1
	v_mfma_f32_16x16x32_bf16 v[126:129], v[140:143], v[178:181], v[126:129]
	v_mfma_f32_16x16x32_bf16 v[122:125], v[154:157], v[178:181], v[122:125]
	v_mfma_f32_16x16x32_bf16 v[110:113], v[140:143], v[186:189], v[110:113]
	v_mfma_f32_16x16x32_bf16 v[106:109], v[154:157], v[186:189], v[106:109]
	v_mfma_f32_16x16x32_bf16 v[94:97], v[140:143], v[214:217], v[94:97]
	v_mfma_f32_16x16x32_bf16 v[90:93], v[154:157], v[214:217], v[90:93]
	v_mfma_f32_16x16x32_bf16 v[78:81], v[140:143], v[222:225], v[78:81]
	v_mfma_f32_16x16x32_bf16 v[74:77], v[154:157], v[222:225], v[74:77]
	v_mfma_f32_16x16x32_bf16 v[126:129], v[150:153], v[182:185], v[126:129]
	v_mfma_f32_16x16x32_bf16 v[122:125], v[158:161], v[182:185], v[122:125]
	v_mfma_f32_16x16x32_bf16 v[110:113], v[150:153], v[190:193], v[110:113]
	v_mfma_f32_16x16x32_bf16 v[106:109], v[158:161], v[190:193], v[106:109]
	v_mfma_f32_16x16x32_bf16 v[94:97], v[150:153], v[218:221], v[94:97]
	v_mfma_f32_16x16x32_bf16 v[90:93], v[158:161], v[218:221], v[90:93]
	v_mfma_f32_16x16x32_bf16 v[78:81], v[150:153], v[226:229], v[78:81]
	v_mfma_f32_16x16x32_bf16 v[74:77], v[158:161], v[226:229], v[74:77]
	s_setprio 0
	s_setprio 1
	v_mfma_f32_16x16x32_bf16 v[118:121], v[162:165], v[178:181], v[118:121]
	v_mfma_f32_16x16x32_bf16 v[114:117], v[170:173], v[178:181], v[114:117]
	v_mfma_f32_16x16x32_bf16 v[102:105], v[162:165], v[186:189], v[102:105]
	v_mfma_f32_16x16x32_bf16 v[98:101], v[170:173], v[186:189], v[98:101]
	v_mfma_f32_16x16x32_bf16 v[86:89], v[162:165], v[214:217], v[86:89]
	v_mfma_f32_16x16x32_bf16 v[82:85], v[170:173], v[214:217], v[82:85]
	v_mfma_f32_16x16x32_bf16 v[70:73], v[162:165], v[222:225], v[70:73]
	v_mfma_f32_16x16x32_bf16 v[66:69], v[170:173], v[222:225], v[66:69]
	v_mfma_f32_16x16x32_bf16 v[118:121], v[166:169], v[182:185], v[118:121]
	v_mfma_f32_16x16x32_bf16 v[114:117], v[174:177], v[182:185], v[114:117]
	v_mfma_f32_16x16x32_bf16 v[102:105], v[166:169], v[190:193], v[102:105]
	v_mfma_f32_16x16x32_bf16 v[98:101], v[174:177], v[190:193], v[98:101]
	v_mfma_f32_16x16x32_bf16 v[86:89], v[166:169], v[218:221], v[86:89]
	v_mfma_f32_16x16x32_bf16 v[82:85], v[174:177], v[218:221], v[82:85]
	v_mfma_f32_16x16x32_bf16 v[70:73], v[166:169], v[226:229], v[70:73]
	v_mfma_f32_16x16x32_bf16 v[66:69], v[174:177], v[226:229], v[66:69]
	s_setprio 0
	s_barrier
; #define PG8_STAGE(bufoff, gbase, voff) do { _Pragma("unroll") for (int _i = 0; _i < 2; ++_i) \
;         __builtin_amdgcn_global_load_lds((const unsigned*)((const char*)(gbase) + (voff)[_i]), (LAS unsigned*)(lds + (bufoff) + ldsw + _i * 8192), 16, 0, 0); } while (0)
; #define PG8_LDA(dst, b, h) do { _Pragma("unroll") for (int m = 0; m < 4; ++m) _Pragma("unroll") for (int k = 0; k < 2; ++k) dst[m][k] = *(const LAS bf16x8*)(lds + PG8_SA(b, h) + aoff + m * 2048 + k * 1024); } while (0)
; #define PG8_MMA(ai, bj, At, Bt) do { __builtin_amdgcn_s_setprio(1); _Pragma("unroll") for (int m = 0; m < 4; ++m) _Pragma("unroll") for (int n = 0; n < 2; ++n) _Pragma("unroll") for (int k = 0; k < 2; ++k) \
;         acc[ai][bj][m][n] = __builtin_amdgcn_mfma_f32_16x16x32_bf16(Bt[n][k], At[m][k], acc[ai][bj][m][n], 0, 0, 0); __builtin_amdgcn_s_setprio(0); } while (0)
; #define PG8_WAIT_V(n) asm volatile("s_waitcnt vmcnt(" #n ")" ::: "memory")
; #define PG8_WAIT_L(n) asm volatile("s_waitcnt lgkmcnt(" #n ")" ::: "memory")
; #define PG8_BAR __builtin_amdgcn_s_barrier()
; #define PG8_SCHED __builtin_amdgcn_sched_barrier(0)
; template <class Epi, bool SP2, class Sched>
; __device__ __forceinline__ void gemm_phase(LAS unsigned char* lds, const Gemm g, const Sched& S, const Epi& E) {
;     ...
;         for (int t = 0; t < nt; t += 2) {
;             const bool last = (t == nt - 2);
;     ...
;             PG8_LDA(At, 1, 1); PG8_STAGE(PG8_SB(1, 0), b3, voffB); PG8_STAGE(PG8_SB(1, 1), b3 + hstepB, voffB); PG8_STAGE(PG8_SA(1, 0), a3, voffA);
;             PG8_WAIT_V(8); PG8_WAIT_L(0); PG8_BAR; PG8_MMA(1, 0, At, B0); PG8_MMA(1, 1, At, B1); PG8_BAR; PG8_SCHED;
	s_add_i32 s10, s22, s12
	v_lshl_add_u64 v[144:145], v[144:145], 0, s[66:67]
	s_mov_b32 m0, s10
	ds_read_b128 v[178:181], v149 offset:49152
	ds_read_b128 v[182:185], v149 offset:50176
	ds_read_b128 v[186:189], v149 offset:51200
	ds_read_b128 v[190:193], v149 offset:52224
	ds_read_b128 v[214:217], v149 offset:53248
	ds_read_b128 v[218:221], v149 offset:54272
	ds_read_b128 v[222:225], v149 offset:55296
	ds_read_b128 v[226:229], v149 offset:56320
	global_load_lds_dwordx4 v[144:145], off
	s_add_i32 m0, s10, 0x2000
	s_add_u32 s6, s6, 0x100080
	v_lshl_add_u64 v[144:145], v[230:231], 0, s[66:67]
	s_addc_u32 s7, s7, 0
	s_add_i32 s10, s23, s12
	global_load_lds_dwordx4 v[144:145], off
	s_mov_b32 m0, s10
	v_lshl_add_u64 v[144:145], s[6:7], 0, v[64:65]
	global_load_lds_dwordx4 v[144:145], off
	s_add_i32 m0, s10, 0x2000
	v_lshl_add_u64 v[144:145], s[6:7], 0, v[134:135]
	global_load_lds_dwordx4 v[144:145], off
	s_mov_b32 m0, s18
	v_lshl_add_u64 v[144:145], v[232:233], 0, s[66:67]
	global_load_lds_dwordx4 v[144:145], off
	s_mov_b32 m0, s19
	v_lshl_add_u64 v[144:145], v[234:235], 0, s[66:67]
	global_load_lds_dwordx4 v[144:145], off
	s_waitcnt vmcnt(8) lgkmcnt(0)
	s_barrier
	s_setprio 1
	v_mfma_f32_16x16x32_bf16 v[60:63], v[140:143], v[178:181], v[60:63]
	v_mfma_f32_16x16x32_bf16 v[56:59], v[154:157], v[178:181], v[56:59]
	v_mfma_f32_16x16x32_bf16 v[44:47], v[140:143], v[186:189], v[44:47]
	v_mfma_f32_16x16x32_bf16 v[40:43], v[154:157], v[186:189], v[40:43]
	v_mfma_f32_16x16x32_bf16 v[28:31], v[140:143], v[214:217], v[28:31]
	v_mfma_f32_16x16x32_bf16 v[24:27], v[154:157], v[214:217], v[24:27]
	v_mfma_f32_16x16x32_bf16 v[12:15], v[140:143], v[222:225], v[12:15]
	v_mfma_f32_16x16x32_bf16 v[8:11], v[154:157], v[222:225], v[8:11]
	v_mfma_f32_16x16x32_bf16 v[60:63], v[150:153], v[182:185], v[60:63]
	v_mfma_f32_16x16x32_bf16 v[56:59], v[158:161], v[182:185], v[56:59]
	v_mfma_f32_16x16x32_bf16 v[44:47], v[150:153], v[190:193], v[44:47]
	v_mfma_f32_16x16x32_bf16 v[40:43], v[158:161], v[190:193], v[40:43]
	v_mfma_f32_16x16x32_bf16 v[28:31], v[150:153], v[218:221], v[28:31]
	v_mfma_f32_16x16x32_bf16 v[24:27], v[158:161], v[218:221], v[24:27]
	v_mfma_f32_16x16x32_bf16 v[12:15], v[150:153], v[226:229], v[12:15]
	v_mfma_f32_16x16x32_bf16 v[8:11], v[158:161], v[226:229], v[8:11]
	s_setprio 0
	s_setprio 1
	v_mfma_f32_16x16x32_bf16 v[52:55], v[162:165], v[178:181], v[52:55]
	v_mfma_f32_16x16x32_bf16 v[48:51], v[170:173], v[178:181], v[48:51]
	v_mfma_f32_16x16x32_bf16 v[36:39], v[162:165], v[186:189], v[36:39]
	v_mfma_f32_16x16x32_bf16 v[32:35], v[170:173], v[186:189], v[32:35]
	v_mfma_f32_16x16x32_bf16 v[20:23], v[162:165], v[214:217], v[20:23]
	v_mfma_f32_16x16x32_bf16 v[16:19], v[170:173], v[214:217], v[16:19]
	v_mfma_f32_16x16x32_bf16 v[4:7], v[162:165], v[222:225], v[4:7]
	v_mfma_f32_16x16x32_bf16 v[0:3], v[170:173], v[222:225], v[0:3]
	v_mfma_f32_16x16x32_bf16 v[52:55], v[166:169], v[182:185], v[52:55]
	v_mfma_f32_16x16x32_bf16 v[48:51], v[174:177], v[182:185], v[48:51]
	v_mfma_f32_16x16x32_bf16 v[36:39], v[166:169], v[190:193], v[36:39]
	v_mfma_f32_16x16x32_bf16 v[32:35], v[174:177], v[190:193], v[32:35]
	v_mfma_f32_16x16x32_bf16 v[20:23], v[166:169], v[218:221], v[20:23]
	v_mfma_f32_16x16x32_bf16 v[16:19], v[174:177], v[218:221], v[16:19]
	v_mfma_f32_16x16x32_bf16 v[4:7], v[166:169], v[226:229], v[4:7]
	v_mfma_f32_16x16x32_bf16 v[0:3], v[174:177], v[226:229], v[0:3]
	s_setprio 0
	s_barrier
	s_add_i32 s21, s21, 2
	s_add_u32 s76, s76, 0x100
	s_addc_u32 s20, s20, 0
	s_add_u32 s92, s92, 0x100
	s_addc_u32 s93, s93, 0
	s_cmp_gt_u32 s21, 61
	s_cbranch_scc0 .LBB0_1118
	s_and_b64 vcc, exec, s[60:61]
	s_cbranch_vccz .LBB0_1121
	s_barrier

; #define PG8_STAGE(bufoff, gbase, voff) do { _Pragma("unroll") for (int _i = 0; _i < 2; ++_i) \
;         __builtin_amdgcn_global_load_lds((const unsigned*)((const char*)(gbase) + (voff)[_i]), (LAS unsigned*)(lds + (bufoff) + ldsw + _i * 8192), 16, 0, 0); } while (0)
; #define PG8_LDA(dst, b, h) do { _Pragma("unroll") for (int m = 0; m < 4; ++m) _Pragma("unroll") for (int k = 0; k < 2; ++k) dst[m][k] = *(const LAS bf16x8*)(lds + PG8_SA(b, h) + aoff + m * 2048 + k * 1024); } while (0)
; #define PG8_LDB(dst, b, h) do { _Pragma("unroll") for (int n = 0; n < 2; ++n) _Pragma("unroll") for (int k = 0; k < 2; ++k) dst[n][k] = *(const LAS bf16x8*)(lds + PG8_SB(b, h) + boff + n * 2048 + k * 1024); } while (0)
; #define PG8_MMA(ai, bj, At, Bt) do { __builtin_amdgcn_s_setprio(1); _Pragma("unroll") for (int m = 0; m < 4; ++m) _Pragma("unroll") for (int n = 0; n < 2; ++n) _Pragma("unroll") for (int k = 0; k < 2; ++k) \
;         acc[ai][bj][m][n] = __builtin_amdgcn_mfma_f32_16x16x32_bf16(Bt[n][k], At[m][k], acc[ai][bj][m][n], 0, 0, 0); __builtin_amdgcn_s_setprio(0); } while (0)
; #define PG8_WAIT_V(n) asm volatile("s_waitcnt vmcnt(" #n ")" ::: "memory")
; #define PG8_WAIT_L(n) asm volatile("s_waitcnt lgkmcnt(" #n ")" ::: "memory")
; #define PG8_BAR __builtin_amdgcn_s_barrier()
; template <class Epi, bool SP2, class Sched>
; __device__ __forceinline__ void gemm_phase(LAS unsigned char* lds, const Gemm g, const Sched& S, const Epi& E) {
;     ...
;             const bool last = (t == nt - 2);
;             const char* a1 = cA + (size_t)(t + 1) * kstep;
;             const char* a2 = last ? nA : cA + (size_t)(t + 2) * kstep; const char* b2 = last ? nB : cB + (size_t)(t + 2) * kstep;
;             const char* a3 = a2 + kstep; const char* b3 = b2 + kstep;
;             if constexpr (Epi::MID) { if (t == (nt >> 1)) E.mid(acc, cur, wr, fr); }
;             if constexpr (SP2) {
;             PG8_LDB(B0, 0, 0); PG8_LDB(B1, 0, 1); PG8_SCHED; PG8_LDA(At, 0, 0); PG8_STAGE(PG8_SA(1, 1), a1 + hstep, voffA);
;             PG8_WAIT_V(8); PG8_WAIT_L(0); PG8_BAR; PG8_MMA(0, 0, At, B0); PG8_MMA(0, 1, At, B1); PG8_BAR; PG8_SCHED;
;             PG8_LDA(At, 0, 1); PG8_STAGE(PG8_SB(0, 0), b2, voffB); PG8_STAGE(PG8_SB(0, 1), b2 + hstepB, voffB); PG8_STAGE(PG8_SA(0, 0), a2, voffA);
;             PG8_WAIT_V(8); PG8_WAIT_L(0); PG8_BAR; PG8_MMA(1, 0, At, B0); PG8_MMA(1, 1, At, B1); PG8_BAR; PG8_SCHED;
.LBB0_1150:
	s_add_u32 s6, s86, 0xfff00080
	s_addc_u32 s7, s87, -1
	s_add_i32 s22, 0, 0x10000
	s_cmp_eq_u32 s21, 12
	s_cselect_b32 s11, s3, s7
	s_cselect_b32 s10, s57, s6
	s_cselect_b32 s7, s53, s20
	s_cselect_b32 s6, s77, s79
	s_add_i32 s24, 0, 0x14000
	v_add_u32_e32 v152, s22, v137
	v_add_u32_e32 v168, s24, v137
	ds_read_b128 v[140:143], v152
	ds_read_b128 v[144:147], v152 offset:1024
	ds_read_b128 v[148:151], v152 offset:2048
	ds_read_b128 v[152:155], v152 offset:3072
	ds_read_b128 v[156:159], v168
	ds_read_b128 v[160:163], v168 offset:1024
	ds_read_b128 v[164:167], v168 offset:2048
	ds_read_b128 v[168:171], v168 offset:3072
	v_lshl_add_u64 v[192:193], s[86:87], 0, v[134:135]
	s_add_i32 m0, s5, 0xc000
	ds_read_b128 v[172:175], v139
	ds_read_b128 v[176:179], v139 offset:1024
	ds_read_b128 v[180:183], v139 offset:2048
	ds_read_b128 v[184:187], v139 offset:3072
	ds_read_b128 v[188:191], v139 offset:4096
	ds_read_b128 v[214:217], v139 offset:5120
	ds_read_b128 v[218:221], v139 offset:6144
	ds_read_b128 v[222:225], v139 offset:7168
	global_load_lds_dwordx4 v[192:193], off
	s_add_i32 m0, s5, 0xe000
	v_lshl_add_u64 v[192:193], s[86:87], 0, v[132:133]
	global_load_lds_dwordx4 v[192:193], off
	s_waitcnt vmcnt(8) lgkmcnt(0)
	s_barrier
	s_setprio 1
	v_mfma_f32_16x16x32_bf16 v[126:129], v[140:143], v[172:175], v[126:129]
	v_mfma_f32_16x16x32_bf16 v[122:125], v[148:151], v[172:175], v[122:125]
	v_mfma_f32_16x16x32_bf16 v[118:121], v[140:143], v[180:183], v[118:121]
	v_mfma_f32_16x16x32_bf16 v[114:117], v[148:151], v[180:183], v[114:117]
	v_mfma_f32_16x16x32_bf16 v[106:109], v[140:143], v[188:191], v[106:109]
	v_mfma_f32_16x16x32_bf16 v[98:101], v[148:151], v[188:191], v[98:101]
	v_mfma_f32_16x16x32_bf16 v[90:93], v[140:143], v[218:221], v[90:93]
	v_mfma_f32_16x16x32_bf16 v[82:85], v[148:151], v[218:221], v[82:85]
	v_mfma_f32_16x16x32_bf16 v[126:129], v[144:147], v[176:179], v[126:129]
	v_mfma_f32_16x16x32_bf16 v[122:125], v[152:155], v[176:179], v[122:125]
	v_mfma_f32_16x16x32_bf16 v[118:121], v[144:147], v[184:187], v[118:121]
	v_mfma_f32_16x16x32_bf16 v[114:117], v[152:155], v[184:187], v[114:117]
	v_mfma_f32_16x16x32_bf16 v[106:109], v[144:147], v[214:217], v[106:109]
	v_mfma_f32_16x16x32_bf16 v[98:101], v[152:155], v[214:217], v[98:101]
	v_mfma_f32_16x16x32_bf16 v[90:93], v[144:147], v[222:225], v[90:93]
	v_mfma_f32_16x16x32_bf16 v[82:85], v[152:155], v[222:225], v[82:85]
	s_setprio 0
	s_setprio 1
	v_mfma_f32_16x16x32_bf16 v[110:113], v[156:159], v[172:175], v[110:113]
	v_mfma_f32_16x16x32_bf16 v[102:105], v[164:167], v[172:175], v[102:105]
	v_mfma_f32_16x16x32_bf16 v[94:97], v[156:159], v[180:183], v[94:97]
	v_mfma_f32_16x16x32_bf16 v[86:89], v[164:167], v[180:183], v[86:89]
	v_mfma_f32_16x16x32_bf16 v[78:81], v[156:159], v[188:191], v[78:81]
	v_mfma_f32_16x16x32_bf16 v[74:77], v[164:167], v[188:191], v[74:77]
	v_mfma_f32_16x16x32_bf16 v[70:73], v[156:159], v[218:221], v[70:73]
	v_mfma_f32_16x16x32_bf16 v[66:69], v[164:167], v[218:221], v[66:69]
	v_mfma_f32_16x16x32_bf16 v[110:113], v[160:163], v[176:179], v[110:113]
	v_mfma_f32_16x16x32_bf16 v[102:105], v[168:171], v[176:179], v[102:105]
	v_mfma_f32_16x16x32_bf16 v[94:97], v[160:163], v[184:187], v[94:97]
	v_mfma_f32_16x16x32_bf16 v[86:89], v[168:171], v[184:187], v[86:89]
	v_mfma_f32_16x16x32_bf16 v[78:81], v[160:163], v[214:217], v[78:81]
	v_mfma_f32_16x16x32_bf16 v[74:77], v[168:171], v[214:217], v[74:77]
	v_mfma_f32_16x16x32_bf16 v[70:73], v[160:163], v[222:225], v[70:73]
	v_mfma_f32_16x16x32_bf16 v[66:69], v[168:171], v[222:225], v[66:69]
	s_setprio 0
	s_barrier
	s_add_i32 s22, s22, s18
	v_lshl_add_u64 v[192:193], s[6:7], 0, v[64:65]
	s_mov_b32 m0, s22
	ds_read_b128 v[172:175], v139 offset:16384
	ds_read_b128 v[176:179], v139 offset:17408
	ds_read_b128 v[180:183], v139 offset:18432
	ds_read_b128 v[184:187], v139 offset:19456
	ds_read_b128 v[188:191], v139 offset:20480
	ds_read_b128 v[214:217], v139 offset:21504
	ds_read_b128 v[218:221], v139 offset:22528
	ds_read_b128 v[222:225], v139 offset:23552
	global_load_lds_dwordx4 v[192:193], off
	s_add_i32 m0, s22, 0x2000
	s_add_u32 s22, s6, 0x100000
	v_lshl_add_u64 v[226:227], s[6:7], 0, v[130:131]
	s_addc_u32 s23, s7, 0
	s_add_i32 s24, s24, s18
	global_load_lds_dwordx4 v[226:227], off
	v_lshl_add_u64 v[228:229], s[22:23], 0, v[64:65]
	s_mov_b32 m0, s24
	v_lshl_add_u64 v[230:231], s[10:11], 0, v[130:131]
	global_load_lds_dwordx4 v[228:229], off
	s_add_i32 m0, s24, 0x2000
	v_lshl_add_u64 v[228:229], s[22:23], 0, v[130:131]
	global_load_lds_dwordx4 v[228:229], off
	s_mov_b32 m0, s5
	v_lshl_add_u64 v[228:229], s[10:11], 0, v[64:65]
	global_load_lds_dwordx4 v[228:229], off
	s_mov_b32 m0, s33
	s_nop 0
	global_load_lds_dwordx4 v[230:231], off
	s_waitcnt vmcnt(8) lgkmcnt(0)
	s_barrier
; #define PG8_STAGE(bufoff, gbase, voff) do { _Pragma("unroll") for (int _i = 0; _i < 2; ++_i) \
;         __builtin_amdgcn_global_load_lds((const unsigned*)((const char*)(gbase) + (voff)[_i]), (LAS unsigned*)(lds + (bufoff) + ldsw + _i * 8192), 16, 0, 0); } while (0)
; #define PG8_LDA(dst, b, h) do { _Pragma("unroll") for (int m = 0; m < 4; ++m) _Pragma("unroll") for (int k = 0; k < 2; ++k) dst[m][k] = *(const LAS bf16x8*)(lds + PG8_SA(b, h) + aoff + m * 2048 + k * 1024); } while (0)
; #define PG8_LDB(dst, b, h) do { _Pragma("unroll") for (int n = 0; n < 2; ++n) _Pragma("unroll") for (int k = 0; k < 2; ++k) dst[n][k] = *(const LAS bf16x8*)(lds + PG8_SB(b, h) + boff + n * 2048 + k * 1024); } while (0)
; #define PG8_MMA(ai, bj, At, Bt) do { __builtin_amdgcn_s_setprio(1); _Pragma("unroll") for (int m = 0; m < 4; ++m) _Pragma("unroll") for (int n = 0; n < 2; ++n) _Pragma("unroll") for (int k = 0; k < 2; ++k) \
;         acc[ai][bj][m][n] = __builtin_amdgcn_mfma_f32_16x16x32_bf16(Bt[n][k], At[m][k], acc[ai][bj][m][n], 0, 0, 0); __builtin_amdgcn_s_setprio(0); } while (0)
; #define PG8_WAIT_V(n) asm volatile("s_waitcnt vmcnt(" #n ")" ::: "memory")
; #define PG8_WAIT_L(n) asm volatile("s_waitcnt lgkmcnt(" #n ")" ::: "memory")
; #define PG8_BAR __builtin_amdgcn_s_barrier()
; #define PG8_SCHED __builtin_amdgcn_sched_barrier(0)
; template <class Epi, bool SP2, class Sched>
; __device__ __forceinline__ void gemm_phase(LAS unsigned char* lds, const Gemm g, const Sched& S, const Epi& E) {
;     ...
;             PG8_WAIT_V(8); PG8_WAIT_L(0); PG8_BAR; PG8_MMA(1, 0, At, B0); PG8_MMA(1, 1, At, B1); PG8_BAR; PG8_SCHED;
;             PG8_LDB(B0, 1, 0); PG8_LDB(B1, 1, 1); PG8_SCHED; PG8_LDA(At, 1, 0); PG8_STAGE(PG8_SA(0, 1), a2 + hstep, voffA);
;             PG8_WAIT_V(8); PG8_WAIT_L(0); PG8_BAR; PG8_MMA(0, 0, At, B0); PG8_MMA(0, 1, At, B1); PG8_BAR; PG8_SCHED;
	s_setprio 1
	v_mfma_f32_16x16x32_bf16 v[60:63], v[140:143], v[172:175], v[60:63]
	v_mfma_f32_16x16x32_bf16 v[56:59], v[148:151], v[172:175], v[56:59]
	v_mfma_f32_16x16x32_bf16 v[52:55], v[140:143], v[180:183], v[52:55]
	v_mfma_f32_16x16x32_bf16 v[48:51], v[148:151], v[180:183], v[48:51]
	v_mfma_f32_16x16x32_bf16 v[36:39], v[140:143], v[188:191], v[36:39]
	v_mfma_f32_16x16x32_bf16 v[32:35], v[148:151], v[188:191], v[32:35]
	v_mfma_f32_16x16x32_bf16 v[20:23], v[140:143], v[218:221], v[20:23]
	v_mfma_f32_16x16x32_bf16 v[16:19], v[148:151], v[218:221], v[16:19]
	v_mfma_f32_16x16x32_bf16 v[60:63], v[144:147], v[176:179], v[60:63]
	v_mfma_f32_16x16x32_bf16 v[56:59], v[152:155], v[176:179], v[56:59]
	v_mfma_f32_16x16x32_bf16 v[52:55], v[144:147], v[184:187], v[52:55]
	v_mfma_f32_16x16x32_bf16 v[48:51], v[152:155], v[184:187], v[48:51]
	v_mfma_f32_16x16x32_bf16 v[36:39], v[144:147], v[214:217], v[36:39]
	v_mfma_f32_16x16x32_bf16 v[32:35], v[152:155], v[214:217], v[32:35]
	v_mfma_f32_16x16x32_bf16 v[20:23], v[144:147], v[222:225], v[20:23]
	v_mfma_f32_16x16x32_bf16 v[16:19], v[152:155], v[222:225], v[16:19]
	s_setprio 0
	s_setprio 1
	v_mfma_f32_16x16x32_bf16 v[44:47], v[156:159], v[172:175], v[44:47]
	v_mfma_f32_16x16x32_bf16 v[40:43], v[164:167], v[172:175], v[40:43]
	v_mfma_f32_16x16x32_bf16 v[28:31], v[156:159], v[180:183], v[28:31]
	v_mfma_f32_16x16x32_bf16 v[24:27], v[164:167], v[180:183], v[24:27]
	v_mfma_f32_16x16x32_bf16 v[12:15], v[156:159], v[188:191], v[12:15]
	v_mfma_f32_16x16x32_bf16 v[8:11], v[164:167], v[188:191], v[8:11]
	v_mfma_f32_16x16x32_bf16 v[4:7], v[156:159], v[218:221], v[4:7]
	v_mfma_f32_16x16x32_bf16 v[0:3], v[164:167], v[218:221], v[0:3]
	v_mfma_f32_16x16x32_bf16 v[44:47], v[160:163], v[176:179], v[44:47]
	v_mfma_f32_16x16x32_bf16 v[40:43], v[168:171], v[176:179], v[40:43]
	v_mfma_f32_16x16x32_bf16 v[28:31], v[160:163], v[184:187], v[28:31]
	v_mfma_f32_16x16x32_bf16 v[24:27], v[168:171], v[184:187], v[24:27]
	v_mfma_f32_16x16x32_bf16 v[12:15], v[160:163], v[214:217], v[12:15]
	v_mfma_f32_16x16x32_bf16 v[8:11], v[168:171], v[214:217], v[8:11]
	v_mfma_f32_16x16x32_bf16 v[4:7], v[160:163], v[222:225], v[4:7]
	v_mfma_f32_16x16x32_bf16 v[0:3], v[168:171], v[222:225], v[0:3]
	s_setprio 0
	s_barrier
	s_add_i32 s22, 0, 0x18000
	s_add_i32 s23, 0, 0x1c000
	v_add_u32_e32 v152, s22, v137
	v_add_u32_e32 v168, s23, v137
	ds_read_b128 v[140:143], v152
	ds_read_b128 v[144:147], v152 offset:1024
	ds_read_b128 v[148:151], v152 offset:2048
	ds_read_b128 v[152:155], v152 offset:3072
	ds_read_b128 v[156:159], v168
	ds_read_b128 v[160:163], v168 offset:1024
	ds_read_b128 v[164:167], v168 offset:2048
	ds_read_b128 v[168:171], v168 offset:3072
	s_add_u32 s10, s10, 0x100000
	s_addc_u32 s11, s11, 0
	s_mov_b32 m0, s62
	v_lshl_add_u64 v[232:233], s[10:11], 0, v[64:65]
	ds_read_b128 v[172:175], v139 offset:32768
	ds_read_b128 v[176:179], v139 offset:33792
	ds_read_b128 v[180:183], v139 offset:34816
	ds_read_b128 v[184:187], v139 offset:35840
	ds_read_b128 v[188:191], v139 offset:36864
	ds_read_b128 v[214:217], v139 offset:37888
	ds_read_b128 v[218:221], v139 offset:38912
	ds_read_b128 v[222:225], v139 offset:39936
	global_load_lds_dwordx4 v[232:233], off
	s_mov_b32 m0, s64
	v_lshl_add_u64 v[232:233], s[10:11], 0, v[130:131]
	global_load_lds_dwordx4 v[232:233], off
	s_waitcnt vmcnt(8) lgkmcnt(0)
	s_barrier
	s_setprio 1
	v_mfma_f32_16x16x32_bf16 v[126:129], v[140:143], v[172:175], v[126:129]
	v_mfma_f32_16x16x32_bf16 v[122:125], v[148:151], v[172:175], v[122:125]
	v_mfma_f32_16x16x32_bf16 v[118:121], v[140:143], v[180:183], v[118:121]
	v_mfma_f32_16x16x32_bf16 v[114:117], v[148:151], v[180:183], v[114:117]
	v_mfma_f32_16x16x32_bf16 v[106:109], v[140:143], v[188:191], v[106:109]
	v_mfma_f32_16x16x32_bf16 v[98:101], v[148:151], v[188:191], v[98:101]
	v_mfma_f32_16x16x32_bf16 v[90:93], v[140:143], v[218:221], v[90:93]
	v_mfma_f32_16x16x32_bf16 v[82:85], v[148:151], v[218:221], v[82:85]
	v_mfma_f32_16x16x32_bf16 v[126:129], v[144:147], v[176:179], v[126:129]
	v_mfma_f32_16x16x32_bf16 v[122:125], v[152:155], v[176:179], v[122:125]
	v_mfma_f32_16x16x32_bf16 v[118:121], v[144:147], v[184:187], v[118:121]
	v_mfma_f32_16x16x32_bf16 v[114:117], v[152:155], v[184:187], v[114:117]
	v_mfma_f32_16x16x32_bf16 v[106:109], v[144:147], v[214:217], v[106:109]
	v_mfma_f32_16x16x32_bf16 v[98:101], v[152:155], v[214:217], v[98:101]
	v_mfma_f32_16x16x32_bf16 v[90:93], v[144:147], v[222:225], v[90:93]
	v_mfma_f32_16x16x32_bf16 v[82:85], v[152:155], v[222:225], v[82:85]
	s_setprio 0
	s_setprio 1
	v_mfma_f32_16x16x32_bf16 v[110:113], v[156:159], v[172:175], v[110:113]
	v_mfma_f32_16x16x32_bf16 v[102:105], v[164:167], v[172:175], v[102:105]
	v_mfma_f32_16x16x32_bf16 v[94:97], v[156:159], v[180:183], v[94:97]
	v_mfma_f32_16x16x32_bf16 v[86:89], v[164:167], v[180:183], v[86:89]
	v_mfma_f32_16x16x32_bf16 v[78:81], v[156:159], v[188:191], v[78:81]
	v_mfma_f32_16x16x32_bf16 v[74:77], v[164:167], v[188:191], v[74:77]
	v_mfma_f32_16x16x32_bf16 v[70:73], v[156:159], v[218:221], v[70:73]
	v_mfma_f32_16x16x32_bf16 v[66:69], v[164:167], v[218:221], v[66:69]
	v_mfma_f32_16x16x32_bf16 v[110:113], v[160:163], v[176:179], v[110:113]
	v_mfma_f32_16x16x32_bf16 v[102:105], v[168:171], v[176:179], v[102:105]
	v_mfma_f32_16x16x32_bf16 v[94:97], v[160:163], v[184:187], v[94:97]
	v_mfma_f32_16x16x32_bf16 v[86:89], v[168:171], v[184:187], v[86:89]
	v_mfma_f32_16x16x32_bf16 v[78:81], v[160:163], v[214:217], v[78:81]
	v_mfma_f32_16x16x32_bf16 v[74:77], v[168:171], v[214:217], v[74:77]
	v_mfma_f32_16x16x32_bf16 v[70:73], v[160:163], v[222:225], v[70:73]
	v_mfma_f32_16x16x32_bf16 v[66:69], v[168:171], v[222:225], v[66:69]
	s_setprio 0
	s_barrier
; #define PG8_STAGE(bufoff, gbase, voff) do { _Pragma("unroll") for (int _i = 0; _i < 2; ++_i) \
;         __builtin_amdgcn_global_load_lds((const unsigned*)((const char*)(gbase) + (voff)[_i]), (LAS unsigned*)(lds + (bufoff) + ldsw + _i * 8192), 16, 0, 0); } while (0)
; #define PG8_LDA(dst, b, h) do { _Pragma("unroll") for (int m = 0; m < 4; ++m) _Pragma("unroll") for (int k = 0; k < 2; ++k) dst[m][k] = *(const LAS bf16x8*)(lds + PG8_SA(b, h) + aoff + m * 2048 + k * 1024); } while (0)
; #define PG8_MMA(ai, bj, At, Bt) do { __builtin_amdgcn_s_setprio(1); _Pragma("unroll") for (int m = 0; m < 4; ++m) _Pragma("unroll") for (int n = 0; n < 2; ++n) _Pragma("unroll") for (int k = 0; k < 2; ++k) \
;         acc[ai][bj][m][n] = __builtin_amdgcn_mfma_f32_16x16x32_bf16(Bt[n][k], At[m][k], acc[ai][bj][m][n], 0, 0, 0); __builtin_amdgcn_s_setprio(0); } while (0)
; #define PG8_WAIT_V(n) asm volatile("s_waitcnt vmcnt(" #n ")" ::: "memory")
; #define PG8_WAIT_L(n) asm volatile("s_waitcnt lgkmcnt(" #n ")" ::: "memory")
; #define PG8_BAR __builtin_amdgcn_s_barrier()
; #define PG8_SCHED __builtin_amdgcn_sched_barrier(0)
; template <class Epi, bool SP2, class Sched>
; __device__ __forceinline__ void gemm_phase(LAS unsigned char* lds, const Gemm g, const Sched& S, const Epi& E) {
;     ...
;         for (int t = 0; t < nt; t += 2) {
;             const bool last = (t == nt - 2);
;     ...
;             PG8_LDA(At, 1, 1); PG8_STAGE(PG8_SB(1, 0), b3, voffB); PG8_STAGE(PG8_SB(1, 1), b3 + hstepB, voffB); PG8_STAGE(PG8_SA(1, 0), a3, voffA);
;             PG8_WAIT_V(8); PG8_WAIT_L(0); PG8_BAR; PG8_MMA(1, 0, At, B0); PG8_MMA(1, 1, At, B1); PG8_BAR; PG8_SCHED;
	s_add_i32 s10, s22, s18
	v_lshl_add_u64 v[192:193], v[192:193], 0, s[66:67]
	s_mov_b32 m0, s10
	ds_read_b128 v[172:175], v139 offset:49152
	ds_read_b128 v[176:179], v139 offset:50176
	ds_read_b128 v[180:183], v139 offset:51200
	ds_read_b128 v[184:187], v139 offset:52224
	ds_read_b128 v[188:191], v139 offset:53248
	ds_read_b128 v[214:217], v139 offset:54272
	ds_read_b128 v[218:221], v139 offset:55296
	ds_read_b128 v[222:225], v139 offset:56320
	global_load_lds_dwordx4 v[192:193], off
	s_add_i32 m0, s10, 0x2000
	s_add_u32 s6, s6, 0x100080
	v_lshl_add_u64 v[192:193], v[226:227], 0, s[66:67]
	s_addc_u32 s7, s7, 0
	s_add_i32 s10, s23, s18
	global_load_lds_dwordx4 v[192:193], off
	s_mov_b32 m0, s10
	v_lshl_add_u64 v[192:193], s[6:7], 0, v[64:65]
	global_load_lds_dwordx4 v[192:193], off
	s_add_i32 m0, s10, 0x2000
	v_lshl_add_u64 v[192:193], s[6:7], 0, v[130:131]
	global_load_lds_dwordx4 v[192:193], off
	s_mov_b32 m0, s72
	v_lshl_add_u64 v[192:193], v[228:229], 0, s[66:67]
	global_load_lds_dwordx4 v[192:193], off
	s_mov_b32 m0, s73
	v_lshl_add_u64 v[192:193], v[230:231], 0, s[66:67]
	global_load_lds_dwordx4 v[192:193], off
	s_waitcnt vmcnt(8) lgkmcnt(0)
	s_barrier
	s_setprio 1
	v_mfma_f32_16x16x32_bf16 v[60:63], v[140:143], v[172:175], v[60:63]
	v_mfma_f32_16x16x32_bf16 v[56:59], v[148:151], v[172:175], v[56:59]
	v_mfma_f32_16x16x32_bf16 v[52:55], v[140:143], v[180:183], v[52:55]
	v_mfma_f32_16x16x32_bf16 v[48:51], v[148:151], v[180:183], v[48:51]
	v_mfma_f32_16x16x32_bf16 v[36:39], v[140:143], v[188:191], v[36:39]
	v_mfma_f32_16x16x32_bf16 v[32:35], v[148:151], v[188:191], v[32:35]
	v_mfma_f32_16x16x32_bf16 v[20:23], v[140:143], v[218:221], v[20:23]
	v_mfma_f32_16x16x32_bf16 v[16:19], v[148:151], v[218:221], v[16:19]
	v_mfma_f32_16x16x32_bf16 v[60:63], v[144:147], v[176:179], v[60:63]
	v_mfma_f32_16x16x32_bf16 v[56:59], v[152:155], v[176:179], v[56:59]
	v_mfma_f32_16x16x32_bf16 v[52:55], v[144:147], v[184:187], v[52:55]
	v_mfma_f32_16x16x32_bf16 v[48:51], v[152:155], v[184:187], v[48:51]
	v_mfma_f32_16x16x32_bf16 v[36:39], v[144:147], v[214:217], v[36:39]
	v_mfma_f32_16x16x32_bf16 v[32:35], v[152:155], v[214:217], v[32:35]
	v_mfma_f32_16x16x32_bf16 v[20:23], v[144:147], v[222:225], v[20:23]
	v_mfma_f32_16x16x32_bf16 v[16:19], v[152:155], v[222:225], v[16:19]
	s_setprio 0
	s_setprio 1
	v_mfma_f32_16x16x32_bf16 v[44:47], v[156:159], v[172:175], v[44:47]
	v_mfma_f32_16x16x32_bf16 v[40:43], v[164:167], v[172:175], v[40:43]
	v_mfma_f32_16x16x32_bf16 v[28:31], v[156:159], v[180:183], v[28:31]
	v_mfma_f32_16x16x32_bf16 v[24:27], v[164:167], v[180:183], v[24:27]
	v_mfma_f32_16x16x32_bf16 v[12:15], v[156:159], v[188:191], v[12:15]
	v_mfma_f32_16x16x32_bf16 v[8:11], v[164:167], v[188:191], v[8:11]
	v_mfma_f32_16x16x32_bf16 v[4:7], v[156:159], v[218:221], v[4:7]
	v_mfma_f32_16x16x32_bf16 v[0:3], v[164:167], v[218:221], v[0:3]
	v_mfma_f32_16x16x32_bf16 v[44:47], v[160:163], v[176:179], v[44:47]
	v_mfma_f32_16x16x32_bf16 v[40:43], v[168:171], v[176:179], v[40:43]
	v_mfma_f32_16x16x32_bf16 v[28:31], v[160:163], v[184:187], v[28:31]
	v_mfma_f32_16x16x32_bf16 v[24:27], v[168:171], v[184:187], v[24:27]
	v_mfma_f32_16x16x32_bf16 v[12:15], v[160:163], v[214:217], v[12:15]
	v_mfma_f32_16x16x32_bf16 v[8:11], v[168:171], v[214:217], v[8:11]
	v_mfma_f32_16x16x32_bf16 v[4:7], v[160:163], v[222:225], v[4:7]
	v_mfma_f32_16x16x32_bf16 v[0:3], v[168:171], v[222:225], v[0:3]
	s_setprio 0
	s_barrier
	s_add_i32 s21, s21, 2
	s_add_u32 s79, s79, 0x100
	s_addc_u32 s20, s20, 0
	s_add_u32 s86, s86, 0x100
	s_addc_u32 s87, s87, 0
	s_cmp_gt_u32 s21, 13
	s_cbranch_scc0 .LBB0_1150
	s_and_b64 vcc, exec, s[16:17]
	s_cbranch_vccz .LBB0_1153
	s_barrier
